# pair-tile FFN-up: MFMAs ordered so each B fragment buffer frees early (next k-step fragments prefetched behind the MFMAs)
# speedup vs baseline: 1.0040x; 1.0040x over previous
; #define G_LOAD(S, kt_) do { G_LD1(S##a0, S##b0, 0, kt_); G_LD1(S##a1, S##b1, 1, kt_); G_LD1(S##a2, S##b2, 2, kt_); G_LD1(S##a3, S##b3, 3, kt_); } while (0)
; #define G_STORE(S, buf_) do { G_ST1(S##a0, S##b0, 0, buf_); G_ST1(S##a1, S##b1, 1, buf_); G_ST1(S##a2, S##b2, 2, buf_); G_ST1(S##a3, S##b3, 3, buf_); } while (0)
; template <class AL, class BL>
; DI void gemm_core(AL al, BL bl, int m0, int n0, int K, char* smem, f32x16 (&acc)[2][2]) {
;     ...
;   G_LOAD(x, 0);
;   G_STORE(x, 0);
;   G_LOAD(x, 1);
;   G_LOAD(y, (nk > 2) ? 2 : 1);
;   __syncthreads();
;   for (int kt = 0; kt < nk; kt += 2) {
;     G_TILE(0, x, true, (kt + 3 < nk), kt + 3);
;     __syncthreads();
;     G_TILE(1, y, (kt + 2 < nk), (kt + 4 < nk), kt + 4);
;     __syncthreads();
; template <class AL, class BL, class EP>
; DI void gemm_phase(int MT, int NTL, int K, AL al, BL bl, EP ep, char* smem) {
;   for (int t = blockIdx.x; t < MT * NTL; t += gridDim.x) {
;     const int tm = t % MT, tn = t / MT;
;     f32x16 acc[2][2];
;     gemm_core(al, bl, tm * 128, tn * 128, K, smem, acc);
;     ep(acc, tm * 128, tn * 128);
.Lfu0_tile:
	s_lshl_b32 s0, s34, 9
	v_add_u32_e32 v61, s0, v252
	s_lshl_b32 s0, s34, 7
	s_mul_i32 s1, s0, 8192
	s_mul_hi_u32 s2, s0, 8192
	s_add_u32 s20, s22, s1
	s_addc_u32 s21, s23, s2
	s_lshl_b32 s1, s35, 9
	s_add_u32 s20, s20, s1
	s_addc_u32 s21, s21, 0
	s_waitcnt vmcnt(6)
	ds_write_b128 v58, v[32:35] offset:0
	ds_write_b128 v58, v[36:39] offset:5120
	ds_write_b128 v58, v[40:43] offset:10240
	ds_write_b128 v58, v[44:47] offset:15360
	ds_write_b128 v58, v[48:51] offset:20480
	ds_write_b128 v58, v[52:55] offset:25600
	global_load_dwordx4 v[32:35], v[240:241], off offset:2176
	global_load_dwordx4 v[36:39], v[242:243], off offset:2176
	global_load_dwordx4 v[40:43], v[244:245], off offset:128
	global_load_dwordx4 v[44:47], v[246:247], off offset:128
	global_load_dwordx4 v[48:51], v[248:249], off offset:128
	global_load_dwordx4 v[52:55], v[250:251], off offset:128
	s_waitcnt lgkmcnt(0)
	s_barrier
	ds_read_b128 v[0:3], v57 offset:0
	ds_read_b128 v[4:7], v57 offset:2560
	ds_read_b128 v[8:11], v57 offset:5120
	ds_read_b128 v[12:15], v57 offset:7680
	ds_read_b128 v[16:19], v56 offset:0
	ds_read_b128 v[20:23], v56 offset:2560
	ds_read_b128 v[24:27], v56 offset:32
	ds_read_b128 v[28:31], v56 offset:2592
	s_waitcnt lgkmcnt(2)
	v_mfma_f32_32x32x16_bf16 v[66:81], v[16:19], v[0:3], 0
	v_mfma_f32_32x32x16_bf16 v[130:145], v[20:23], v[0:3], 0
	ds_read_b128 v[0:3], v57 offset:32
	s_waitcnt vmcnt(6)
	ds_write_b128 v58, v[214:217] offset:30720
	ds_write_b128 v58, v[218:221] offset:35840
	v_mfma_f32_32x32x16_bf16 v[82:97], v[16:19], v[4:7], 0
	v_mfma_f32_32x32x16_bf16 v[146:161], v[20:23], v[4:7], 0
	ds_read_b128 v[4:7], v57 offset:2592
	ds_write_b128 v58, v[222:225] offset:40960
	ds_write_b128 v58, v[228:231] offset:46080
	v_mfma_f32_32x32x16_bf16 v[98:113], v[16:19], v[8:11], 0
	v_mfma_f32_32x32x16_bf16 v[162:177], v[20:23], v[8:11], 0
	ds_read_b128 v[8:11], v57 offset:5152
	ds_write_b128 v58, v[232:235] offset:51200
	ds_write_b128 v58, v[236:239] offset:56320
	v_mfma_f32_32x32x16_bf16 v[114:129], v[16:19], v[12:15], 0
	v_mfma_f32_32x32x16_bf16 v[178:193], v[20:23], v[12:15], 0
	ds_read_b128 v[12:15], v57 offset:7712
	s_waitcnt lgkmcnt(9)
	v_mfma_f32_32x32x16_bf16 v[66:81], v[24:27], v[0:3], v[66:81]
	global_load_dwordx4 v[214:217], v[240:241], off offset:2240
	global_load_dwordx4 v[218:221], v[242:243], off offset:2240
	v_mfma_f32_32x32x16_bf16 v[130:145], v[28:31], v[0:3], v[130:145]
	s_waitcnt lgkmcnt(6)
	v_mfma_f32_32x32x16_bf16 v[82:97], v[24:27], v[4:7], v[82:97]
	global_load_dwordx4 v[222:225], v[244:245], off offset:192
	global_load_dwordx4 v[228:231], v[246:247], off offset:192
	v_mfma_f32_32x32x16_bf16 v[146:161], v[28:31], v[4:7], v[146:161]
	s_waitcnt lgkmcnt(3)
	v_mfma_f32_32x32x16_bf16 v[98:113], v[24:27], v[8:11], v[98:113]
	global_load_dwordx4 v[232:235], v[248:249], off offset:192
	global_load_dwordx4 v[236:239], v[250:251], off offset:192
	v_mfma_f32_32x32x16_bf16 v[162:177], v[28:31], v[8:11], v[162:177]
	s_waitcnt lgkmcnt(0)
	v_mfma_f32_32x32x16_bf16 v[114:129], v[24:27], v[12:15], v[114:129]
	v_mfma_f32_32x32x16_bf16 v[178:193], v[28:31], v[12:15], v[178:193]
	s_waitcnt lgkmcnt(0)
	s_barrier
	ds_read_b128 v[0:3], v57 offset:30720
	ds_read_b128 v[4:7], v57 offset:33280
	ds_read_b128 v[8:11], v57 offset:35840
	ds_read_b128 v[12:15], v57 offset:38400
	ds_read_b128 v[16:19], v56 offset:30720
	ds_read_b128 v[20:23], v56 offset:33280
	ds_read_b128 v[24:27], v56 offset:30752
	ds_read_b128 v[28:31], v56 offset:33312
	s_waitcnt lgkmcnt(2)
	v_mfma_f32_32x32x16_bf16 v[66:81], v[16:19], v[0:3], v[66:81]
	v_mfma_f32_32x32x16_bf16 v[130:145], v[20:23], v[0:3], v[130:145]
	ds_read_b128 v[0:3], v57 offset:30752
	s_waitcnt vmcnt(6)
	ds_write_b128 v58, v[32:35] offset:0
	ds_write_b128 v58, v[36:39] offset:5120
	v_mfma_f32_32x32x16_bf16 v[82:97], v[16:19], v[4:7], v[82:97]
	v_mfma_f32_32x32x16_bf16 v[146:161], v[20:23], v[4:7], v[146:161]
	ds_read_b128 v[4:7], v57 offset:33312
	ds_write_b128 v58, v[40:43] offset:10240
	ds_write_b128 v58, v[44:47] offset:15360
	v_mfma_f32_32x32x16_bf16 v[98:113], v[16:19], v[8:11], v[98:113]
	v_mfma_f32_32x32x16_bf16 v[162:177], v[20:23], v[8:11], v[162:177]
	ds_read_b128 v[8:11], v57 offset:35872
	ds_write_b128 v58, v[48:51] offset:20480
	ds_write_b128 v58, v[52:55] offset:25600
	v_mfma_f32_32x32x16_bf16 v[114:129], v[16:19], v[12:15], v[114:129]
	v_mfma_f32_32x32x16_bf16 v[178:193], v[20:23], v[12:15], v[178:193]
	ds_read_b128 v[12:15], v57 offset:38432
	s_waitcnt lgkmcnt(9)
	v_mfma_f32_32x32x16_bf16 v[66:81], v[24:27], v[0:3], v[66:81]
	global_load_dwordx4 v[32:35], v[240:241], off offset:2304
	global_load_dwordx4 v[36:39], v[242:243], off offset:2304
	v_mfma_f32_32x32x16_bf16 v[130:145], v[28:31], v[0:3], v[130:145]
	s_waitcnt lgkmcnt(6)
	v_mfma_f32_32x32x16_bf16 v[82:97], v[24:27], v[4:7], v[82:97]
	global_load_dwordx4 v[40:43], v[244:245], off offset:256
	global_load_dwordx4 v[44:47], v[246:247], off offset:256
	v_mfma_f32_32x32x16_bf16 v[146:161], v[28:31], v[4:7], v[146:161]
	s_waitcnt lgkmcnt(3)
	v_mfma_f32_32x32x16_bf16 v[98:113], v[24:27], v[8:11], v[98:113]
	global_load_dwordx4 v[48:51], v[248:249], off offset:256
	global_load_dwordx4 v[52:55], v[250:251], off offset:256
	v_mfma_f32_32x32x16_bf16 v[162:177], v[28:31], v[8:11], v[162:177]
	s_waitcnt lgkmcnt(0)
	v_mfma_f32_32x32x16_bf16 v[114:129], v[24:27], v[12:15], v[114:129]
	v_mfma_f32_32x32x16_bf16 v[178:193], v[28:31], v[12:15], v[178:193]
	s_waitcnt lgkmcnt(0)
	s_barrier
; #define G_LOAD(S, kt_) do { G_LD1(S##a0, S##b0, 0, kt_); G_LD1(S##a1, S##b1, 1, kt_); G_LD1(S##a2, S##b2, 2, kt_); G_LD1(S##a3, S##b3, 3, kt_); } while (0)
; #define G_STORE(S, buf_) do { G_ST1(S##a0, S##b0, 0, buf_); G_ST1(S##a1, S##b1, 1, buf_); G_ST1(S##a2, S##b2, 2, buf_); G_ST1(S##a3, S##b3, 3, buf_); } while (0)
; template <class AL, class BL>
; DI void gemm_core(AL al, BL bl, int m0, int n0, int K, char* smem, f32x16 (&acc)[2][2]) {
;     ...
;   G_LOAD(x, 0);
;   G_STORE(x, 0);
;   G_LOAD(x, 1);
;   G_LOAD(y, (nk > 2) ? 2 : 1);
;   __syncthreads();
;   for (int kt = 0; kt < nk; kt += 2) {
;     G_TILE(0, x, true, (kt + 3 < nk), kt + 3);
;     __syncthreads();
;     G_TILE(1, y, (kt + 2 < nk), (kt + 4 < nk), kt + 4);
;     __syncthreads();
	ds_read_b128 v[0:3], v57 offset:0
	ds_read_b128 v[4:7], v57 offset:2560
	ds_read_b128 v[8:11], v57 offset:5120
	ds_read_b128 v[12:15], v57 offset:7680
	ds_read_b128 v[16:19], v56 offset:0
	ds_read_b128 v[20:23], v56 offset:2560
	ds_read_b128 v[24:27], v56 offset:32
	ds_read_b128 v[28:31], v56 offset:2592
	s_waitcnt lgkmcnt(2)
	v_mfma_f32_32x32x16_bf16 v[66:81], v[16:19], v[0:3], v[66:81]
	v_mfma_f32_32x32x16_bf16 v[130:145], v[20:23], v[0:3], v[130:145]
	ds_read_b128 v[0:3], v57 offset:32
	s_waitcnt vmcnt(6)
	ds_write_b128 v58, v[214:217] offset:30720
	ds_write_b128 v58, v[218:221] offset:35840
	v_mfma_f32_32x32x16_bf16 v[82:97], v[16:19], v[4:7], v[82:97]
	v_mfma_f32_32x32x16_bf16 v[146:161], v[20:23], v[4:7], v[146:161]
	ds_read_b128 v[4:7], v57 offset:2592
	ds_write_b128 v58, v[222:225] offset:40960
	ds_write_b128 v58, v[228:231] offset:46080
	v_mfma_f32_32x32x16_bf16 v[98:113], v[16:19], v[8:11], v[98:113]
	v_mfma_f32_32x32x16_bf16 v[162:177], v[20:23], v[8:11], v[162:177]
	ds_read_b128 v[8:11], v57 offset:5152
	ds_write_b128 v58, v[232:235] offset:51200
	ds_write_b128 v58, v[236:239] offset:56320
	v_mfma_f32_32x32x16_bf16 v[114:129], v[16:19], v[12:15], v[114:129]
	v_mfma_f32_32x32x16_bf16 v[178:193], v[20:23], v[12:15], v[178:193]
	ds_read_b128 v[12:15], v57 offset:7712
	s_waitcnt lgkmcnt(9)
	v_mfma_f32_32x32x16_bf16 v[66:81], v[24:27], v[0:3], v[66:81]
	global_load_dwordx4 v[214:217], v[240:241], off offset:2368
	global_load_dwordx4 v[218:221], v[242:243], off offset:2368
	v_mfma_f32_32x32x16_bf16 v[130:145], v[28:31], v[0:3], v[130:145]
	s_waitcnt lgkmcnt(6)
	v_mfma_f32_32x32x16_bf16 v[82:97], v[24:27], v[4:7], v[82:97]
	global_load_dwordx4 v[222:225], v[244:245], off offset:320
	global_load_dwordx4 v[228:231], v[246:247], off offset:320
	v_mfma_f32_32x32x16_bf16 v[146:161], v[28:31], v[4:7], v[146:161]
	s_waitcnt lgkmcnt(3)
	v_mfma_f32_32x32x16_bf16 v[98:113], v[24:27], v[8:11], v[98:113]
	global_load_dwordx4 v[232:235], v[248:249], off offset:320
	global_load_dwordx4 v[236:239], v[250:251], off offset:320
	v_mfma_f32_32x32x16_bf16 v[162:177], v[28:31], v[8:11], v[162:177]
	s_waitcnt lgkmcnt(0)
	v_mfma_f32_32x32x16_bf16 v[114:129], v[24:27], v[12:15], v[114:129]
	v_mfma_f32_32x32x16_bf16 v[178:193], v[28:31], v[12:15], v[178:193]
	s_waitcnt lgkmcnt(0)
	s_barrier
	ds_read_b128 v[0:3], v57 offset:30720
	ds_read_b128 v[4:7], v57 offset:33280
	ds_read_b128 v[8:11], v57 offset:35840
	ds_read_b128 v[12:15], v57 offset:38400
	ds_read_b128 v[16:19], v56 offset:30720
	ds_read_b128 v[20:23], v56 offset:33280
	ds_read_b128 v[24:27], v56 offset:30752
	ds_read_b128 v[28:31], v56 offset:33312
	s_waitcnt lgkmcnt(2)
	v_mfma_f32_32x32x16_bf16 v[66:81], v[16:19], v[0:3], v[66:81]
	v_mfma_f32_32x32x16_bf16 v[130:145], v[20:23], v[0:3], v[130:145]
	ds_read_b128 v[0:3], v57 offset:30752
	s_waitcnt vmcnt(6)
	ds_write_b128 v58, v[32:35] offset:0
	ds_write_b128 v58, v[36:39] offset:5120
	v_mfma_f32_32x32x16_bf16 v[82:97], v[16:19], v[4:7], v[82:97]
	v_mfma_f32_32x32x16_bf16 v[146:161], v[20:23], v[4:7], v[146:161]
	ds_read_b128 v[4:7], v57 offset:33312
	ds_write_b128 v58, v[40:43] offset:10240
	ds_write_b128 v58, v[44:47] offset:15360
	v_mfma_f32_32x32x16_bf16 v[98:113], v[16:19], v[8:11], v[98:113]
	v_mfma_f32_32x32x16_bf16 v[162:177], v[20:23], v[8:11], v[162:177]
	ds_read_b128 v[8:11], v57 offset:35872
	ds_write_b128 v58, v[48:51] offset:20480
	ds_write_b128 v58, v[52:55] offset:25600
	v_mfma_f32_32x32x16_bf16 v[114:129], v[16:19], v[12:15], v[114:129]
	v_mfma_f32_32x32x16_bf16 v[178:193], v[20:23], v[12:15], v[178:193]
	ds_read_b128 v[12:15], v57 offset:38432
	s_waitcnt lgkmcnt(9)
	v_mfma_f32_32x32x16_bf16 v[66:81], v[24:27], v[0:3], v[66:81]
	global_load_dwordx4 v[32:35], v[240:241], off offset:2432
	global_load_dwordx4 v[36:39], v[242:243], off offset:2432
	v_mfma_f32_32x32x16_bf16 v[130:145], v[28:31], v[0:3], v[130:145]
	s_waitcnt lgkmcnt(6)
	v_mfma_f32_32x32x16_bf16 v[82:97], v[24:27], v[4:7], v[82:97]
	global_load_dwordx4 v[40:43], v[244:245], off offset:384
	global_load_dwordx4 v[44:47], v[246:247], off offset:384
	v_mfma_f32_32x32x16_bf16 v[146:161], v[28:31], v[4:7], v[146:161]
	s_waitcnt lgkmcnt(3)
	v_mfma_f32_32x32x16_bf16 v[98:113], v[24:27], v[8:11], v[98:113]
	global_load_dwordx4 v[48:51], v[248:249], off offset:384
	global_load_dwordx4 v[52:55], v[250:251], off offset:384
	v_mfma_f32_32x32x16_bf16 v[162:177], v[28:31], v[8:11], v[162:177]
	s_waitcnt lgkmcnt(0)
	v_mfma_f32_32x32x16_bf16 v[114:129], v[24:27], v[12:15], v[114:129]
	v_mfma_f32_32x32x16_bf16 v[178:193], v[28:31], v[12:15], v[178:193]
	s_waitcnt lgkmcnt(0)
	s_barrier
; #define G_LOAD(S, kt_) do { G_LD1(S##a0, S##b0, 0, kt_); G_LD1(S##a1, S##b1, 1, kt_); G_LD1(S##a2, S##b2, 2, kt_); G_LD1(S##a3, S##b3, 3, kt_); } while (0)
; #define G_STORE(S, buf_) do { G_ST1(S##a0, S##b0, 0, buf_); G_ST1(S##a1, S##b1, 1, buf_); G_ST1(S##a2, S##b2, 2, buf_); G_ST1(S##a3, S##b3, 3, buf_); } while (0)
; template <class AL, class BL>
; DI void gemm_core(AL al, BL bl, int m0, int n0, int K, char* smem, f32x16 (&acc)[2][2]) {
;     ...
;   G_LOAD(x, 0);
;   G_STORE(x, 0);
;   G_LOAD(x, 1);
;   G_LOAD(y, (nk > 2) ? 2 : 1);
;   __syncthreads();
;   for (int kt = 0; kt < nk; kt += 2) {
;     G_TILE(0, x, true, (kt + 3 < nk), kt + 3);
;     __syncthreads();
;     G_TILE(1, y, (kt + 2 < nk), (kt + 4 < nk), kt + 4);
;     __syncthreads();
	ds_read_b128 v[0:3], v57 offset:0
	ds_read_b128 v[4:7], v57 offset:2560
	ds_read_b128 v[8:11], v57 offset:5120
	ds_read_b128 v[12:15], v57 offset:7680
	ds_read_b128 v[16:19], v56 offset:0
	ds_read_b128 v[20:23], v56 offset:2560
	ds_read_b128 v[24:27], v56 offset:32
	ds_read_b128 v[28:31], v56 offset:2592
	s_waitcnt lgkmcnt(2)
	v_mfma_f32_32x32x16_bf16 v[66:81], v[16:19], v[0:3], v[66:81]
	v_mfma_f32_32x32x16_bf16 v[130:145], v[20:23], v[0:3], v[130:145]
	ds_read_b128 v[0:3], v57 offset:32
	s_waitcnt vmcnt(6)
	ds_write_b128 v58, v[214:217] offset:30720
	ds_write_b128 v58, v[218:221] offset:35840
	v_mfma_f32_32x32x16_bf16 v[82:97], v[16:19], v[4:7], v[82:97]
	v_mfma_f32_32x32x16_bf16 v[146:161], v[20:23], v[4:7], v[146:161]
	ds_read_b128 v[4:7], v57 offset:2592
	ds_write_b128 v58, v[222:225] offset:40960
	ds_write_b128 v58, v[228:231] offset:46080
	v_mfma_f32_32x32x16_bf16 v[98:113], v[16:19], v[8:11], v[98:113]
	v_mfma_f32_32x32x16_bf16 v[162:177], v[20:23], v[8:11], v[162:177]
	ds_read_b128 v[8:11], v57 offset:5152
	ds_write_b128 v58, v[232:235] offset:51200
	ds_write_b128 v58, v[236:239] offset:56320
	v_mfma_f32_32x32x16_bf16 v[114:129], v[16:19], v[12:15], v[114:129]
	v_mfma_f32_32x32x16_bf16 v[178:193], v[20:23], v[12:15], v[178:193]
	ds_read_b128 v[12:15], v57 offset:7712
	s_waitcnt lgkmcnt(9)
	v_mfma_f32_32x32x16_bf16 v[66:81], v[24:27], v[0:3], v[66:81]
	global_load_dwordx4 v[214:217], v[240:241], off offset:2496
	global_load_dwordx4 v[218:221], v[242:243], off offset:2496
	v_mfma_f32_32x32x16_bf16 v[130:145], v[28:31], v[0:3], v[130:145]
	s_waitcnt lgkmcnt(6)
	v_mfma_f32_32x32x16_bf16 v[82:97], v[24:27], v[4:7], v[82:97]
	global_load_dwordx4 v[222:225], v[244:245], off offset:448
	global_load_dwordx4 v[228:231], v[246:247], off offset:448
	v_mfma_f32_32x32x16_bf16 v[146:161], v[28:31], v[4:7], v[146:161]
	s_waitcnt lgkmcnt(3)
	v_mfma_f32_32x32x16_bf16 v[98:113], v[24:27], v[8:11], v[98:113]
	global_load_dwordx4 v[232:235], v[248:249], off offset:448
	global_load_dwordx4 v[236:239], v[250:251], off offset:448
	v_mfma_f32_32x32x16_bf16 v[162:177], v[28:31], v[8:11], v[162:177]
	s_waitcnt lgkmcnt(0)
	v_mfma_f32_32x32x16_bf16 v[114:129], v[24:27], v[12:15], v[114:129]
	v_mfma_f32_32x32x16_bf16 v[178:193], v[28:31], v[12:15], v[178:193]
	s_waitcnt lgkmcnt(0)
	s_barrier
	ds_read_b128 v[0:3], v57 offset:30720
	ds_read_b128 v[4:7], v57 offset:33280
	ds_read_b128 v[8:11], v57 offset:35840
	ds_read_b128 v[12:15], v57 offset:38400
	ds_read_b128 v[16:19], v56 offset:30720
	ds_read_b128 v[20:23], v56 offset:33280
	ds_read_b128 v[24:27], v56 offset:30752
	ds_read_b128 v[28:31], v56 offset:33312
	s_waitcnt lgkmcnt(2)
	v_mfma_f32_32x32x16_bf16 v[66:81], v[16:19], v[0:3], v[66:81]
	v_mfma_f32_32x32x16_bf16 v[130:145], v[20:23], v[0:3], v[130:145]
	ds_read_b128 v[0:3], v57 offset:30752
	s_waitcnt vmcnt(6)
	ds_write_b128 v58, v[32:35] offset:0
	ds_write_b128 v58, v[36:39] offset:5120
	v_mfma_f32_32x32x16_bf16 v[82:97], v[16:19], v[4:7], v[82:97]
	v_mfma_f32_32x32x16_bf16 v[146:161], v[20:23], v[4:7], v[146:161]
	ds_read_b128 v[4:7], v57 offset:33312
	ds_write_b128 v58, v[40:43] offset:10240
	ds_write_b128 v58, v[44:47] offset:15360
	v_mfma_f32_32x32x16_bf16 v[98:113], v[16:19], v[8:11], v[98:113]
	v_mfma_f32_32x32x16_bf16 v[162:177], v[20:23], v[8:11], v[162:177]
	ds_read_b128 v[8:11], v57 offset:35872
	ds_write_b128 v58, v[48:51] offset:20480
	ds_write_b128 v58, v[52:55] offset:25600
	v_mfma_f32_32x32x16_bf16 v[114:129], v[16:19], v[12:15], v[114:129]
	v_mfma_f32_32x32x16_bf16 v[178:193], v[20:23], v[12:15], v[178:193]
	ds_read_b128 v[12:15], v57 offset:38432
	s_waitcnt lgkmcnt(9)
	v_mfma_f32_32x32x16_bf16 v[66:81], v[24:27], v[0:3], v[66:81]
	global_load_dwordx4 v[32:35], v[240:241], off offset:2560
	global_load_dwordx4 v[36:39], v[242:243], off offset:2560
	v_mfma_f32_32x32x16_bf16 v[130:145], v[28:31], v[0:3], v[130:145]
	s_waitcnt lgkmcnt(6)
	v_mfma_f32_32x32x16_bf16 v[82:97], v[24:27], v[4:7], v[82:97]
	global_load_dwordx4 v[40:43], v[244:245], off offset:512
	global_load_dwordx4 v[44:47], v[246:247], off offset:512
	v_mfma_f32_32x32x16_bf16 v[146:161], v[28:31], v[4:7], v[146:161]
	s_waitcnt lgkmcnt(3)
	v_mfma_f32_32x32x16_bf16 v[98:113], v[24:27], v[8:11], v[98:113]
	global_load_dwordx4 v[48:51], v[248:249], off offset:512
	global_load_dwordx4 v[52:55], v[250:251], off offset:512
	v_mfma_f32_32x32x16_bf16 v[162:177], v[28:31], v[8:11], v[162:177]
	s_waitcnt lgkmcnt(0)
	v_mfma_f32_32x32x16_bf16 v[114:129], v[24:27], v[12:15], v[114:129]
	v_mfma_f32_32x32x16_bf16 v[178:193], v[28:31], v[12:15], v[178:193]
	s_waitcnt lgkmcnt(0)
	s_barrier
; #define G_LOAD(S, kt_) do { G_LD1(S##a0, S##b0, 0, kt_); G_LD1(S##a1, S##b1, 1, kt_); G_LD1(S##a2, S##b2, 2, kt_); G_LD1(S##a3, S##b3, 3, kt_); } while (0)
; #define G_STORE(S, buf_) do { G_ST1(S##a0, S##b0, 0, buf_); G_ST1(S##a1, S##b1, 1, buf_); G_ST1(S##a2, S##b2, 2, buf_); G_ST1(S##a3, S##b3, 3, buf_); } while (0)
; template <class AL, class BL>
; DI void gemm_core(AL al, BL bl, int m0, int n0, int K, char* smem, f32x16 (&acc)[2][2]) {
;     ...
;   G_LOAD(x, 0);
;   G_STORE(x, 0);
;   G_LOAD(x, 1);
;   G_LOAD(y, (nk > 2) ? 2 : 1);
;   __syncthreads();
;   for (int kt = 0; kt < nk; kt += 2) {
;     G_TILE(0, x, true, (kt + 3 < nk), kt + 3);
;     __syncthreads();
;     G_TILE(1, y, (kt + 2 < nk), (kt + 4 < nk), kt + 4);
;     __syncthreads();
	ds_read_b128 v[0:3], v57 offset:0
	ds_read_b128 v[4:7], v57 offset:2560
	ds_read_b128 v[8:11], v57 offset:5120
	ds_read_b128 v[12:15], v57 offset:7680
	ds_read_b128 v[16:19], v56 offset:0
	ds_read_b128 v[20:23], v56 offset:2560
	ds_read_b128 v[24:27], v56 offset:32
	ds_read_b128 v[28:31], v56 offset:2592
	s_waitcnt lgkmcnt(2)
	v_mfma_f32_32x32x16_bf16 v[66:81], v[16:19], v[0:3], v[66:81]
	v_mfma_f32_32x32x16_bf16 v[130:145], v[20:23], v[0:3], v[130:145]
	ds_read_b128 v[0:3], v57 offset:32
	s_waitcnt vmcnt(6)
	ds_write_b128 v58, v[214:217] offset:30720
	ds_write_b128 v58, v[218:221] offset:35840
	v_mfma_f32_32x32x16_bf16 v[82:97], v[16:19], v[4:7], v[82:97]
	v_mfma_f32_32x32x16_bf16 v[146:161], v[20:23], v[4:7], v[146:161]
	ds_read_b128 v[4:7], v57 offset:2592
	ds_write_b128 v58, v[222:225] offset:40960
	ds_write_b128 v58, v[228:231] offset:46080
	v_mfma_f32_32x32x16_bf16 v[98:113], v[16:19], v[8:11], v[98:113]
	v_mfma_f32_32x32x16_bf16 v[162:177], v[20:23], v[8:11], v[162:177]
	ds_read_b128 v[8:11], v57 offset:5152
	ds_write_b128 v58, v[232:235] offset:51200
	ds_write_b128 v58, v[236:239] offset:56320
	v_mfma_f32_32x32x16_bf16 v[114:129], v[16:19], v[12:15], v[114:129]
	v_mfma_f32_32x32x16_bf16 v[178:193], v[20:23], v[12:15], v[178:193]
	ds_read_b128 v[12:15], v57 offset:7712
	s_waitcnt lgkmcnt(9)
	v_mfma_f32_32x32x16_bf16 v[66:81], v[24:27], v[0:3], v[66:81]
	global_load_dwordx4 v[214:217], v[240:241], off offset:2624
	global_load_dwordx4 v[218:221], v[242:243], off offset:2624
	v_mfma_f32_32x32x16_bf16 v[130:145], v[28:31], v[0:3], v[130:145]
	s_waitcnt lgkmcnt(6)
	v_mfma_f32_32x32x16_bf16 v[82:97], v[24:27], v[4:7], v[82:97]
	global_load_dwordx4 v[222:225], v[244:245], off offset:576
	global_load_dwordx4 v[228:231], v[246:247], off offset:576
	v_mfma_f32_32x32x16_bf16 v[146:161], v[28:31], v[4:7], v[146:161]
	s_waitcnt lgkmcnt(3)
	v_mfma_f32_32x32x16_bf16 v[98:113], v[24:27], v[8:11], v[98:113]
	global_load_dwordx4 v[232:235], v[248:249], off offset:576
	global_load_dwordx4 v[236:239], v[250:251], off offset:576
	v_mfma_f32_32x32x16_bf16 v[162:177], v[28:31], v[8:11], v[162:177]
	s_waitcnt lgkmcnt(0)
	v_mfma_f32_32x32x16_bf16 v[114:129], v[24:27], v[12:15], v[114:129]
	v_mfma_f32_32x32x16_bf16 v[178:193], v[28:31], v[12:15], v[178:193]
	s_waitcnt lgkmcnt(0)
	s_barrier
	ds_read_b128 v[0:3], v57 offset:30720
	ds_read_b128 v[4:7], v57 offset:33280
	ds_read_b128 v[8:11], v57 offset:35840
	ds_read_b128 v[12:15], v57 offset:38400
	ds_read_b128 v[16:19], v56 offset:30720
	ds_read_b128 v[20:23], v56 offset:33280
	ds_read_b128 v[24:27], v56 offset:30752
	ds_read_b128 v[28:31], v56 offset:33312
	s_waitcnt lgkmcnt(2)
	v_mfma_f32_32x32x16_bf16 v[66:81], v[16:19], v[0:3], v[66:81]
	v_mfma_f32_32x32x16_bf16 v[130:145], v[20:23], v[0:3], v[130:145]
	ds_read_b128 v[0:3], v57 offset:30752
	s_waitcnt vmcnt(6)
	ds_write_b128 v58, v[32:35] offset:0
	ds_write_b128 v58, v[36:39] offset:5120
	v_mfma_f32_32x32x16_bf16 v[82:97], v[16:19], v[4:7], v[82:97]
	v_mfma_f32_32x32x16_bf16 v[146:161], v[20:23], v[4:7], v[146:161]
	ds_read_b128 v[4:7], v57 offset:33312
	ds_write_b128 v58, v[40:43] offset:10240
	ds_write_b128 v58, v[44:47] offset:15360
	v_mfma_f32_32x32x16_bf16 v[98:113], v[16:19], v[8:11], v[98:113]
	v_mfma_f32_32x32x16_bf16 v[162:177], v[20:23], v[8:11], v[162:177]
	ds_read_b128 v[8:11], v57 offset:35872
	ds_write_b128 v58, v[48:51] offset:20480
	ds_write_b128 v58, v[52:55] offset:25600
	v_mfma_f32_32x32x16_bf16 v[114:129], v[16:19], v[12:15], v[114:129]
	v_mfma_f32_32x32x16_bf16 v[178:193], v[20:23], v[12:15], v[178:193]
	ds_read_b128 v[12:15], v57 offset:38432
	s_waitcnt lgkmcnt(9)
	v_mfma_f32_32x32x16_bf16 v[66:81], v[24:27], v[0:3], v[66:81]
	global_load_dwordx4 v[32:35], v[240:241], off offset:2688
	global_load_dwordx4 v[36:39], v[242:243], off offset:2688
	v_mfma_f32_32x32x16_bf16 v[130:145], v[28:31], v[0:3], v[130:145]
	s_waitcnt lgkmcnt(6)
	v_mfma_f32_32x32x16_bf16 v[82:97], v[24:27], v[4:7], v[82:97]
	global_load_dwordx4 v[40:43], v[244:245], off offset:640
	global_load_dwordx4 v[44:47], v[246:247], off offset:640
	v_mfma_f32_32x32x16_bf16 v[146:161], v[28:31], v[4:7], v[146:161]
	s_waitcnt lgkmcnt(3)
	v_mfma_f32_32x32x16_bf16 v[98:113], v[24:27], v[8:11], v[98:113]
	global_load_dwordx4 v[48:51], v[248:249], off offset:640
	global_load_dwordx4 v[52:55], v[250:251], off offset:640
	v_mfma_f32_32x32x16_bf16 v[162:177], v[28:31], v[8:11], v[162:177]
	s_waitcnt lgkmcnt(0)
	v_mfma_f32_32x32x16_bf16 v[114:129], v[24:27], v[12:15], v[114:129]
	v_mfma_f32_32x32x16_bf16 v[178:193], v[28:31], v[12:15], v[178:193]
	s_waitcnt lgkmcnt(0)
	s_barrier
; #define G_LOAD(S, kt_) do { G_LD1(S##a0, S##b0, 0, kt_); G_LD1(S##a1, S##b1, 1, kt_); G_LD1(S##a2, S##b2, 2, kt_); G_LD1(S##a3, S##b3, 3, kt_); } while (0)
; #define G_STORE(S, buf_) do { G_ST1(S##a0, S##b0, 0, buf_); G_ST1(S##a1, S##b1, 1, buf_); G_ST1(S##a2, S##b2, 2, buf_); G_ST1(S##a3, S##b3, 3, buf_); } while (0)
; template <class AL, class BL>
; DI void gemm_core(AL al, BL bl, int m0, int n0, int K, char* smem, f32x16 (&acc)[2][2]) {
;     ...
;   G_LOAD(x, 0);
;   G_STORE(x, 0);
;   G_LOAD(x, 1);
;   G_LOAD(y, (nk > 2) ? 2 : 1);
;   __syncthreads();
;   for (int kt = 0; kt < nk; kt += 2) {
;     G_TILE(0, x, true, (kt + 3 < nk), kt + 3);
;     __syncthreads();
;     G_TILE(1, y, (kt + 2 < nk), (kt + 4 < nk), kt + 4);
;     __syncthreads();
	ds_read_b128 v[0:3], v57 offset:0
	ds_read_b128 v[4:7], v57 offset:2560
	ds_read_b128 v[8:11], v57 offset:5120
	ds_read_b128 v[12:15], v57 offset:7680
	ds_read_b128 v[16:19], v56 offset:0
	ds_read_b128 v[20:23], v56 offset:2560
	ds_read_b128 v[24:27], v56 offset:32
	ds_read_b128 v[28:31], v56 offset:2592
	s_waitcnt lgkmcnt(2)
	v_mfma_f32_32x32x16_bf16 v[66:81], v[16:19], v[0:3], v[66:81]
	v_mfma_f32_32x32x16_bf16 v[130:145], v[20:23], v[0:3], v[130:145]
	ds_read_b128 v[0:3], v57 offset:32
	s_waitcnt vmcnt(6)
	ds_write_b128 v58, v[214:217] offset:30720
	ds_write_b128 v58, v[218:221] offset:35840
	v_mfma_f32_32x32x16_bf16 v[82:97], v[16:19], v[4:7], v[82:97]
	v_mfma_f32_32x32x16_bf16 v[146:161], v[20:23], v[4:7], v[146:161]
	ds_read_b128 v[4:7], v57 offset:2592
	ds_write_b128 v58, v[222:225] offset:40960
	ds_write_b128 v58, v[228:231] offset:46080
	v_mfma_f32_32x32x16_bf16 v[98:113], v[16:19], v[8:11], v[98:113]
	v_mfma_f32_32x32x16_bf16 v[162:177], v[20:23], v[8:11], v[162:177]
	ds_read_b128 v[8:11], v57 offset:5152
	ds_write_b128 v58, v[232:235] offset:51200
	ds_write_b128 v58, v[236:239] offset:56320
	v_mfma_f32_32x32x16_bf16 v[114:129], v[16:19], v[12:15], v[114:129]
	v_mfma_f32_32x32x16_bf16 v[178:193], v[20:23], v[12:15], v[178:193]
	ds_read_b128 v[12:15], v57 offset:7712
	s_waitcnt lgkmcnt(9)
	v_mfma_f32_32x32x16_bf16 v[66:81], v[24:27], v[0:3], v[66:81]
	global_load_dwordx4 v[214:217], v[240:241], off offset:2752
	global_load_dwordx4 v[218:221], v[242:243], off offset:2752
	v_mfma_f32_32x32x16_bf16 v[130:145], v[28:31], v[0:3], v[130:145]
	s_waitcnt lgkmcnt(6)
	v_mfma_f32_32x32x16_bf16 v[82:97], v[24:27], v[4:7], v[82:97]
	global_load_dwordx4 v[222:225], v[244:245], off offset:704
	global_load_dwordx4 v[228:231], v[246:247], off offset:704
	v_mfma_f32_32x32x16_bf16 v[146:161], v[28:31], v[4:7], v[146:161]
	s_waitcnt lgkmcnt(3)
	v_mfma_f32_32x32x16_bf16 v[98:113], v[24:27], v[8:11], v[98:113]
	global_load_dwordx4 v[232:235], v[248:249], off offset:704
	global_load_dwordx4 v[236:239], v[250:251], off offset:704
	v_mfma_f32_32x32x16_bf16 v[162:177], v[28:31], v[8:11], v[162:177]
	s_waitcnt lgkmcnt(0)
	v_mfma_f32_32x32x16_bf16 v[114:129], v[24:27], v[12:15], v[114:129]
	v_mfma_f32_32x32x16_bf16 v[178:193], v[28:31], v[12:15], v[178:193]
	s_waitcnt lgkmcnt(0)
	s_barrier
	ds_read_b128 v[0:3], v57 offset:30720
	ds_read_b128 v[4:7], v57 offset:33280
	ds_read_b128 v[8:11], v57 offset:35840
	ds_read_b128 v[12:15], v57 offset:38400
	ds_read_b128 v[16:19], v56 offset:30720
	ds_read_b128 v[20:23], v56 offset:33280
	ds_read_b128 v[24:27], v56 offset:30752
	ds_read_b128 v[28:31], v56 offset:33312
	s_waitcnt lgkmcnt(2)
	v_mfma_f32_32x32x16_bf16 v[66:81], v[16:19], v[0:3], v[66:81]
	v_mfma_f32_32x32x16_bf16 v[130:145], v[20:23], v[0:3], v[130:145]
	ds_read_b128 v[0:3], v57 offset:30752
	s_waitcnt vmcnt(6)
	ds_write_b128 v58, v[32:35] offset:0
	ds_write_b128 v58, v[36:39] offset:5120
	v_mfma_f32_32x32x16_bf16 v[82:97], v[16:19], v[4:7], v[82:97]
	v_mfma_f32_32x32x16_bf16 v[146:161], v[20:23], v[4:7], v[146:161]
	ds_read_b128 v[4:7], v57 offset:33312
	ds_write_b128 v58, v[40:43] offset:10240
	ds_write_b128 v58, v[44:47] offset:15360
	v_mfma_f32_32x32x16_bf16 v[98:113], v[16:19], v[8:11], v[98:113]
	v_mfma_f32_32x32x16_bf16 v[162:177], v[20:23], v[8:11], v[162:177]
	ds_read_b128 v[8:11], v57 offset:35872
	ds_write_b128 v58, v[48:51] offset:20480
	ds_write_b128 v58, v[52:55] offset:25600
	v_mfma_f32_32x32x16_bf16 v[114:129], v[16:19], v[12:15], v[114:129]
	v_mfma_f32_32x32x16_bf16 v[178:193], v[20:23], v[12:15], v[178:193]
	ds_read_b128 v[12:15], v57 offset:38432
	s_waitcnt lgkmcnt(9)
	v_mfma_f32_32x32x16_bf16 v[66:81], v[24:27], v[0:3], v[66:81]
	global_load_dwordx4 v[32:35], v[240:241], off offset:2816
	global_load_dwordx4 v[36:39], v[242:243], off offset:2816
	v_mfma_f32_32x32x16_bf16 v[130:145], v[28:31], v[0:3], v[130:145]
	s_waitcnt lgkmcnt(6)
	v_mfma_f32_32x32x16_bf16 v[82:97], v[24:27], v[4:7], v[82:97]
	global_load_dwordx4 v[40:43], v[244:245], off offset:768
	global_load_dwordx4 v[44:47], v[246:247], off offset:768
	v_mfma_f32_32x32x16_bf16 v[146:161], v[28:31], v[4:7], v[146:161]
	s_waitcnt lgkmcnt(3)
	v_mfma_f32_32x32x16_bf16 v[98:113], v[24:27], v[8:11], v[98:113]
	global_load_dwordx4 v[48:51], v[248:249], off offset:768
	global_load_dwordx4 v[52:55], v[250:251], off offset:768
	v_mfma_f32_32x32x16_bf16 v[162:177], v[28:31], v[8:11], v[162:177]
	s_waitcnt lgkmcnt(0)
	v_mfma_f32_32x32x16_bf16 v[114:129], v[24:27], v[12:15], v[114:129]
	v_mfma_f32_32x32x16_bf16 v[178:193], v[28:31], v[12:15], v[178:193]
	s_waitcnt lgkmcnt(0)
	s_barrier
; #define G_LOAD(S, kt_) do { G_LD1(S##a0, S##b0, 0, kt_); G_LD1(S##a1, S##b1, 1, kt_); G_LD1(S##a2, S##b2, 2, kt_); G_LD1(S##a3, S##b3, 3, kt_); } while (0)
; #define G_STORE(S, buf_) do { G_ST1(S##a0, S##b0, 0, buf_); G_ST1(S##a1, S##b1, 1, buf_); G_ST1(S##a2, S##b2, 2, buf_); G_ST1(S##a3, S##b3, 3, buf_); } while (0)
; template <class AL, class BL>
; DI void gemm_core(AL al, BL bl, int m0, int n0, int K, char* smem, f32x16 (&acc)[2][2]) {
;     ...
;   G_LOAD(x, 0);
;   G_STORE(x, 0);
;   G_LOAD(x, 1);
;   G_LOAD(y, (nk > 2) ? 2 : 1);
;   __syncthreads();
;   for (int kt = 0; kt < nk; kt += 2) {
;     G_TILE(0, x, true, (kt + 3 < nk), kt + 3);
;     __syncthreads();
;     G_TILE(1, y, (kt + 2 < nk), (kt + 4 < nk), kt + 4);
;     __syncthreads();
	ds_read_b128 v[0:3], v57 offset:0
	ds_read_b128 v[4:7], v57 offset:2560
	ds_read_b128 v[8:11], v57 offset:5120
	ds_read_b128 v[12:15], v57 offset:7680
	ds_read_b128 v[16:19], v56 offset:0
	ds_read_b128 v[20:23], v56 offset:2560
	ds_read_b128 v[24:27], v56 offset:32
	ds_read_b128 v[28:31], v56 offset:2592
	s_waitcnt lgkmcnt(2)
	v_mfma_f32_32x32x16_bf16 v[66:81], v[16:19], v[0:3], v[66:81]
	v_mfma_f32_32x32x16_bf16 v[130:145], v[20:23], v[0:3], v[130:145]
	ds_read_b128 v[0:3], v57 offset:32
	s_waitcnt vmcnt(6)
	ds_write_b128 v58, v[214:217] offset:30720
	ds_write_b128 v58, v[218:221] offset:35840
	v_mfma_f32_32x32x16_bf16 v[82:97], v[16:19], v[4:7], v[82:97]
	v_mfma_f32_32x32x16_bf16 v[146:161], v[20:23], v[4:7], v[146:161]
	ds_read_b128 v[4:7], v57 offset:2592
	ds_write_b128 v58, v[222:225] offset:40960
	ds_write_b128 v58, v[228:231] offset:46080
	v_mfma_f32_32x32x16_bf16 v[98:113], v[16:19], v[8:11], v[98:113]
	v_mfma_f32_32x32x16_bf16 v[162:177], v[20:23], v[8:11], v[162:177]
	ds_read_b128 v[8:11], v57 offset:5152
	ds_write_b128 v58, v[232:235] offset:51200
	ds_write_b128 v58, v[236:239] offset:56320
	v_mfma_f32_32x32x16_bf16 v[114:129], v[16:19], v[12:15], v[114:129]
	v_mfma_f32_32x32x16_bf16 v[178:193], v[20:23], v[12:15], v[178:193]
	ds_read_b128 v[12:15], v57 offset:7712
	s_waitcnt lgkmcnt(9)
	v_mfma_f32_32x32x16_bf16 v[66:81], v[24:27], v[0:3], v[66:81]
	global_load_dwordx4 v[214:217], v[240:241], off offset:2880
	global_load_dwordx4 v[218:221], v[242:243], off offset:2880
	v_mfma_f32_32x32x16_bf16 v[130:145], v[28:31], v[0:3], v[130:145]
	s_waitcnt lgkmcnt(6)
	v_mfma_f32_32x32x16_bf16 v[82:97], v[24:27], v[4:7], v[82:97]
	global_load_dwordx4 v[222:225], v[244:245], off offset:832
	global_load_dwordx4 v[228:231], v[246:247], off offset:832
	v_mfma_f32_32x32x16_bf16 v[146:161], v[28:31], v[4:7], v[146:161]
	s_waitcnt lgkmcnt(3)
	v_mfma_f32_32x32x16_bf16 v[98:113], v[24:27], v[8:11], v[98:113]
	global_load_dwordx4 v[232:235], v[248:249], off offset:832
	global_load_dwordx4 v[236:239], v[250:251], off offset:832
	v_mfma_f32_32x32x16_bf16 v[162:177], v[28:31], v[8:11], v[162:177]
	s_waitcnt lgkmcnt(0)
	v_mfma_f32_32x32x16_bf16 v[114:129], v[24:27], v[12:15], v[114:129]
	v_mfma_f32_32x32x16_bf16 v[178:193], v[28:31], v[12:15], v[178:193]
	s_waitcnt lgkmcnt(0)
	s_barrier
	ds_read_b128 v[0:3], v57 offset:30720
	ds_read_b128 v[4:7], v57 offset:33280
	ds_read_b128 v[8:11], v57 offset:35840
	ds_read_b128 v[12:15], v57 offset:38400
	ds_read_b128 v[16:19], v56 offset:30720
	ds_read_b128 v[20:23], v56 offset:33280
	ds_read_b128 v[24:27], v56 offset:30752
	ds_read_b128 v[28:31], v56 offset:33312
	s_waitcnt lgkmcnt(2)
	v_mfma_f32_32x32x16_bf16 v[66:81], v[16:19], v[0:3], v[66:81]
	v_mfma_f32_32x32x16_bf16 v[130:145], v[20:23], v[0:3], v[130:145]
	ds_read_b128 v[0:3], v57 offset:30752
	s_waitcnt vmcnt(6)
	ds_write_b128 v58, v[32:35] offset:0
	ds_write_b128 v58, v[36:39] offset:5120
	v_mfma_f32_32x32x16_bf16 v[82:97], v[16:19], v[4:7], v[82:97]
	v_mfma_f32_32x32x16_bf16 v[146:161], v[20:23], v[4:7], v[146:161]
	ds_read_b128 v[4:7], v57 offset:33312
	ds_write_b128 v58, v[40:43] offset:10240
	ds_write_b128 v58, v[44:47] offset:15360
	v_mfma_f32_32x32x16_bf16 v[98:113], v[16:19], v[8:11], v[98:113]
	v_mfma_f32_32x32x16_bf16 v[162:177], v[20:23], v[8:11], v[162:177]
	ds_read_b128 v[8:11], v57 offset:35872
	ds_write_b128 v58, v[48:51] offset:20480
	ds_write_b128 v58, v[52:55] offset:25600
	v_mfma_f32_32x32x16_bf16 v[114:129], v[16:19], v[12:15], v[114:129]
	v_mfma_f32_32x32x16_bf16 v[178:193], v[20:23], v[12:15], v[178:193]
	ds_read_b128 v[12:15], v57 offset:38432
	s_waitcnt lgkmcnt(9)
	v_mfma_f32_32x32x16_bf16 v[66:81], v[24:27], v[0:3], v[66:81]
	global_load_dwordx4 v[32:35], v[240:241], off offset:2944
	global_load_dwordx4 v[36:39], v[242:243], off offset:2944
	v_mfma_f32_32x32x16_bf16 v[130:145], v[28:31], v[0:3], v[130:145]
	s_waitcnt lgkmcnt(6)
	v_mfma_f32_32x32x16_bf16 v[82:97], v[24:27], v[4:7], v[82:97]
	global_load_dwordx4 v[40:43], v[244:245], off offset:896
	global_load_dwordx4 v[44:47], v[246:247], off offset:896
	v_mfma_f32_32x32x16_bf16 v[146:161], v[28:31], v[4:7], v[146:161]
	s_waitcnt lgkmcnt(3)
	v_mfma_f32_32x32x16_bf16 v[98:113], v[24:27], v[8:11], v[98:113]
	global_load_dwordx4 v[48:51], v[248:249], off offset:896
	global_load_dwordx4 v[52:55], v[250:251], off offset:896
	v_mfma_f32_32x32x16_bf16 v[162:177], v[28:31], v[8:11], v[162:177]
	s_waitcnt lgkmcnt(0)
	v_mfma_f32_32x32x16_bf16 v[114:129], v[24:27], v[12:15], v[114:129]
	v_mfma_f32_32x32x16_bf16 v[178:193], v[28:31], v[12:15], v[178:193]
	s_waitcnt lgkmcnt(0)
	s_barrier
; #define G_LOAD(S, kt_) do { G_LD1(S##a0, S##b0, 0, kt_); G_LD1(S##a1, S##b1, 1, kt_); G_LD1(S##a2, S##b2, 2, kt_); G_LD1(S##a3, S##b3, 3, kt_); } while (0)
; #define G_STORE(S, buf_) do { G_ST1(S##a0, S##b0, 0, buf_); G_ST1(S##a1, S##b1, 1, buf_); G_ST1(S##a2, S##b2, 2, buf_); G_ST1(S##a3, S##b3, 3, buf_); } while (0)
; template <class AL, class BL>
; DI void gemm_core(AL al, BL bl, int m0, int n0, int K, char* smem, f32x16 (&acc)[2][2]) {
;     ...
;   G_LOAD(x, 0);
;   G_STORE(x, 0);
;   G_LOAD(x, 1);
;   G_LOAD(y, (nk > 2) ? 2 : 1);
;   __syncthreads();
;   for (int kt = 0; kt < nk; kt += 2) {
;     G_TILE(0, x, true, (kt + 3 < nk), kt + 3);
;     __syncthreads();
;     G_TILE(1, y, (kt + 2 < nk), (kt + 4 < nk), kt + 4);
;     __syncthreads();
	ds_read_b128 v[0:3], v57 offset:0
	ds_read_b128 v[4:7], v57 offset:2560
	ds_read_b128 v[8:11], v57 offset:5120
	ds_read_b128 v[12:15], v57 offset:7680
	ds_read_b128 v[16:19], v56 offset:0
	ds_read_b128 v[20:23], v56 offset:2560
	ds_read_b128 v[24:27], v56 offset:32
	ds_read_b128 v[28:31], v56 offset:2592
	s_waitcnt lgkmcnt(2)
	v_mfma_f32_32x32x16_bf16 v[66:81], v[16:19], v[0:3], v[66:81]
	v_mfma_f32_32x32x16_bf16 v[130:145], v[20:23], v[0:3], v[130:145]
	ds_read_b128 v[0:3], v57 offset:32
	s_waitcnt vmcnt(6)
	ds_write_b128 v58, v[214:217] offset:30720
	ds_write_b128 v58, v[218:221] offset:35840
	v_mfma_f32_32x32x16_bf16 v[82:97], v[16:19], v[4:7], v[82:97]
	v_mfma_f32_32x32x16_bf16 v[146:161], v[20:23], v[4:7], v[146:161]
	ds_read_b128 v[4:7], v57 offset:2592
	ds_write_b128 v58, v[222:225] offset:40960
	ds_write_b128 v58, v[228:231] offset:46080
	v_mfma_f32_32x32x16_bf16 v[98:113], v[16:19], v[8:11], v[98:113]
	v_mfma_f32_32x32x16_bf16 v[162:177], v[20:23], v[8:11], v[162:177]
	ds_read_b128 v[8:11], v57 offset:5152
	ds_write_b128 v58, v[232:235] offset:51200
	ds_write_b128 v58, v[236:239] offset:56320
	v_mfma_f32_32x32x16_bf16 v[114:129], v[16:19], v[12:15], v[114:129]
	v_mfma_f32_32x32x16_bf16 v[178:193], v[20:23], v[12:15], v[178:193]
	ds_read_b128 v[12:15], v57 offset:7712
	s_waitcnt lgkmcnt(9)
	v_mfma_f32_32x32x16_bf16 v[66:81], v[24:27], v[0:3], v[66:81]
	global_load_dwordx4 v[214:217], v[240:241], off offset:3008
	global_load_dwordx4 v[218:221], v[242:243], off offset:3008
	v_mfma_f32_32x32x16_bf16 v[130:145], v[28:31], v[0:3], v[130:145]
	s_waitcnt lgkmcnt(6)
	v_mfma_f32_32x32x16_bf16 v[82:97], v[24:27], v[4:7], v[82:97]
	global_load_dwordx4 v[222:225], v[244:245], off offset:960
	global_load_dwordx4 v[228:231], v[246:247], off offset:960
	v_mfma_f32_32x32x16_bf16 v[146:161], v[28:31], v[4:7], v[146:161]
	s_waitcnt lgkmcnt(3)
	v_mfma_f32_32x32x16_bf16 v[98:113], v[24:27], v[8:11], v[98:113]
	global_load_dwordx4 v[232:235], v[248:249], off offset:960
	global_load_dwordx4 v[236:239], v[250:251], off offset:960
	v_mfma_f32_32x32x16_bf16 v[162:177], v[28:31], v[8:11], v[162:177]
	s_waitcnt lgkmcnt(0)
	v_mfma_f32_32x32x16_bf16 v[114:129], v[24:27], v[12:15], v[114:129]
	v_mfma_f32_32x32x16_bf16 v[178:193], v[28:31], v[12:15], v[178:193]
	s_waitcnt lgkmcnt(0)
	s_barrier
	ds_read_b128 v[0:3], v57 offset:30720
	ds_read_b128 v[4:7], v57 offset:33280
	ds_read_b128 v[8:11], v57 offset:35840
	ds_read_b128 v[12:15], v57 offset:38400
	ds_read_b128 v[16:19], v56 offset:30720
	ds_read_b128 v[20:23], v56 offset:33280
	ds_read_b128 v[24:27], v56 offset:30752
	ds_read_b128 v[28:31], v56 offset:33312
	s_waitcnt lgkmcnt(2)
	v_mfma_f32_32x32x16_bf16 v[66:81], v[16:19], v[0:3], v[66:81]
	v_mfma_f32_32x32x16_bf16 v[130:145], v[20:23], v[0:3], v[130:145]
	ds_read_b128 v[0:3], v57 offset:30752
	s_waitcnt vmcnt(6)
	ds_write_b128 v58, v[32:35] offset:0
	ds_write_b128 v58, v[36:39] offset:5120
	v_mfma_f32_32x32x16_bf16 v[82:97], v[16:19], v[4:7], v[82:97]
	v_mfma_f32_32x32x16_bf16 v[146:161], v[20:23], v[4:7], v[146:161]
	ds_read_b128 v[4:7], v57 offset:33312
	ds_write_b128 v58, v[40:43] offset:10240
	ds_write_b128 v58, v[44:47] offset:15360
	v_mfma_f32_32x32x16_bf16 v[98:113], v[16:19], v[8:11], v[98:113]
	v_mfma_f32_32x32x16_bf16 v[162:177], v[20:23], v[8:11], v[162:177]
	ds_read_b128 v[8:11], v57 offset:35872
	ds_write_b128 v58, v[48:51] offset:20480
	ds_write_b128 v58, v[52:55] offset:25600
	v_mfma_f32_32x32x16_bf16 v[114:129], v[16:19], v[12:15], v[114:129]
	v_mfma_f32_32x32x16_bf16 v[178:193], v[20:23], v[12:15], v[178:193]
	ds_read_b128 v[12:15], v57 offset:38432
	s_waitcnt lgkmcnt(9)
	v_mfma_f32_32x32x16_bf16 v[66:81], v[24:27], v[0:3], v[66:81]
	global_load_dwordx4 v[32:35], v[240:241], off offset:3072
	global_load_dwordx4 v[36:39], v[242:243], off offset:3072
	v_mfma_f32_32x32x16_bf16 v[130:145], v[28:31], v[0:3], v[130:145]
	s_waitcnt lgkmcnt(6)
	v_mfma_f32_32x32x16_bf16 v[82:97], v[24:27], v[4:7], v[82:97]
	global_load_dwordx4 v[40:43], v[244:245], off offset:1024
	global_load_dwordx4 v[44:47], v[246:247], off offset:1024
	v_mfma_f32_32x32x16_bf16 v[146:161], v[28:31], v[4:7], v[146:161]
	s_waitcnt lgkmcnt(3)
	v_mfma_f32_32x32x16_bf16 v[98:113], v[24:27], v[8:11], v[98:113]
	global_load_dwordx4 v[48:51], v[248:249], off offset:1024
	global_load_dwordx4 v[52:55], v[250:251], off offset:1024
	v_mfma_f32_32x32x16_bf16 v[162:177], v[28:31], v[8:11], v[162:177]
	s_waitcnt lgkmcnt(0)
	v_mfma_f32_32x32x16_bf16 v[114:129], v[24:27], v[12:15], v[114:129]
	v_mfma_f32_32x32x16_bf16 v[178:193], v[28:31], v[12:15], v[178:193]
	s_waitcnt lgkmcnt(0)
	s_barrier
; #define G_LOAD(S, kt_) do { G_LD1(S##a0, S##b0, 0, kt_); G_LD1(S##a1, S##b1, 1, kt_); G_LD1(S##a2, S##b2, 2, kt_); G_LD1(S##a3, S##b3, 3, kt_); } while (0)
; #define G_STORE(S, buf_) do { G_ST1(S##a0, S##b0, 0, buf_); G_ST1(S##a1, S##b1, 1, buf_); G_ST1(S##a2, S##b2, 2, buf_); G_ST1(S##a3, S##b3, 3, buf_); } while (0)
; template <class AL, class BL>
; DI void gemm_core(AL al, BL bl, int m0, int n0, int K, char* smem, f32x16 (&acc)[2][2]) {
;     ...
;   G_LOAD(x, 0);
;   G_STORE(x, 0);
;   G_LOAD(x, 1);
;   G_LOAD(y, (nk > 2) ? 2 : 1);
;   __syncthreads();
;   for (int kt = 0; kt < nk; kt += 2) {
;     G_TILE(0, x, true, (kt + 3 < nk), kt + 3);
;     __syncthreads();
;     G_TILE(1, y, (kt + 2 < nk), (kt + 4 < nk), kt + 4);
;     __syncthreads();
	ds_read_b128 v[0:3], v57 offset:0
	ds_read_b128 v[4:7], v57 offset:2560
	ds_read_b128 v[8:11], v57 offset:5120
	ds_read_b128 v[12:15], v57 offset:7680
	ds_read_b128 v[16:19], v56 offset:0
	ds_read_b128 v[20:23], v56 offset:2560
	ds_read_b128 v[24:27], v56 offset:32
	ds_read_b128 v[28:31], v56 offset:2592
	s_waitcnt lgkmcnt(2)
	v_mfma_f32_32x32x16_bf16 v[66:81], v[16:19], v[0:3], v[66:81]
	v_mfma_f32_32x32x16_bf16 v[130:145], v[20:23], v[0:3], v[130:145]
	ds_read_b128 v[0:3], v57 offset:32
	s_waitcnt vmcnt(6)
	ds_write_b128 v58, v[214:217] offset:30720
	ds_write_b128 v58, v[218:221] offset:35840
	v_mfma_f32_32x32x16_bf16 v[82:97], v[16:19], v[4:7], v[82:97]
	v_mfma_f32_32x32x16_bf16 v[146:161], v[20:23], v[4:7], v[146:161]
	ds_read_b128 v[4:7], v57 offset:2592
	ds_write_b128 v58, v[222:225] offset:40960
	ds_write_b128 v58, v[228:231] offset:46080
	v_mfma_f32_32x32x16_bf16 v[98:113], v[16:19], v[8:11], v[98:113]
	v_mfma_f32_32x32x16_bf16 v[162:177], v[20:23], v[8:11], v[162:177]
	ds_read_b128 v[8:11], v57 offset:5152
	ds_write_b128 v58, v[232:235] offset:51200
	ds_write_b128 v58, v[236:239] offset:56320
	v_mfma_f32_32x32x16_bf16 v[114:129], v[16:19], v[12:15], v[114:129]
	v_mfma_f32_32x32x16_bf16 v[178:193], v[20:23], v[12:15], v[178:193]
	ds_read_b128 v[12:15], v57 offset:7712
	s_waitcnt lgkmcnt(9)
	v_mfma_f32_32x32x16_bf16 v[66:81], v[24:27], v[0:3], v[66:81]
	global_load_dwordx4 v[214:217], v[240:241], off offset:3136
	global_load_dwordx4 v[218:221], v[242:243], off offset:3136
	v_mfma_f32_32x32x16_bf16 v[130:145], v[28:31], v[0:3], v[130:145]
	s_waitcnt lgkmcnt(6)
	v_mfma_f32_32x32x16_bf16 v[82:97], v[24:27], v[4:7], v[82:97]
	global_load_dwordx4 v[222:225], v[244:245], off offset:1088
	global_load_dwordx4 v[228:231], v[246:247], off offset:1088
	v_mfma_f32_32x32x16_bf16 v[146:161], v[28:31], v[4:7], v[146:161]
	s_waitcnt lgkmcnt(3)
	v_mfma_f32_32x32x16_bf16 v[98:113], v[24:27], v[8:11], v[98:113]
	global_load_dwordx4 v[232:235], v[248:249], off offset:1088
	global_load_dwordx4 v[236:239], v[250:251], off offset:1088
	v_mfma_f32_32x32x16_bf16 v[162:177], v[28:31], v[8:11], v[162:177]
	s_waitcnt lgkmcnt(0)
	v_mfma_f32_32x32x16_bf16 v[114:129], v[24:27], v[12:15], v[114:129]
	v_mfma_f32_32x32x16_bf16 v[178:193], v[28:31], v[12:15], v[178:193]
	s_waitcnt lgkmcnt(0)
	s_barrier
	ds_read_b128 v[0:3], v57 offset:30720
	ds_read_b128 v[4:7], v57 offset:33280
	ds_read_b128 v[8:11], v57 offset:35840
	ds_read_b128 v[12:15], v57 offset:38400
	ds_read_b128 v[16:19], v56 offset:30720
	ds_read_b128 v[20:23], v56 offset:33280
	ds_read_b128 v[24:27], v56 offset:30752
	ds_read_b128 v[28:31], v56 offset:33312
	s_waitcnt lgkmcnt(2)
	v_mfma_f32_32x32x16_bf16 v[66:81], v[16:19], v[0:3], v[66:81]
	v_mfma_f32_32x32x16_bf16 v[130:145], v[20:23], v[0:3], v[130:145]
	ds_read_b128 v[0:3], v57 offset:30752
	s_waitcnt vmcnt(6)
	ds_write_b128 v58, v[32:35] offset:0
	ds_write_b128 v58, v[36:39] offset:5120
	v_mfma_f32_32x32x16_bf16 v[82:97], v[16:19], v[4:7], v[82:97]
	v_mfma_f32_32x32x16_bf16 v[146:161], v[20:23], v[4:7], v[146:161]
	ds_read_b128 v[4:7], v57 offset:33312
	ds_write_b128 v58, v[40:43] offset:10240
	ds_write_b128 v58, v[44:47] offset:15360
	v_mfma_f32_32x32x16_bf16 v[98:113], v[16:19], v[8:11], v[98:113]
	v_mfma_f32_32x32x16_bf16 v[162:177], v[20:23], v[8:11], v[162:177]
	ds_read_b128 v[8:11], v57 offset:35872
	ds_write_b128 v58, v[48:51] offset:20480
	ds_write_b128 v58, v[52:55] offset:25600
	v_mfma_f32_32x32x16_bf16 v[114:129], v[16:19], v[12:15], v[114:129]
	v_mfma_f32_32x32x16_bf16 v[178:193], v[20:23], v[12:15], v[178:193]
	ds_read_b128 v[12:15], v57 offset:38432
	s_waitcnt lgkmcnt(9)
	v_mfma_f32_32x32x16_bf16 v[66:81], v[24:27], v[0:3], v[66:81]
	global_load_dwordx4 v[32:35], v[240:241], off offset:3200
	global_load_dwordx4 v[36:39], v[242:243], off offset:3200
	v_mfma_f32_32x32x16_bf16 v[130:145], v[28:31], v[0:3], v[130:145]
	s_waitcnt lgkmcnt(6)
	v_mfma_f32_32x32x16_bf16 v[82:97], v[24:27], v[4:7], v[82:97]
	global_load_dwordx4 v[40:43], v[244:245], off offset:1152
	global_load_dwordx4 v[44:47], v[246:247], off offset:1152
	v_mfma_f32_32x32x16_bf16 v[146:161], v[28:31], v[4:7], v[146:161]
	s_waitcnt lgkmcnt(3)
	v_mfma_f32_32x32x16_bf16 v[98:113], v[24:27], v[8:11], v[98:113]
	global_load_dwordx4 v[48:51], v[248:249], off offset:1152
	global_load_dwordx4 v[52:55], v[250:251], off offset:1152
	v_mfma_f32_32x32x16_bf16 v[162:177], v[28:31], v[8:11], v[162:177]
	s_waitcnt lgkmcnt(0)
	v_mfma_f32_32x32x16_bf16 v[114:129], v[24:27], v[12:15], v[114:129]
	v_mfma_f32_32x32x16_bf16 v[178:193], v[28:31], v[12:15], v[178:193]
	s_waitcnt lgkmcnt(0)
	s_barrier
; #define G_LOAD(S, kt_) do { G_LD1(S##a0, S##b0, 0, kt_); G_LD1(S##a1, S##b1, 1, kt_); G_LD1(S##a2, S##b2, 2, kt_); G_LD1(S##a3, S##b3, 3, kt_); } while (0)
; #define G_STORE(S, buf_) do { G_ST1(S##a0, S##b0, 0, buf_); G_ST1(S##a1, S##b1, 1, buf_); G_ST1(S##a2, S##b2, 2, buf_); G_ST1(S##a3, S##b3, 3, buf_); } while (0)
; template <class AL, class BL>
; DI void gemm_core(AL al, BL bl, int m0, int n0, int K, char* smem, f32x16 (&acc)[2][2]) {
;     ...
;   G_LOAD(x, 0);
;   G_STORE(x, 0);
;   G_LOAD(x, 1);
;   G_LOAD(y, (nk > 2) ? 2 : 1);
;   __syncthreads();
;   for (int kt = 0; kt < nk; kt += 2) {
;     G_TILE(0, x, true, (kt + 3 < nk), kt + 3);
;     __syncthreads();
;     G_TILE(1, y, (kt + 2 < nk), (kt + 4 < nk), kt + 4);
;     __syncthreads();
	ds_read_b128 v[0:3], v57 offset:0
	ds_read_b128 v[4:7], v57 offset:2560
	ds_read_b128 v[8:11], v57 offset:5120
	ds_read_b128 v[12:15], v57 offset:7680
	ds_read_b128 v[16:19], v56 offset:0
	ds_read_b128 v[20:23], v56 offset:2560
	ds_read_b128 v[24:27], v56 offset:32
	ds_read_b128 v[28:31], v56 offset:2592
	s_waitcnt lgkmcnt(2)
	v_mfma_f32_32x32x16_bf16 v[66:81], v[16:19], v[0:3], v[66:81]
	v_mfma_f32_32x32x16_bf16 v[130:145], v[20:23], v[0:3], v[130:145]
	ds_read_b128 v[0:3], v57 offset:32
	s_waitcnt vmcnt(6)
	ds_write_b128 v58, v[214:217] offset:30720
	ds_write_b128 v58, v[218:221] offset:35840
	v_mfma_f32_32x32x16_bf16 v[82:97], v[16:19], v[4:7], v[82:97]
	v_mfma_f32_32x32x16_bf16 v[146:161], v[20:23], v[4:7], v[146:161]
	ds_read_b128 v[4:7], v57 offset:2592
	ds_write_b128 v58, v[222:225] offset:40960
	ds_write_b128 v58, v[228:231] offset:46080
	v_mfma_f32_32x32x16_bf16 v[98:113], v[16:19], v[8:11], v[98:113]
	v_mfma_f32_32x32x16_bf16 v[162:177], v[20:23], v[8:11], v[162:177]
	ds_read_b128 v[8:11], v57 offset:5152
	ds_write_b128 v58, v[232:235] offset:51200
	ds_write_b128 v58, v[236:239] offset:56320
	v_mfma_f32_32x32x16_bf16 v[114:129], v[16:19], v[12:15], v[114:129]
	v_mfma_f32_32x32x16_bf16 v[178:193], v[20:23], v[12:15], v[178:193]
	ds_read_b128 v[12:15], v57 offset:7712
	s_waitcnt lgkmcnt(9)
	v_mfma_f32_32x32x16_bf16 v[66:81], v[24:27], v[0:3], v[66:81]
	global_load_dwordx4 v[214:217], v[240:241], off offset:3264
	global_load_dwordx4 v[218:221], v[242:243], off offset:3264
	v_mfma_f32_32x32x16_bf16 v[130:145], v[28:31], v[0:3], v[130:145]
	s_waitcnt lgkmcnt(6)
	v_mfma_f32_32x32x16_bf16 v[82:97], v[24:27], v[4:7], v[82:97]
	global_load_dwordx4 v[222:225], v[244:245], off offset:1216
	global_load_dwordx4 v[228:231], v[246:247], off offset:1216
	v_mfma_f32_32x32x16_bf16 v[146:161], v[28:31], v[4:7], v[146:161]
	s_waitcnt lgkmcnt(3)
	v_mfma_f32_32x32x16_bf16 v[98:113], v[24:27], v[8:11], v[98:113]
	global_load_dwordx4 v[232:235], v[248:249], off offset:1216
	global_load_dwordx4 v[236:239], v[250:251], off offset:1216
	v_mfma_f32_32x32x16_bf16 v[162:177], v[28:31], v[8:11], v[162:177]
	s_waitcnt lgkmcnt(0)
	v_mfma_f32_32x32x16_bf16 v[114:129], v[24:27], v[12:15], v[114:129]
	v_mfma_f32_32x32x16_bf16 v[178:193], v[28:31], v[12:15], v[178:193]
	s_waitcnt lgkmcnt(0)
	s_barrier
	ds_read_b128 v[0:3], v57 offset:30720
	ds_read_b128 v[4:7], v57 offset:33280
	ds_read_b128 v[8:11], v57 offset:35840
	ds_read_b128 v[12:15], v57 offset:38400
	ds_read_b128 v[16:19], v56 offset:30720
	ds_read_b128 v[20:23], v56 offset:33280
	ds_read_b128 v[24:27], v56 offset:30752
	ds_read_b128 v[28:31], v56 offset:33312
	s_waitcnt lgkmcnt(2)
	v_mfma_f32_32x32x16_bf16 v[66:81], v[16:19], v[0:3], v[66:81]
	v_mfma_f32_32x32x16_bf16 v[130:145], v[20:23], v[0:3], v[130:145]
	ds_read_b128 v[0:3], v57 offset:30752
	s_waitcnt vmcnt(6)
	ds_write_b128 v58, v[32:35] offset:0
	ds_write_b128 v58, v[36:39] offset:5120
	v_mfma_f32_32x32x16_bf16 v[82:97], v[16:19], v[4:7], v[82:97]
	v_mfma_f32_32x32x16_bf16 v[146:161], v[20:23], v[4:7], v[146:161]
	ds_read_b128 v[4:7], v57 offset:33312
	ds_write_b128 v58, v[40:43] offset:10240
	ds_write_b128 v58, v[44:47] offset:15360
	v_mfma_f32_32x32x16_bf16 v[98:113], v[16:19], v[8:11], v[98:113]
	v_mfma_f32_32x32x16_bf16 v[162:177], v[20:23], v[8:11], v[162:177]
	ds_read_b128 v[8:11], v57 offset:35872
	ds_write_b128 v58, v[48:51] offset:20480
	ds_write_b128 v58, v[52:55] offset:25600
	v_mfma_f32_32x32x16_bf16 v[114:129], v[16:19], v[12:15], v[114:129]
	v_mfma_f32_32x32x16_bf16 v[178:193], v[20:23], v[12:15], v[178:193]
	ds_read_b128 v[12:15], v57 offset:38432
	s_waitcnt lgkmcnt(9)
	v_mfma_f32_32x32x16_bf16 v[66:81], v[24:27], v[0:3], v[66:81]
	global_load_dwordx4 v[32:35], v[240:241], off offset:3328
	global_load_dwordx4 v[36:39], v[242:243], off offset:3328
	v_mfma_f32_32x32x16_bf16 v[130:145], v[28:31], v[0:3], v[130:145]
	s_waitcnt lgkmcnt(6)
	v_mfma_f32_32x32x16_bf16 v[82:97], v[24:27], v[4:7], v[82:97]
	global_load_dwordx4 v[40:43], v[244:245], off offset:1280
	global_load_dwordx4 v[44:47], v[246:247], off offset:1280
	v_mfma_f32_32x32x16_bf16 v[146:161], v[28:31], v[4:7], v[146:161]
	s_waitcnt lgkmcnt(3)
	v_mfma_f32_32x32x16_bf16 v[98:113], v[24:27], v[8:11], v[98:113]
	global_load_dwordx4 v[48:51], v[248:249], off offset:1280
	global_load_dwordx4 v[52:55], v[250:251], off offset:1280
	v_mfma_f32_32x32x16_bf16 v[162:177], v[28:31], v[8:11], v[162:177]
	s_waitcnt lgkmcnt(0)
	v_mfma_f32_32x32x16_bf16 v[114:129], v[24:27], v[12:15], v[114:129]
	v_mfma_f32_32x32x16_bf16 v[178:193], v[28:31], v[12:15], v[178:193]
	s_waitcnt lgkmcnt(0)
	s_barrier
; #define G_LOAD(S, kt_) do { G_LD1(S##a0, S##b0, 0, kt_); G_LD1(S##a1, S##b1, 1, kt_); G_LD1(S##a2, S##b2, 2, kt_); G_LD1(S##a3, S##b3, 3, kt_); } while (0)
; #define G_STORE(S, buf_) do { G_ST1(S##a0, S##b0, 0, buf_); G_ST1(S##a1, S##b1, 1, buf_); G_ST1(S##a2, S##b2, 2, buf_); G_ST1(S##a3, S##b3, 3, buf_); } while (0)
; template <class AL, class BL>
; DI void gemm_core(AL al, BL bl, int m0, int n0, int K, char* smem, f32x16 (&acc)[2][2]) {
;     ...
;   G_LOAD(x, 0);
;   G_STORE(x, 0);
;   G_LOAD(x, 1);
;   G_LOAD(y, (nk > 2) ? 2 : 1);
;   __syncthreads();
;   for (int kt = 0; kt < nk; kt += 2) {
;     G_TILE(0, x, true, (kt + 3 < nk), kt + 3);
;     __syncthreads();
;     G_TILE(1, y, (kt + 2 < nk), (kt + 4 < nk), kt + 4);
;     __syncthreads();
	ds_read_b128 v[0:3], v57 offset:0
	ds_read_b128 v[4:7], v57 offset:2560
	ds_read_b128 v[8:11], v57 offset:5120
	ds_read_b128 v[12:15], v57 offset:7680
	ds_read_b128 v[16:19], v56 offset:0
	ds_read_b128 v[20:23], v56 offset:2560
	ds_read_b128 v[24:27], v56 offset:32
	ds_read_b128 v[28:31], v56 offset:2592
	s_waitcnt lgkmcnt(2)
	v_mfma_f32_32x32x16_bf16 v[66:81], v[16:19], v[0:3], v[66:81]
	v_mfma_f32_32x32x16_bf16 v[130:145], v[20:23], v[0:3], v[130:145]
	ds_read_b128 v[0:3], v57 offset:32
	s_waitcnt vmcnt(6)
	ds_write_b128 v58, v[214:217] offset:30720
	ds_write_b128 v58, v[218:221] offset:35840
	v_mfma_f32_32x32x16_bf16 v[82:97], v[16:19], v[4:7], v[82:97]
	v_mfma_f32_32x32x16_bf16 v[146:161], v[20:23], v[4:7], v[146:161]
	ds_read_b128 v[4:7], v57 offset:2592
	ds_write_b128 v58, v[222:225] offset:40960
	ds_write_b128 v58, v[228:231] offset:46080
	v_mfma_f32_32x32x16_bf16 v[98:113], v[16:19], v[8:11], v[98:113]
	v_mfma_f32_32x32x16_bf16 v[162:177], v[20:23], v[8:11], v[162:177]
	ds_read_b128 v[8:11], v57 offset:5152
	ds_write_b128 v58, v[232:235] offset:51200
	ds_write_b128 v58, v[236:239] offset:56320
	v_mfma_f32_32x32x16_bf16 v[114:129], v[16:19], v[12:15], v[114:129]
	v_mfma_f32_32x32x16_bf16 v[178:193], v[20:23], v[12:15], v[178:193]
	ds_read_b128 v[12:15], v57 offset:7712
	s_waitcnt lgkmcnt(9)
	v_mfma_f32_32x32x16_bf16 v[66:81], v[24:27], v[0:3], v[66:81]
	global_load_dwordx4 v[214:217], v[240:241], off offset:3392
	global_load_dwordx4 v[218:221], v[242:243], off offset:3392
	v_mfma_f32_32x32x16_bf16 v[130:145], v[28:31], v[0:3], v[130:145]
	s_waitcnt lgkmcnt(6)
	v_mfma_f32_32x32x16_bf16 v[82:97], v[24:27], v[4:7], v[82:97]
	global_load_dwordx4 v[222:225], v[244:245], off offset:1344
	global_load_dwordx4 v[228:231], v[246:247], off offset:1344
	v_mfma_f32_32x32x16_bf16 v[146:161], v[28:31], v[4:7], v[146:161]
	s_waitcnt lgkmcnt(3)
	v_mfma_f32_32x32x16_bf16 v[98:113], v[24:27], v[8:11], v[98:113]
	global_load_dwordx4 v[232:235], v[248:249], off offset:1344
	global_load_dwordx4 v[236:239], v[250:251], off offset:1344
	v_mfma_f32_32x32x16_bf16 v[162:177], v[28:31], v[8:11], v[162:177]
	s_waitcnt lgkmcnt(0)
	v_mfma_f32_32x32x16_bf16 v[114:129], v[24:27], v[12:15], v[114:129]
	v_mfma_f32_32x32x16_bf16 v[178:193], v[28:31], v[12:15], v[178:193]
	s_waitcnt lgkmcnt(0)
	s_barrier
	ds_read_b128 v[0:3], v57 offset:30720
	ds_read_b128 v[4:7], v57 offset:33280
	ds_read_b128 v[8:11], v57 offset:35840
	ds_read_b128 v[12:15], v57 offset:38400
	ds_read_b128 v[16:19], v56 offset:30720
	ds_read_b128 v[20:23], v56 offset:33280
	ds_read_b128 v[24:27], v56 offset:30752
	ds_read_b128 v[28:31], v56 offset:33312
	s_waitcnt lgkmcnt(2)
	v_mfma_f32_32x32x16_bf16 v[66:81], v[16:19], v[0:3], v[66:81]
	v_mfma_f32_32x32x16_bf16 v[130:145], v[20:23], v[0:3], v[130:145]
	ds_read_b128 v[0:3], v57 offset:30752
	s_waitcnt vmcnt(6)
	ds_write_b128 v58, v[32:35] offset:0
	ds_write_b128 v58, v[36:39] offset:5120
	v_mfma_f32_32x32x16_bf16 v[82:97], v[16:19], v[4:7], v[82:97]
	v_mfma_f32_32x32x16_bf16 v[146:161], v[20:23], v[4:7], v[146:161]
	ds_read_b128 v[4:7], v57 offset:33312
	ds_write_b128 v58, v[40:43] offset:10240
	ds_write_b128 v58, v[44:47] offset:15360
	v_mfma_f32_32x32x16_bf16 v[98:113], v[16:19], v[8:11], v[98:113]
	v_mfma_f32_32x32x16_bf16 v[162:177], v[20:23], v[8:11], v[162:177]
	ds_read_b128 v[8:11], v57 offset:35872
	ds_write_b128 v58, v[48:51] offset:20480
	ds_write_b128 v58, v[52:55] offset:25600
	v_mfma_f32_32x32x16_bf16 v[114:129], v[16:19], v[12:15], v[114:129]
	v_mfma_f32_32x32x16_bf16 v[178:193], v[20:23], v[12:15], v[178:193]
	ds_read_b128 v[12:15], v57 offset:38432
	s_waitcnt lgkmcnt(9)
	v_mfma_f32_32x32x16_bf16 v[66:81], v[24:27], v[0:3], v[66:81]
	global_load_dwordx4 v[32:35], v[240:241], off offset:3456
	global_load_dwordx4 v[36:39], v[242:243], off offset:3456
	v_mfma_f32_32x32x16_bf16 v[130:145], v[28:31], v[0:3], v[130:145]
	s_waitcnt lgkmcnt(6)
	v_mfma_f32_32x32x16_bf16 v[82:97], v[24:27], v[4:7], v[82:97]
	global_load_dwordx4 v[40:43], v[244:245], off offset:1408
	global_load_dwordx4 v[44:47], v[246:247], off offset:1408
	v_mfma_f32_32x32x16_bf16 v[146:161], v[28:31], v[4:7], v[146:161]
	s_waitcnt lgkmcnt(3)
	v_mfma_f32_32x32x16_bf16 v[98:113], v[24:27], v[8:11], v[98:113]
	global_load_dwordx4 v[48:51], v[248:249], off offset:1408
	global_load_dwordx4 v[52:55], v[250:251], off offset:1408
	v_mfma_f32_32x32x16_bf16 v[162:177], v[28:31], v[8:11], v[162:177]
	s_waitcnt lgkmcnt(0)
	v_mfma_f32_32x32x16_bf16 v[114:129], v[24:27], v[12:15], v[114:129]
	v_mfma_f32_32x32x16_bf16 v[178:193], v[28:31], v[12:15], v[178:193]
	s_waitcnt lgkmcnt(0)
	s_barrier
; #define G_LOAD(S, kt_) do { G_LD1(S##a0, S##b0, 0, kt_); G_LD1(S##a1, S##b1, 1, kt_); G_LD1(S##a2, S##b2, 2, kt_); G_LD1(S##a3, S##b3, 3, kt_); } while (0)
; #define G_STORE(S, buf_) do { G_ST1(S##a0, S##b0, 0, buf_); G_ST1(S##a1, S##b1, 1, buf_); G_ST1(S##a2, S##b2, 2, buf_); G_ST1(S##a3, S##b3, 3, buf_); } while (0)
; template <class AL, class BL>
; DI void gemm_core(AL al, BL bl, int m0, int n0, int K, char* smem, f32x16 (&acc)[2][2]) {
;     ...
;   G_LOAD(x, 0);
;   G_STORE(x, 0);
;   G_LOAD(x, 1);
;   G_LOAD(y, (nk > 2) ? 2 : 1);
;   __syncthreads();
;   for (int kt = 0; kt < nk; kt += 2) {
;     G_TILE(0, x, true, (kt + 3 < nk), kt + 3);
;     __syncthreads();
;     G_TILE(1, y, (kt + 2 < nk), (kt + 4 < nk), kt + 4);
;     __syncthreads();
	ds_read_b128 v[0:3], v57 offset:0
	ds_read_b128 v[4:7], v57 offset:2560
	ds_read_b128 v[8:11], v57 offset:5120
	ds_read_b128 v[12:15], v57 offset:7680
	ds_read_b128 v[16:19], v56 offset:0
	ds_read_b128 v[20:23], v56 offset:2560
	ds_read_b128 v[24:27], v56 offset:32
	ds_read_b128 v[28:31], v56 offset:2592
	s_waitcnt lgkmcnt(2)
	v_mfma_f32_32x32x16_bf16 v[66:81], v[16:19], v[0:3], v[66:81]
	v_mfma_f32_32x32x16_bf16 v[130:145], v[20:23], v[0:3], v[130:145]
	ds_read_b128 v[0:3], v57 offset:32
	s_waitcnt vmcnt(6)
	ds_write_b128 v58, v[214:217] offset:30720
	ds_write_b128 v58, v[218:221] offset:35840
	v_mfma_f32_32x32x16_bf16 v[82:97], v[16:19], v[4:7], v[82:97]
	v_mfma_f32_32x32x16_bf16 v[146:161], v[20:23], v[4:7], v[146:161]
	ds_read_b128 v[4:7], v57 offset:2592
	ds_write_b128 v58, v[222:225] offset:40960
	ds_write_b128 v58, v[228:231] offset:46080
	v_mfma_f32_32x32x16_bf16 v[98:113], v[16:19], v[8:11], v[98:113]
	v_mfma_f32_32x32x16_bf16 v[162:177], v[20:23], v[8:11], v[162:177]
	ds_read_b128 v[8:11], v57 offset:5152
	ds_write_b128 v58, v[232:235] offset:51200
	ds_write_b128 v58, v[236:239] offset:56320
	v_mfma_f32_32x32x16_bf16 v[114:129], v[16:19], v[12:15], v[114:129]
	v_mfma_f32_32x32x16_bf16 v[178:193], v[20:23], v[12:15], v[178:193]
	ds_read_b128 v[12:15], v57 offset:7712
	s_waitcnt lgkmcnt(9)
	v_mfma_f32_32x32x16_bf16 v[66:81], v[24:27], v[0:3], v[66:81]
	global_load_dwordx4 v[214:217], v[240:241], off offset:3520
	global_load_dwordx4 v[218:221], v[242:243], off offset:3520
	v_mfma_f32_32x32x16_bf16 v[130:145], v[28:31], v[0:3], v[130:145]
	s_waitcnt lgkmcnt(6)
	v_mfma_f32_32x32x16_bf16 v[82:97], v[24:27], v[4:7], v[82:97]
	global_load_dwordx4 v[222:225], v[244:245], off offset:1472
	global_load_dwordx4 v[228:231], v[246:247], off offset:1472
	v_mfma_f32_32x32x16_bf16 v[146:161], v[28:31], v[4:7], v[146:161]
	s_waitcnt lgkmcnt(3)
	v_mfma_f32_32x32x16_bf16 v[98:113], v[24:27], v[8:11], v[98:113]
	global_load_dwordx4 v[232:235], v[248:249], off offset:1472
	global_load_dwordx4 v[236:239], v[250:251], off offset:1472
	v_mfma_f32_32x32x16_bf16 v[162:177], v[28:31], v[8:11], v[162:177]
	s_waitcnt lgkmcnt(0)
	v_mfma_f32_32x32x16_bf16 v[114:129], v[24:27], v[12:15], v[114:129]
	v_mfma_f32_32x32x16_bf16 v[178:193], v[28:31], v[12:15], v[178:193]
	s_waitcnt lgkmcnt(0)
	s_barrier
	ds_read_b128 v[0:3], v57 offset:30720
	ds_read_b128 v[4:7], v57 offset:33280
	ds_read_b128 v[8:11], v57 offset:35840
	ds_read_b128 v[12:15], v57 offset:38400
	ds_read_b128 v[16:19], v56 offset:30720
	ds_read_b128 v[20:23], v56 offset:33280
	ds_read_b128 v[24:27], v56 offset:30752
	ds_read_b128 v[28:31], v56 offset:33312
	s_waitcnt lgkmcnt(2)
	v_mfma_f32_32x32x16_bf16 v[66:81], v[16:19], v[0:3], v[66:81]
	v_mfma_f32_32x32x16_bf16 v[130:145], v[20:23], v[0:3], v[130:145]
	ds_read_b128 v[0:3], v57 offset:30752
	s_waitcnt vmcnt(6)
	ds_write_b128 v58, v[32:35] offset:0
	ds_write_b128 v58, v[36:39] offset:5120
	v_mfma_f32_32x32x16_bf16 v[82:97], v[16:19], v[4:7], v[82:97]
	v_mfma_f32_32x32x16_bf16 v[146:161], v[20:23], v[4:7], v[146:161]
	ds_read_b128 v[4:7], v57 offset:33312
	ds_write_b128 v58, v[40:43] offset:10240
	ds_write_b128 v58, v[44:47] offset:15360
	v_mfma_f32_32x32x16_bf16 v[98:113], v[16:19], v[8:11], v[98:113]
	v_mfma_f32_32x32x16_bf16 v[162:177], v[20:23], v[8:11], v[162:177]
	ds_read_b128 v[8:11], v57 offset:35872
	ds_write_b128 v58, v[48:51] offset:20480
	ds_write_b128 v58, v[52:55] offset:25600
	v_mfma_f32_32x32x16_bf16 v[114:129], v[16:19], v[12:15], v[114:129]
	v_mfma_f32_32x32x16_bf16 v[178:193], v[20:23], v[12:15], v[178:193]
	ds_read_b128 v[12:15], v57 offset:38432
	s_waitcnt lgkmcnt(9)
	v_mfma_f32_32x32x16_bf16 v[66:81], v[24:27], v[0:3], v[66:81]
	global_load_dwordx4 v[32:35], v[240:241], off offset:3584
	global_load_dwordx4 v[36:39], v[242:243], off offset:3584
	v_mfma_f32_32x32x16_bf16 v[130:145], v[28:31], v[0:3], v[130:145]
	s_waitcnt lgkmcnt(6)
	v_mfma_f32_32x32x16_bf16 v[82:97], v[24:27], v[4:7], v[82:97]
	global_load_dwordx4 v[40:43], v[244:245], off offset:1536
	global_load_dwordx4 v[44:47], v[246:247], off offset:1536
	v_mfma_f32_32x32x16_bf16 v[146:161], v[28:31], v[4:7], v[146:161]
	s_waitcnt lgkmcnt(3)
	v_mfma_f32_32x32x16_bf16 v[98:113], v[24:27], v[8:11], v[98:113]
	global_load_dwordx4 v[48:51], v[248:249], off offset:1536
	global_load_dwordx4 v[52:55], v[250:251], off offset:1536
	v_mfma_f32_32x32x16_bf16 v[162:177], v[28:31], v[8:11], v[162:177]
	s_waitcnt lgkmcnt(0)
	v_mfma_f32_32x32x16_bf16 v[114:129], v[24:27], v[12:15], v[114:129]
	v_mfma_f32_32x32x16_bf16 v[178:193], v[28:31], v[12:15], v[178:193]
	s_waitcnt lgkmcnt(0)
	s_barrier
; #define G_LOAD(S, kt_) do { G_LD1(S##a0, S##b0, 0, kt_); G_LD1(S##a1, S##b1, 1, kt_); G_LD1(S##a2, S##b2, 2, kt_); G_LD1(S##a3, S##b3, 3, kt_); } while (0)
; #define G_STORE(S, buf_) do { G_ST1(S##a0, S##b0, 0, buf_); G_ST1(S##a1, S##b1, 1, buf_); G_ST1(S##a2, S##b2, 2, buf_); G_ST1(S##a3, S##b3, 3, buf_); } while (0)
; template <class AL, class BL>
; DI void gemm_core(AL al, BL bl, int m0, int n0, int K, char* smem, f32x16 (&acc)[2][2]) {
;     ...
;   G_LOAD(x, 0);
;   G_STORE(x, 0);
;   G_LOAD(x, 1);
;   G_LOAD(y, (nk > 2) ? 2 : 1);
;   __syncthreads();
;   for (int kt = 0; kt < nk; kt += 2) {
;     G_TILE(0, x, true, (kt + 3 < nk), kt + 3);
;     __syncthreads();
;     G_TILE(1, y, (kt + 2 < nk), (kt + 4 < nk), kt + 4);
;     __syncthreads();
	ds_read_b128 v[0:3], v57 offset:0
	ds_read_b128 v[4:7], v57 offset:2560
	ds_read_b128 v[8:11], v57 offset:5120
	ds_read_b128 v[12:15], v57 offset:7680
	ds_read_b128 v[16:19], v56 offset:0
	ds_read_b128 v[20:23], v56 offset:2560
	ds_read_b128 v[24:27], v56 offset:32
	ds_read_b128 v[28:31], v56 offset:2592
	s_waitcnt lgkmcnt(2)
	v_mfma_f32_32x32x16_bf16 v[66:81], v[16:19], v[0:3], v[66:81]
	v_mfma_f32_32x32x16_bf16 v[130:145], v[20:23], v[0:3], v[130:145]
	ds_read_b128 v[0:3], v57 offset:32
	s_waitcnt vmcnt(6)
	ds_write_b128 v58, v[214:217] offset:30720
	ds_write_b128 v58, v[218:221] offset:35840
	v_mfma_f32_32x32x16_bf16 v[82:97], v[16:19], v[4:7], v[82:97]
	v_mfma_f32_32x32x16_bf16 v[146:161], v[20:23], v[4:7], v[146:161]
	ds_read_b128 v[4:7], v57 offset:2592
	ds_write_b128 v58, v[222:225] offset:40960
	ds_write_b128 v58, v[228:231] offset:46080
	v_mfma_f32_32x32x16_bf16 v[98:113], v[16:19], v[8:11], v[98:113]
	v_mfma_f32_32x32x16_bf16 v[162:177], v[20:23], v[8:11], v[162:177]
	ds_read_b128 v[8:11], v57 offset:5152
	ds_write_b128 v58, v[232:235] offset:51200
	ds_write_b128 v58, v[236:239] offset:56320
	v_mfma_f32_32x32x16_bf16 v[114:129], v[16:19], v[12:15], v[114:129]
	v_mfma_f32_32x32x16_bf16 v[178:193], v[20:23], v[12:15], v[178:193]
	ds_read_b128 v[12:15], v57 offset:7712
	s_waitcnt lgkmcnt(9)
	v_mfma_f32_32x32x16_bf16 v[66:81], v[24:27], v[0:3], v[66:81]
	global_load_dwordx4 v[214:217], v[240:241], off offset:3648
	global_load_dwordx4 v[218:221], v[242:243], off offset:3648
	v_mfma_f32_32x32x16_bf16 v[130:145], v[28:31], v[0:3], v[130:145]
	s_waitcnt lgkmcnt(6)
	v_mfma_f32_32x32x16_bf16 v[82:97], v[24:27], v[4:7], v[82:97]
	global_load_dwordx4 v[222:225], v[244:245], off offset:1600
	global_load_dwordx4 v[228:231], v[246:247], off offset:1600
	v_mfma_f32_32x32x16_bf16 v[146:161], v[28:31], v[4:7], v[146:161]
	s_waitcnt lgkmcnt(3)
	v_mfma_f32_32x32x16_bf16 v[98:113], v[24:27], v[8:11], v[98:113]
	global_load_dwordx4 v[232:235], v[248:249], off offset:1600
	global_load_dwordx4 v[236:239], v[250:251], off offset:1600
	v_mfma_f32_32x32x16_bf16 v[162:177], v[28:31], v[8:11], v[162:177]
	s_waitcnt lgkmcnt(0)
	v_mfma_f32_32x32x16_bf16 v[114:129], v[24:27], v[12:15], v[114:129]
	v_mfma_f32_32x32x16_bf16 v[178:193], v[28:31], v[12:15], v[178:193]
	s_waitcnt lgkmcnt(0)
	s_barrier
	ds_read_b128 v[0:3], v57 offset:30720
	ds_read_b128 v[4:7], v57 offset:33280
	ds_read_b128 v[8:11], v57 offset:35840
	ds_read_b128 v[12:15], v57 offset:38400
	ds_read_b128 v[16:19], v56 offset:30720
	ds_read_b128 v[20:23], v56 offset:33280
	ds_read_b128 v[24:27], v56 offset:30752
	ds_read_b128 v[28:31], v56 offset:33312
	s_waitcnt lgkmcnt(2)
	v_mfma_f32_32x32x16_bf16 v[66:81], v[16:19], v[0:3], v[66:81]
	v_mfma_f32_32x32x16_bf16 v[130:145], v[20:23], v[0:3], v[130:145]
	ds_read_b128 v[0:3], v57 offset:30752
	s_waitcnt vmcnt(6)
	ds_write_b128 v58, v[32:35] offset:0
	ds_write_b128 v58, v[36:39] offset:5120
	v_mfma_f32_32x32x16_bf16 v[82:97], v[16:19], v[4:7], v[82:97]
	v_mfma_f32_32x32x16_bf16 v[146:161], v[20:23], v[4:7], v[146:161]
	ds_read_b128 v[4:7], v57 offset:33312
	ds_write_b128 v58, v[40:43] offset:10240
	ds_write_b128 v58, v[44:47] offset:15360
	v_mfma_f32_32x32x16_bf16 v[98:113], v[16:19], v[8:11], v[98:113]
	v_mfma_f32_32x32x16_bf16 v[162:177], v[20:23], v[8:11], v[162:177]
	ds_read_b128 v[8:11], v57 offset:35872
	ds_write_b128 v58, v[48:51] offset:20480
	ds_write_b128 v58, v[52:55] offset:25600
	v_mfma_f32_32x32x16_bf16 v[114:129], v[16:19], v[12:15], v[114:129]
	v_mfma_f32_32x32x16_bf16 v[178:193], v[20:23], v[12:15], v[178:193]
	ds_read_b128 v[12:15], v57 offset:38432
	s_waitcnt lgkmcnt(9)
	v_mfma_f32_32x32x16_bf16 v[66:81], v[24:27], v[0:3], v[66:81]
	global_load_dwordx4 v[32:35], v[240:241], off offset:3712
	global_load_dwordx4 v[36:39], v[242:243], off offset:3712
	v_mfma_f32_32x32x16_bf16 v[130:145], v[28:31], v[0:3], v[130:145]
	s_waitcnt lgkmcnt(6)
	v_mfma_f32_32x32x16_bf16 v[82:97], v[24:27], v[4:7], v[82:97]
	global_load_dwordx4 v[40:43], v[244:245], off offset:1664
	global_load_dwordx4 v[44:47], v[246:247], off offset:1664
	v_mfma_f32_32x32x16_bf16 v[146:161], v[28:31], v[4:7], v[146:161]
	s_waitcnt lgkmcnt(3)
	v_mfma_f32_32x32x16_bf16 v[98:113], v[24:27], v[8:11], v[98:113]
	global_load_dwordx4 v[48:51], v[248:249], off offset:1664
	global_load_dwordx4 v[52:55], v[250:251], off offset:1664
	v_mfma_f32_32x32x16_bf16 v[162:177], v[28:31], v[8:11], v[162:177]
	s_waitcnt lgkmcnt(0)
	v_mfma_f32_32x32x16_bf16 v[114:129], v[24:27], v[12:15], v[114:129]
	v_mfma_f32_32x32x16_bf16 v[178:193], v[28:31], v[12:15], v[178:193]
	s_waitcnt lgkmcnt(0)
	s_barrier
; #define G_LOAD(S, kt_) do { G_LD1(S##a0, S##b0, 0, kt_); G_LD1(S##a1, S##b1, 1, kt_); G_LD1(S##a2, S##b2, 2, kt_); G_LD1(S##a3, S##b3, 3, kt_); } while (0)
; #define G_STORE(S, buf_) do { G_ST1(S##a0, S##b0, 0, buf_); G_ST1(S##a1, S##b1, 1, buf_); G_ST1(S##a2, S##b2, 2, buf_); G_ST1(S##a3, S##b3, 3, buf_); } while (0)
; template <class AL, class BL>
; DI void gemm_core(AL al, BL bl, int m0, int n0, int K, char* smem, f32x16 (&acc)[2][2]) {
;     ...
;   G_LOAD(x, 0);
;   G_STORE(x, 0);
;   G_LOAD(x, 1);
;   G_LOAD(y, (nk > 2) ? 2 : 1);
;   __syncthreads();
;   for (int kt = 0; kt < nk; kt += 2) {
;     G_TILE(0, x, true, (kt + 3 < nk), kt + 3);
;     __syncthreads();
;     G_TILE(1, y, (kt + 2 < nk), (kt + 4 < nk), kt + 4);
;     __syncthreads();
	ds_read_b128 v[0:3], v57 offset:0
	ds_read_b128 v[4:7], v57 offset:2560
	ds_read_b128 v[8:11], v57 offset:5120
	ds_read_b128 v[12:15], v57 offset:7680
	ds_read_b128 v[16:19], v56 offset:0
	ds_read_b128 v[20:23], v56 offset:2560
	ds_read_b128 v[24:27], v56 offset:32
	ds_read_b128 v[28:31], v56 offset:2592
	s_waitcnt lgkmcnt(2)
	v_mfma_f32_32x32x16_bf16 v[66:81], v[16:19], v[0:3], v[66:81]
	v_mfma_f32_32x32x16_bf16 v[130:145], v[20:23], v[0:3], v[130:145]
	ds_read_b128 v[0:3], v57 offset:32
	s_waitcnt vmcnt(6)
	ds_write_b128 v58, v[214:217] offset:30720
	ds_write_b128 v58, v[218:221] offset:35840
	v_mfma_f32_32x32x16_bf16 v[82:97], v[16:19], v[4:7], v[82:97]
	v_mfma_f32_32x32x16_bf16 v[146:161], v[20:23], v[4:7], v[146:161]
	ds_read_b128 v[4:7], v57 offset:2592
	ds_write_b128 v58, v[222:225] offset:40960
	ds_write_b128 v58, v[228:231] offset:46080
	v_mfma_f32_32x32x16_bf16 v[98:113], v[16:19], v[8:11], v[98:113]
	v_mfma_f32_32x32x16_bf16 v[162:177], v[20:23], v[8:11], v[162:177]
	ds_read_b128 v[8:11], v57 offset:5152
	ds_write_b128 v58, v[232:235] offset:51200
	ds_write_b128 v58, v[236:239] offset:56320
	v_mfma_f32_32x32x16_bf16 v[114:129], v[16:19], v[12:15], v[114:129]
	v_mfma_f32_32x32x16_bf16 v[178:193], v[20:23], v[12:15], v[178:193]
	ds_read_b128 v[12:15], v57 offset:7712
	s_waitcnt lgkmcnt(9)
	v_mfma_f32_32x32x16_bf16 v[66:81], v[24:27], v[0:3], v[66:81]
	global_load_dwordx4 v[214:217], v[240:241], off offset:3776
	global_load_dwordx4 v[218:221], v[242:243], off offset:3776
	v_mfma_f32_32x32x16_bf16 v[130:145], v[28:31], v[0:3], v[130:145]
	s_waitcnt lgkmcnt(6)
	v_mfma_f32_32x32x16_bf16 v[82:97], v[24:27], v[4:7], v[82:97]
	global_load_dwordx4 v[222:225], v[244:245], off offset:1728
	global_load_dwordx4 v[228:231], v[246:247], off offset:1728
	v_mfma_f32_32x32x16_bf16 v[146:161], v[28:31], v[4:7], v[146:161]
	s_waitcnt lgkmcnt(3)
	v_mfma_f32_32x32x16_bf16 v[98:113], v[24:27], v[8:11], v[98:113]
	global_load_dwordx4 v[232:235], v[248:249], off offset:1728
	global_load_dwordx4 v[236:239], v[250:251], off offset:1728
	v_mfma_f32_32x32x16_bf16 v[162:177], v[28:31], v[8:11], v[162:177]
	s_waitcnt lgkmcnt(0)
	v_mfma_f32_32x32x16_bf16 v[114:129], v[24:27], v[12:15], v[114:129]
	v_mfma_f32_32x32x16_bf16 v[178:193], v[28:31], v[12:15], v[178:193]
	s_waitcnt lgkmcnt(0)
	s_barrier
	ds_read_b128 v[0:3], v57 offset:30720
	ds_read_b128 v[4:7], v57 offset:33280
	ds_read_b128 v[8:11], v57 offset:35840
	ds_read_b128 v[12:15], v57 offset:38400
	ds_read_b128 v[16:19], v56 offset:30720
	ds_read_b128 v[20:23], v56 offset:33280
	ds_read_b128 v[24:27], v56 offset:30752
	ds_read_b128 v[28:31], v56 offset:33312
	s_waitcnt lgkmcnt(2)
	v_mfma_f32_32x32x16_bf16 v[66:81], v[16:19], v[0:3], v[66:81]
	v_mfma_f32_32x32x16_bf16 v[130:145], v[20:23], v[0:3], v[130:145]
	ds_read_b128 v[0:3], v57 offset:30752
	s_waitcnt vmcnt(6)
	ds_write_b128 v58, v[32:35] offset:0
	ds_write_b128 v58, v[36:39] offset:5120
	v_mfma_f32_32x32x16_bf16 v[82:97], v[16:19], v[4:7], v[82:97]
	v_mfma_f32_32x32x16_bf16 v[146:161], v[20:23], v[4:7], v[146:161]
	ds_read_b128 v[4:7], v57 offset:33312
	ds_write_b128 v58, v[40:43] offset:10240
	ds_write_b128 v58, v[44:47] offset:15360
	v_mfma_f32_32x32x16_bf16 v[98:113], v[16:19], v[8:11], v[98:113]
	v_mfma_f32_32x32x16_bf16 v[162:177], v[20:23], v[8:11], v[162:177]
	ds_read_b128 v[8:11], v57 offset:35872
	ds_write_b128 v58, v[48:51] offset:20480
	ds_write_b128 v58, v[52:55] offset:25600
	v_mfma_f32_32x32x16_bf16 v[114:129], v[16:19], v[12:15], v[114:129]
	v_mfma_f32_32x32x16_bf16 v[178:193], v[20:23], v[12:15], v[178:193]
	ds_read_b128 v[12:15], v57 offset:38432
	s_waitcnt lgkmcnt(9)
	v_mfma_f32_32x32x16_bf16 v[66:81], v[24:27], v[0:3], v[66:81]
	global_load_dwordx4 v[32:35], v[240:241], off offset:3840
	global_load_dwordx4 v[36:39], v[242:243], off offset:3840
	v_mfma_f32_32x32x16_bf16 v[130:145], v[28:31], v[0:3], v[130:145]
	s_waitcnt lgkmcnt(6)
	v_mfma_f32_32x32x16_bf16 v[82:97], v[24:27], v[4:7], v[82:97]
	global_load_dwordx4 v[40:43], v[244:245], off offset:1792
	global_load_dwordx4 v[44:47], v[246:247], off offset:1792
	v_mfma_f32_32x32x16_bf16 v[146:161], v[28:31], v[4:7], v[146:161]
	s_waitcnt lgkmcnt(3)
	v_mfma_f32_32x32x16_bf16 v[98:113], v[24:27], v[8:11], v[98:113]
	global_load_dwordx4 v[48:51], v[248:249], off offset:1792
	global_load_dwordx4 v[52:55], v[250:251], off offset:1792
	v_mfma_f32_32x32x16_bf16 v[162:177], v[28:31], v[8:11], v[162:177]
	s_waitcnt lgkmcnt(0)
	v_mfma_f32_32x32x16_bf16 v[114:129], v[24:27], v[12:15], v[114:129]
	v_mfma_f32_32x32x16_bf16 v[178:193], v[28:31], v[12:15], v[178:193]
	s_waitcnt lgkmcnt(0)
	s_barrier
; #define G_LOAD(S, kt_) do { G_LD1(S##a0, S##b0, 0, kt_); G_LD1(S##a1, S##b1, 1, kt_); G_LD1(S##a2, S##b2, 2, kt_); G_LD1(S##a3, S##b3, 3, kt_); } while (0)
; #define G_STORE(S, buf_) do { G_ST1(S##a0, S##b0, 0, buf_); G_ST1(S##a1, S##b1, 1, buf_); G_ST1(S##a2, S##b2, 2, buf_); G_ST1(S##a3, S##b3, 3, buf_); } while (0)
; template <class AL, class BL>
; DI void gemm_core(AL al, BL bl, int m0, int n0, int K, char* smem, f32x16 (&acc)[2][2]) {
;     ...
;   G_LOAD(x, 0);
;   G_STORE(x, 0);
;   G_LOAD(x, 1);
;   G_LOAD(y, (nk > 2) ? 2 : 1);
;   __syncthreads();
;   for (int kt = 0; kt < nk; kt += 2) {
;     G_TILE(0, x, true, (kt + 3 < nk), kt + 3);
;     __syncthreads();
;     G_TILE(1, y, (kt + 2 < nk), (kt + 4 < nk), kt + 4);
;     __syncthreads();
	ds_read_b128 v[0:3], v57 offset:0
	ds_read_b128 v[4:7], v57 offset:2560
	ds_read_b128 v[8:11], v57 offset:5120
	ds_read_b128 v[12:15], v57 offset:7680
	ds_read_b128 v[16:19], v56 offset:0
	ds_read_b128 v[20:23], v56 offset:2560
	ds_read_b128 v[24:27], v56 offset:32
	ds_read_b128 v[28:31], v56 offset:2592
	s_waitcnt lgkmcnt(2)
	v_mfma_f32_32x32x16_bf16 v[66:81], v[16:19], v[0:3], v[66:81]
	v_mfma_f32_32x32x16_bf16 v[130:145], v[20:23], v[0:3], v[130:145]
	ds_read_b128 v[0:3], v57 offset:32
	s_waitcnt vmcnt(6)
	ds_write_b128 v58, v[214:217] offset:30720
	ds_write_b128 v58, v[218:221] offset:35840
	v_mfma_f32_32x32x16_bf16 v[82:97], v[16:19], v[4:7], v[82:97]
	v_mfma_f32_32x32x16_bf16 v[146:161], v[20:23], v[4:7], v[146:161]
	ds_read_b128 v[4:7], v57 offset:2592
	ds_write_b128 v58, v[222:225] offset:40960
	ds_write_b128 v58, v[228:231] offset:46080
	v_mfma_f32_32x32x16_bf16 v[98:113], v[16:19], v[8:11], v[98:113]
	v_mfma_f32_32x32x16_bf16 v[162:177], v[20:23], v[8:11], v[162:177]
	ds_read_b128 v[8:11], v57 offset:5152
	ds_write_b128 v58, v[232:235] offset:51200
	ds_write_b128 v58, v[236:239] offset:56320
	v_mfma_f32_32x32x16_bf16 v[114:129], v[16:19], v[12:15], v[114:129]
	v_mfma_f32_32x32x16_bf16 v[178:193], v[20:23], v[12:15], v[178:193]
	ds_read_b128 v[12:15], v57 offset:7712
	s_waitcnt lgkmcnt(9)
	v_mfma_f32_32x32x16_bf16 v[66:81], v[24:27], v[0:3], v[66:81]
	global_load_dwordx4 v[214:217], v[240:241], off offset:3904
	global_load_dwordx4 v[218:221], v[242:243], off offset:3904
	v_mfma_f32_32x32x16_bf16 v[130:145], v[28:31], v[0:3], v[130:145]
	s_waitcnt lgkmcnt(6)
	v_mfma_f32_32x32x16_bf16 v[82:97], v[24:27], v[4:7], v[82:97]
	global_load_dwordx4 v[222:225], v[244:245], off offset:1856
	global_load_dwordx4 v[228:231], v[246:247], off offset:1856
	v_mfma_f32_32x32x16_bf16 v[146:161], v[28:31], v[4:7], v[146:161]
	s_waitcnt lgkmcnt(3)
	v_mfma_f32_32x32x16_bf16 v[98:113], v[24:27], v[8:11], v[98:113]
	global_load_dwordx4 v[232:235], v[248:249], off offset:1856
	global_load_dwordx4 v[236:239], v[250:251], off offset:1856
	v_mfma_f32_32x32x16_bf16 v[162:177], v[28:31], v[8:11], v[162:177]
	s_waitcnt lgkmcnt(0)
	v_mfma_f32_32x32x16_bf16 v[114:129], v[24:27], v[12:15], v[114:129]
	v_mfma_f32_32x32x16_bf16 v[178:193], v[28:31], v[12:15], v[178:193]
	s_waitcnt lgkmcnt(0)
	s_barrier
	ds_read_b128 v[0:3], v57 offset:30720
	ds_read_b128 v[4:7], v57 offset:33280
	ds_read_b128 v[8:11], v57 offset:35840
	ds_read_b128 v[12:15], v57 offset:38400
	ds_read_b128 v[16:19], v56 offset:30720
	ds_read_b128 v[20:23], v56 offset:33280
	ds_read_b128 v[24:27], v56 offset:30752
	ds_read_b128 v[28:31], v56 offset:33312
	s_waitcnt lgkmcnt(2)
	v_mfma_f32_32x32x16_bf16 v[66:81], v[16:19], v[0:3], v[66:81]
	v_mfma_f32_32x32x16_bf16 v[130:145], v[20:23], v[0:3], v[130:145]
	ds_read_b128 v[0:3], v57 offset:30752
	s_waitcnt vmcnt(6)
	ds_write_b128 v58, v[32:35] offset:0
	ds_write_b128 v58, v[36:39] offset:5120
	v_mfma_f32_32x32x16_bf16 v[82:97], v[16:19], v[4:7], v[82:97]
	v_mfma_f32_32x32x16_bf16 v[146:161], v[20:23], v[4:7], v[146:161]
	ds_read_b128 v[4:7], v57 offset:33312
	ds_write_b128 v58, v[40:43] offset:10240
	ds_write_b128 v58, v[44:47] offset:15360
	v_mfma_f32_32x32x16_bf16 v[98:113], v[16:19], v[8:11], v[98:113]
	v_mfma_f32_32x32x16_bf16 v[162:177], v[20:23], v[8:11], v[162:177]
	ds_read_b128 v[8:11], v57 offset:35872
	ds_write_b128 v58, v[48:51] offset:20480
	ds_write_b128 v58, v[52:55] offset:25600
	v_mfma_f32_32x32x16_bf16 v[114:129], v[16:19], v[12:15], v[114:129]
	v_mfma_f32_32x32x16_bf16 v[178:193], v[20:23], v[12:15], v[178:193]
	ds_read_b128 v[12:15], v57 offset:38432
	s_waitcnt lgkmcnt(9)
	v_mfma_f32_32x32x16_bf16 v[66:81], v[24:27], v[0:3], v[66:81]
	global_load_dwordx4 v[32:35], v[240:241], off offset:3968
	global_load_dwordx4 v[36:39], v[242:243], off offset:3968
	v_mfma_f32_32x32x16_bf16 v[130:145], v[28:31], v[0:3], v[130:145]
	s_waitcnt lgkmcnt(6)
	v_mfma_f32_32x32x16_bf16 v[82:97], v[24:27], v[4:7], v[82:97]
	global_load_dwordx4 v[40:43], v[244:245], off offset:1920
	global_load_dwordx4 v[44:47], v[246:247], off offset:1920
	v_mfma_f32_32x32x16_bf16 v[146:161], v[28:31], v[4:7], v[146:161]
	s_waitcnt lgkmcnt(3)
	v_mfma_f32_32x32x16_bf16 v[98:113], v[24:27], v[8:11], v[98:113]
	global_load_dwordx4 v[48:51], v[248:249], off offset:1920
	global_load_dwordx4 v[52:55], v[250:251], off offset:1920
	v_mfma_f32_32x32x16_bf16 v[162:177], v[28:31], v[8:11], v[162:177]
	s_waitcnt lgkmcnt(0)
	v_mfma_f32_32x32x16_bf16 v[114:129], v[24:27], v[12:15], v[114:129]
	v_mfma_f32_32x32x16_bf16 v[178:193], v[28:31], v[12:15], v[178:193]
	s_waitcnt lgkmcnt(0)
	s_barrier
; #define G_LOAD(S, kt_) do { G_LD1(S##a0, S##b0, 0, kt_); G_LD1(S##a1, S##b1, 1, kt_); G_LD1(S##a2, S##b2, 2, kt_); G_LD1(S##a3, S##b3, 3, kt_); } while (0)
; #define G_STORE(S, buf_) do { G_ST1(S##a0, S##b0, 0, buf_); G_ST1(S##a1, S##b1, 1, buf_); G_ST1(S##a2, S##b2, 2, buf_); G_ST1(S##a3, S##b3, 3, buf_); } while (0)
; template <class AL, class BL>
; DI void gemm_core(AL al, BL bl, int m0, int n0, int K, char* smem, f32x16 (&acc)[2][2]) {
;     ...
;   G_LOAD(x, 0);
;   G_STORE(x, 0);
;   G_LOAD(x, 1);
;   G_LOAD(y, (nk > 2) ? 2 : 1);
;   __syncthreads();
;   for (int kt = 0; kt < nk; kt += 2) {
;     G_TILE(0, x, true, (kt + 3 < nk), kt + 3);
;     __syncthreads();
;     G_TILE(1, y, (kt + 2 < nk), (kt + 4 < nk), kt + 4);
;     __syncthreads();
	ds_read_b128 v[0:3], v57 offset:0
	ds_read_b128 v[4:7], v57 offset:2560
	ds_read_b128 v[8:11], v57 offset:5120
	ds_read_b128 v[12:15], v57 offset:7680
	ds_read_b128 v[16:19], v56 offset:0
	ds_read_b128 v[20:23], v56 offset:2560
	ds_read_b128 v[24:27], v56 offset:32
	ds_read_b128 v[28:31], v56 offset:2592
	s_waitcnt lgkmcnt(2)
	v_mfma_f32_32x32x16_bf16 v[66:81], v[16:19], v[0:3], v[66:81]
	v_mfma_f32_32x32x16_bf16 v[130:145], v[20:23], v[0:3], v[130:145]
	ds_read_b128 v[0:3], v57 offset:32
	s_waitcnt vmcnt(6)
	ds_write_b128 v58, v[214:217] offset:30720
	ds_write_b128 v58, v[218:221] offset:35840
	v_mfma_f32_32x32x16_bf16 v[82:97], v[16:19], v[4:7], v[82:97]
	v_mfma_f32_32x32x16_bf16 v[146:161], v[20:23], v[4:7], v[146:161]
	ds_read_b128 v[4:7], v57 offset:2592
	ds_write_b128 v58, v[222:225] offset:40960
	ds_write_b128 v58, v[228:231] offset:46080
	v_mfma_f32_32x32x16_bf16 v[98:113], v[16:19], v[8:11], v[98:113]
	v_mfma_f32_32x32x16_bf16 v[162:177], v[20:23], v[8:11], v[162:177]
	ds_read_b128 v[8:11], v57 offset:5152
	ds_write_b128 v58, v[232:235] offset:51200
	ds_write_b128 v58, v[236:239] offset:56320
	v_mfma_f32_32x32x16_bf16 v[114:129], v[16:19], v[12:15], v[114:129]
	v_mfma_f32_32x32x16_bf16 v[178:193], v[20:23], v[12:15], v[178:193]
	ds_read_b128 v[12:15], v57 offset:7712
	s_waitcnt lgkmcnt(9)
	v_mfma_f32_32x32x16_bf16 v[66:81], v[24:27], v[0:3], v[66:81]
	global_load_dwordx4 v[214:217], v[240:241], off offset:4032
	global_load_dwordx4 v[218:221], v[242:243], off offset:4032
	v_mfma_f32_32x32x16_bf16 v[130:145], v[28:31], v[0:3], v[130:145]
	s_waitcnt lgkmcnt(6)
	v_mfma_f32_32x32x16_bf16 v[82:97], v[24:27], v[4:7], v[82:97]
	global_load_dwordx4 v[222:225], v[244:245], off offset:1984
	global_load_dwordx4 v[228:231], v[246:247], off offset:1984
	v_mfma_f32_32x32x16_bf16 v[146:161], v[28:31], v[4:7], v[146:161]
	s_waitcnt lgkmcnt(3)
	v_mfma_f32_32x32x16_bf16 v[98:113], v[24:27], v[8:11], v[98:113]
	global_load_dwordx4 v[232:235], v[248:249], off offset:1984
	global_load_dwordx4 v[236:239], v[250:251], off offset:1984
	v_mfma_f32_32x32x16_bf16 v[162:177], v[28:31], v[8:11], v[162:177]
	s_waitcnt lgkmcnt(0)
	v_mfma_f32_32x32x16_bf16 v[114:129], v[24:27], v[12:15], v[114:129]
	v_mfma_f32_32x32x16_bf16 v[178:193], v[28:31], v[12:15], v[178:193]
	s_waitcnt lgkmcnt(0)
	s_barrier
	ds_read_b128 v[0:3], v57 offset:30720
	ds_read_b128 v[4:7], v57 offset:33280
	ds_read_b128 v[8:11], v57 offset:35840
	ds_read_b128 v[12:15], v57 offset:38400
	ds_read_b128 v[16:19], v56 offset:30720
	ds_read_b128 v[20:23], v56 offset:33280
	ds_read_b128 v[24:27], v56 offset:30752
	ds_read_b128 v[28:31], v56 offset:33312
	s_waitcnt lgkmcnt(2)
	v_mfma_f32_32x32x16_bf16 v[66:81], v[16:19], v[0:3], v[66:81]
	v_mfma_f32_32x32x16_bf16 v[130:145], v[20:23], v[0:3], v[130:145]
	ds_read_b128 v[0:3], v57 offset:30752
	s_waitcnt vmcnt(6)
	ds_write_b128 v58, v[32:35] offset:0
	ds_write_b128 v58, v[36:39] offset:5120
	v_mfma_f32_32x32x16_bf16 v[82:97], v[16:19], v[4:7], v[82:97]
	v_mfma_f32_32x32x16_bf16 v[146:161], v[20:23], v[4:7], v[146:161]
	ds_read_b128 v[4:7], v57 offset:33312
	ds_write_b128 v58, v[40:43] offset:10240
	ds_write_b128 v58, v[44:47] offset:15360
	v_mfma_f32_32x32x16_bf16 v[98:113], v[16:19], v[8:11], v[98:113]
	v_mfma_f32_32x32x16_bf16 v[162:177], v[20:23], v[8:11], v[162:177]
	ds_read_b128 v[8:11], v57 offset:35872
	ds_write_b128 v58, v[48:51] offset:20480
	ds_write_b128 v58, v[52:55] offset:25600
	v_mfma_f32_32x32x16_bf16 v[114:129], v[16:19], v[12:15], v[114:129]
	v_mfma_f32_32x32x16_bf16 v[178:193], v[20:23], v[12:15], v[178:193]
	ds_read_b128 v[12:15], v57 offset:38432
	s_waitcnt lgkmcnt(9)
	v_mfma_f32_32x32x16_bf16 v[66:81], v[24:27], v[0:3], v[66:81]
	v_mfma_f32_32x32x16_bf16 v[130:145], v[28:31], v[0:3], v[130:145]
	s_waitcnt lgkmcnt(6)
	v_mfma_f32_32x32x16_bf16 v[82:97], v[24:27], v[4:7], v[82:97]
	v_mfma_f32_32x32x16_bf16 v[146:161], v[28:31], v[4:7], v[146:161]
	s_waitcnt lgkmcnt(3)
	v_mfma_f32_32x32x16_bf16 v[98:113], v[24:27], v[8:11], v[98:113]
	v_mfma_f32_32x32x16_bf16 v[162:177], v[28:31], v[8:11], v[162:177]
	s_waitcnt lgkmcnt(0)
	v_mfma_f32_32x32x16_bf16 v[114:129], v[24:27], v[12:15], v[114:129]
	v_mfma_f32_32x32x16_bf16 v[178:193], v[28:31], v[12:15], v[178:193]
	s_waitcnt lgkmcnt(0)
	s_barrier
; #define G_LOAD(S, kt_) do { G_LD1(S##a0, S##b0, 0, kt_); G_LD1(S##a1, S##b1, 1, kt_); G_LD1(S##a2, S##b2, 2, kt_); G_LD1(S##a3, S##b3, 3, kt_); } while (0)
; #define G_STORE(S, buf_) do { G_ST1(S##a0, S##b0, 0, buf_); G_ST1(S##a1, S##b1, 1, buf_); G_ST1(S##a2, S##b2, 2, buf_); G_ST1(S##a3, S##b3, 3, buf_); } while (0)
; template <class AL, class BL>
; DI void gemm_core(AL al, BL bl, int m0, int n0, int K, char* smem, f32x16 (&acc)[2][2]) {
;     ...
;   G_LOAD(x, 0);
;   G_STORE(x, 0);
;   G_LOAD(x, 1);
;   G_LOAD(y, (nk > 2) ? 2 : 1);
;   __syncthreads();
;   for (int kt = 0; kt < nk; kt += 2) {
;     G_TILE(0, x, true, (kt + 3 < nk), kt + 3);
;     __syncthreads();
;     G_TILE(1, y, (kt + 2 < nk), (kt + 4 < nk), kt + 4);
;     __syncthreads();
; DI void ffn_up_phase(const Params& p, const u16* xb, int ldx, const u16* wupT, u16* hid, char* smem) {
;     ...
;              [=](const f32x16 (&acc)[2][2], int m0, int n0) {
;                epi_bf16_tile(acc, m0, n0, hid + (long)m0 * 4096 + n0, 4096, smem, [=](int m, int n, float v) {
;                  const float a = fmaxf(v * rs[m], 0.f);
;                  return a * a;
;                });
	ds_read_b128 v[0:3], v57 offset:0
	ds_read_b128 v[4:7], v57 offset:2560
	ds_read_b128 v[8:11], v57 offset:5120
	ds_read_b128 v[12:15], v57 offset:7680
	ds_read_b128 v[16:19], v56 offset:0
	ds_read_b128 v[20:23], v56 offset:2560
	ds_read_b128 v[24:27], v56 offset:32
	ds_read_b128 v[28:31], v56 offset:2592
	s_waitcnt lgkmcnt(2)
	v_mfma_f32_32x32x16_bf16 v[66:81], v[16:19], v[0:3], v[66:81]
	v_mfma_f32_32x32x16_bf16 v[130:145], v[20:23], v[0:3], v[130:145]
	ds_read_b128 v[0:3], v57 offset:32
	s_waitcnt vmcnt(0)
	ds_write_b128 v58, v[214:217] offset:30720
	ds_write_b128 v58, v[218:221] offset:35840
	v_mfma_f32_32x32x16_bf16 v[82:97], v[16:19], v[4:7], v[82:97]
	v_mfma_f32_32x32x16_bf16 v[146:161], v[20:23], v[4:7], v[146:161]
	ds_read_b128 v[4:7], v57 offset:2592
	ds_write_b128 v58, v[222:225] offset:40960
	ds_write_b128 v58, v[228:231] offset:46080
	v_mfma_f32_32x32x16_bf16 v[98:113], v[16:19], v[8:11], v[98:113]
	v_mfma_f32_32x32x16_bf16 v[162:177], v[20:23], v[8:11], v[162:177]
	ds_read_b128 v[8:11], v57 offset:5152
	ds_write_b128 v58, v[232:235] offset:51200
	ds_write_b128 v58, v[236:239] offset:56320
	v_mfma_f32_32x32x16_bf16 v[114:129], v[16:19], v[12:15], v[114:129]
	v_mfma_f32_32x32x16_bf16 v[178:193], v[20:23], v[12:15], v[178:193]
	ds_read_b128 v[12:15], v57 offset:7712
	s_waitcnt lgkmcnt(9)
	v_mfma_f32_32x32x16_bf16 v[66:81], v[24:27], v[0:3], v[66:81]
	v_mfma_f32_32x32x16_bf16 v[130:145], v[28:31], v[0:3], v[130:145]
	s_waitcnt lgkmcnt(6)
	v_mfma_f32_32x32x16_bf16 v[82:97], v[24:27], v[4:7], v[82:97]
	v_mfma_f32_32x32x16_bf16 v[146:161], v[28:31], v[4:7], v[146:161]
	s_waitcnt lgkmcnt(3)
	v_mfma_f32_32x32x16_bf16 v[98:113], v[24:27], v[8:11], v[98:113]
	v_mfma_f32_32x32x16_bf16 v[162:177], v[28:31], v[8:11], v[162:177]
	s_waitcnt lgkmcnt(0)
	v_mfma_f32_32x32x16_bf16 v[114:129], v[24:27], v[12:15], v[114:129]
	v_mfma_f32_32x32x16_bf16 v[178:193], v[28:31], v[12:15], v[178:193]
	s_waitcnt lgkmcnt(0)
	s_barrier
	ds_read_b128 v[0:3], v57 offset:30720
	ds_read_b128 v[4:7], v57 offset:33280
	ds_read_b128 v[8:11], v57 offset:35840
	ds_read_b128 v[12:15], v57 offset:38400
	ds_read_b128 v[16:19], v56 offset:30720
	ds_read_b128 v[20:23], v56 offset:33280
	ds_read_b128 v[24:27], v56 offset:30752
	ds_read_b128 v[28:31], v56 offset:33312
	s_waitcnt lgkmcnt(2)
	v_mfma_f32_32x32x16_bf16 v[66:81], v[16:19], v[0:3], v[66:81]
	global_load_dword v32, v61, s[14:15] offset:0
	global_load_dword v33, v61, s[14:15] offset:4
	global_load_dword v34, v61, s[14:15] offset:8
	global_load_dword v35, v61, s[14:15] offset:12
	v_mfma_f32_32x32x16_bf16 v[130:145], v[20:23], v[0:3], v[130:145]
	ds_read_b128 v[0:3], v57 offset:30752
	v_mfma_f32_32x32x16_bf16 v[82:97], v[16:19], v[4:7], v[82:97]
	global_load_dword v36, v61, s[14:15] offset:32
	global_load_dword v37, v61, s[14:15] offset:36
	global_load_dword v38, v61, s[14:15] offset:40
	global_load_dword v39, v61, s[14:15] offset:44
	v_mfma_f32_32x32x16_bf16 v[146:161], v[20:23], v[4:7], v[146:161]
	ds_read_b128 v[4:7], v57 offset:33312
	v_mfma_f32_32x32x16_bf16 v[98:113], v[16:19], v[8:11], v[98:113]
	global_load_dword v40, v61, s[14:15] offset:64
	global_load_dword v41, v61, s[14:15] offset:68
	global_load_dword v42, v61, s[14:15] offset:72
	global_load_dword v43, v61, s[14:15] offset:76
	v_mfma_f32_32x32x16_bf16 v[162:177], v[20:23], v[8:11], v[162:177]
	ds_read_b128 v[8:11], v57 offset:35872
	v_mfma_f32_32x32x16_bf16 v[114:129], v[16:19], v[12:15], v[114:129]
	global_load_dword v44, v61, s[14:15] offset:96
	global_load_dword v45, v61, s[14:15] offset:100
	global_load_dword v46, v61, s[14:15] offset:104
	global_load_dword v47, v61, s[14:15] offset:108
	v_mfma_f32_32x32x16_bf16 v[178:193], v[20:23], v[12:15], v[178:193]
	ds_read_b128 v[12:15], v57 offset:38432
	s_waitcnt lgkmcnt(3)
	v_mfma_f32_32x32x16_bf16 v[66:81], v[24:27], v[0:3], v[66:81]
	global_load_dword v48, v61, s[14:15] offset:128
	global_load_dword v49, v61, s[14:15] offset:132
	global_load_dword v50, v61, s[14:15] offset:136
	global_load_dword v51, v61, s[14:15] offset:140
	v_mfma_f32_32x32x16_bf16 v[130:145], v[28:31], v[0:3], v[130:145]
	s_waitcnt lgkmcnt(2)
	v_mfma_f32_32x32x16_bf16 v[82:97], v[24:27], v[4:7], v[82:97]
	global_load_dword v52, v61, s[14:15] offset:160
	global_load_dword v53, v61, s[14:15] offset:164
	global_load_dword v54, v61, s[14:15] offset:168
	global_load_dword v55, v61, s[14:15] offset:172
	v_mfma_f32_32x32x16_bf16 v[146:161], v[28:31], v[4:7], v[146:161]
	s_waitcnt lgkmcnt(1)
	v_mfma_f32_32x32x16_bf16 v[98:113], v[24:27], v[8:11], v[98:113]
	global_load_dword v214, v61, s[14:15] offset:192
	global_load_dword v215, v61, s[14:15] offset:196
	global_load_dword v216, v61, s[14:15] offset:200
	global_load_dword v217, v61, s[14:15] offset:204
	v_mfma_f32_32x32x16_bf16 v[162:177], v[28:31], v[8:11], v[162:177]
	s_waitcnt lgkmcnt(0)
	v_mfma_f32_32x32x16_bf16 v[114:129], v[24:27], v[12:15], v[114:129]
	global_load_dword v218, v61, s[14:15] offset:224
	global_load_dword v219, v61, s[14:15] offset:228
	global_load_dword v220, v61, s[14:15] offset:232
	global_load_dword v221, v61, s[14:15] offset:236
	v_mfma_f32_32x32x16_bf16 v[178:193], v[28:31], v[12:15], v[178:193]
	s_waitcnt lgkmcnt(0)
	s_barrier
	s_nop 7
	s_nop 3
	s_waitcnt vmcnt(0)
	v_mov_b32_e32 v0, v32
	v_mov_b32_e32 v1, v33
	v_mov_b32_e32 v2, v34
	v_mov_b32_e32 v3, v35
	v_mov_b32_e32 v4, v36
	v_mov_b32_e32 v5, v37
	v_mov_b32_e32 v6, v38
	v_mov_b32_e32 v7, v39
	v_mov_b32_e32 v8, v40
	v_mov_b32_e32 v9, v41
	v_mov_b32_e32 v10, v42
	v_mov_b32_e32 v11, v43
	v_mov_b32_e32 v12, v44
	v_mov_b32_e32 v13, v45
	v_mov_b32_e32 v14, v46
	v_mov_b32_e32 v15, v47
	v_mov_b32_e32 v16, v48
	v_mov_b32_e32 v17, v49
	v_mov_b32_e32 v18, v50
	v_mov_b32_e32 v19, v51
	v_mov_b32_e32 v20, v52
	v_mov_b32_e32 v21, v53
	v_mov_b32_e32 v22, v54
	v_mov_b32_e32 v23, v55
	v_mov_b32_e32 v24, v214
	v_mov_b32_e32 v25, v215
	v_mov_b32_e32 v26, v216
	v_mov_b32_e32 v27, v217
	v_mov_b32_e32 v28, v218
	v_mov_b32_e32 v29, v219
	v_mov_b32_e32 v30, v220
	v_mov_b32_e32 v31, v221
	s_add_u32 s98, s98, s50
	s_cmpk_lt_u32 s98, 2048
	s_cbranch_scc0 .Lfu0_nonext
	s_cmpk_lt_u32 s98, 2016
	s_cbranch_scc1 .Lfu0_m1
	s_sub_u32 s34, s98, 2016
	s_mov_b32 s35, 14
	s_branch .Lfu0_g1

; #define G_LOAD(S, kt_) do { G_LD1(S##a0, S##b0, 0, kt_); G_LD1(S##a1, S##b1, 1, kt_); G_LD1(S##a2, S##b2, 2, kt_); G_LD1(S##a3, S##b3, 3, kt_); } while (0)
; #define G_STORE(S, buf_) do { G_ST1(S##a0, S##b0, 0, buf_); G_ST1(S##a1, S##b1, 1, buf_); G_ST1(S##a2, S##b2, 2, buf_); G_ST1(S##a3, S##b3, 3, buf_); } while (0)
; template <class AL, class BL>
; DI void gemm_core(AL al, BL bl, int m0, int n0, int K, char* smem, f32x16 (&acc)[2][2]) {
;     ...
;   G_LOAD(x, 0);
;   G_STORE(x, 0);
;   G_LOAD(x, 1);
;   G_LOAD(y, (nk > 2) ? 2 : 1);
;   __syncthreads();
;   for (int kt = 0; kt < nk; kt += 2) {
;     G_TILE(0, x, true, (kt + 3 < nk), kt + 3);
;     __syncthreads();
;     G_TILE(1, y, (kt + 2 < nk), (kt + 4 < nk), kt + 4);
;     __syncthreads();
; DI void ffn_up_phase(const Params& p, const u16* xb, int ldx, const u16* wupT, u16* hid, char* smem) {
;     ...
;   gemm_phase(NT / 128, 32, 1024,
;              [=](int m, int k) { return xb + (long)m * ldx + k; },
;              [=](int n, int k) { return wupT + (long)n * 1024 + k; },
;              [=](const f32x16 (&acc)[2][2], int m0, int n0) {
;                epi_bf16_tile(acc, m0, n0, hid + (long)m0 * 4096 + n0, 4096, smem, [=](int m, int n, float v) {
.Lfu1_tile:
	s_lshl_b32 s0, s31, 9
	v_add_u32_e32 v61, s0, v252
	s_lshl_b32 s0, s31, 7
	s_mul_i32 s1, s0, 8192
	s_mul_hi_u32 s2, s0, 8192
	s_add_u32 s18, s20, s1
	s_addc_u32 s19, s21, s2
	s_lshl_b32 s1, s33, 9
	s_add_u32 s18, s18, s1
	s_addc_u32 s19, s19, 0
	s_waitcnt vmcnt(6)
	ds_write_b128 v58, v[32:35] offset:0
	ds_write_b128 v58, v[36:39] offset:5120
	ds_write_b128 v58, v[40:43] offset:10240
	ds_write_b128 v58, v[44:47] offset:15360
	ds_write_b128 v58, v[48:51] offset:20480
	ds_write_b128 v58, v[52:55] offset:25600
	global_load_dwordx4 v[32:35], v[240:241], off offset:2176
	global_load_dwordx4 v[36:39], v[242:243], off offset:2176
	global_load_dwordx4 v[40:43], v[244:245], off offset:128
	global_load_dwordx4 v[44:47], v[246:247], off offset:128
	global_load_dwordx4 v[48:51], v[248:249], off offset:128
	global_load_dwordx4 v[52:55], v[250:251], off offset:128
	s_waitcnt lgkmcnt(0)
	s_barrier
	ds_read_b128 v[0:3], v57 offset:0
	ds_read_b128 v[4:7], v57 offset:2560
	ds_read_b128 v[8:11], v57 offset:5120
	ds_read_b128 v[12:15], v57 offset:7680
	ds_read_b128 v[16:19], v56 offset:0
	ds_read_b128 v[20:23], v56 offset:2560
	ds_read_b128 v[24:27], v56 offset:32
	ds_read_b128 v[28:31], v56 offset:2592
	s_waitcnt lgkmcnt(2)
	v_mfma_f32_32x32x16_bf16 v[66:81], v[16:19], v[0:3], 0
	v_mfma_f32_32x32x16_bf16 v[130:145], v[20:23], v[0:3], 0
	ds_read_b128 v[0:3], v57 offset:32
	s_waitcnt vmcnt(6)
	ds_write_b128 v58, v[214:217] offset:30720
	ds_write_b128 v58, v[218:221] offset:35840
	v_mfma_f32_32x32x16_bf16 v[82:97], v[16:19], v[4:7], 0
	v_mfma_f32_32x32x16_bf16 v[146:161], v[20:23], v[4:7], 0
	ds_read_b128 v[4:7], v57 offset:2592
	ds_write_b128 v58, v[222:225] offset:40960
	ds_write_b128 v58, v[228:231] offset:46080
	v_mfma_f32_32x32x16_bf16 v[98:113], v[16:19], v[8:11], 0
	v_mfma_f32_32x32x16_bf16 v[162:177], v[20:23], v[8:11], 0
	ds_read_b128 v[8:11], v57 offset:5152
	ds_write_b128 v58, v[232:235] offset:51200
	ds_write_b128 v58, v[236:239] offset:56320
	v_mfma_f32_32x32x16_bf16 v[114:129], v[16:19], v[12:15], 0
	v_mfma_f32_32x32x16_bf16 v[178:193], v[20:23], v[12:15], 0
	ds_read_b128 v[12:15], v57 offset:7712
	s_waitcnt lgkmcnt(9)
	v_mfma_f32_32x32x16_bf16 v[66:81], v[24:27], v[0:3], v[66:81]
	global_load_dwordx4 v[214:217], v[240:241], off offset:2240
	global_load_dwordx4 v[218:221], v[242:243], off offset:2240
	v_mfma_f32_32x32x16_bf16 v[130:145], v[28:31], v[0:3], v[130:145]
	s_waitcnt lgkmcnt(6)
	v_mfma_f32_32x32x16_bf16 v[82:97], v[24:27], v[4:7], v[82:97]
	global_load_dwordx4 v[222:225], v[244:245], off offset:192
	global_load_dwordx4 v[228:231], v[246:247], off offset:192
	v_mfma_f32_32x32x16_bf16 v[146:161], v[28:31], v[4:7], v[146:161]
	s_waitcnt lgkmcnt(3)
	v_mfma_f32_32x32x16_bf16 v[98:113], v[24:27], v[8:11], v[98:113]
	global_load_dwordx4 v[232:235], v[248:249], off offset:192
	global_load_dwordx4 v[236:239], v[250:251], off offset:192
	v_mfma_f32_32x32x16_bf16 v[162:177], v[28:31], v[8:11], v[162:177]
	s_waitcnt lgkmcnt(0)
	v_mfma_f32_32x32x16_bf16 v[114:129], v[24:27], v[12:15], v[114:129]
	v_mfma_f32_32x32x16_bf16 v[178:193], v[28:31], v[12:15], v[178:193]
	s_waitcnt lgkmcnt(0)
	s_barrier
	ds_read_b128 v[0:3], v57 offset:30720
	ds_read_b128 v[4:7], v57 offset:33280
	ds_read_b128 v[8:11], v57 offset:35840
	ds_read_b128 v[12:15], v57 offset:38400
	ds_read_b128 v[16:19], v56 offset:30720
	ds_read_b128 v[20:23], v56 offset:33280
	ds_read_b128 v[24:27], v56 offset:30752
	ds_read_b128 v[28:31], v56 offset:33312
	s_waitcnt lgkmcnt(2)
	v_mfma_f32_32x32x16_bf16 v[66:81], v[16:19], v[0:3], v[66:81]
	v_mfma_f32_32x32x16_bf16 v[130:145], v[20:23], v[0:3], v[130:145]
	ds_read_b128 v[0:3], v57 offset:30752
	s_waitcnt vmcnt(6)
	ds_write_b128 v58, v[32:35] offset:0
	ds_write_b128 v58, v[36:39] offset:5120
	v_mfma_f32_32x32x16_bf16 v[82:97], v[16:19], v[4:7], v[82:97]
	v_mfma_f32_32x32x16_bf16 v[146:161], v[20:23], v[4:7], v[146:161]
	ds_read_b128 v[4:7], v57 offset:33312
	ds_write_b128 v58, v[40:43] offset:10240
	ds_write_b128 v58, v[44:47] offset:15360
	v_mfma_f32_32x32x16_bf16 v[98:113], v[16:19], v[8:11], v[98:113]
	v_mfma_f32_32x32x16_bf16 v[162:177], v[20:23], v[8:11], v[162:177]
	ds_read_b128 v[8:11], v57 offset:35872
	ds_write_b128 v58, v[48:51] offset:20480
	ds_write_b128 v58, v[52:55] offset:25600
	v_mfma_f32_32x32x16_bf16 v[114:129], v[16:19], v[12:15], v[114:129]
	v_mfma_f32_32x32x16_bf16 v[178:193], v[20:23], v[12:15], v[178:193]
	ds_read_b128 v[12:15], v57 offset:38432
	s_waitcnt lgkmcnt(9)
	v_mfma_f32_32x32x16_bf16 v[66:81], v[24:27], v[0:3], v[66:81]
	global_load_dwordx4 v[32:35], v[240:241], off offset:2304
	global_load_dwordx4 v[36:39], v[242:243], off offset:2304
	v_mfma_f32_32x32x16_bf16 v[130:145], v[28:31], v[0:3], v[130:145]
	s_waitcnt lgkmcnt(6)
	v_mfma_f32_32x32x16_bf16 v[82:97], v[24:27], v[4:7], v[82:97]
	global_load_dwordx4 v[40:43], v[244:245], off offset:256
	global_load_dwordx4 v[44:47], v[246:247], off offset:256
	v_mfma_f32_32x32x16_bf16 v[146:161], v[28:31], v[4:7], v[146:161]
	s_waitcnt lgkmcnt(3)
	v_mfma_f32_32x32x16_bf16 v[98:113], v[24:27], v[8:11], v[98:113]
	global_load_dwordx4 v[48:51], v[248:249], off offset:256
	global_load_dwordx4 v[52:55], v[250:251], off offset:256
	v_mfma_f32_32x32x16_bf16 v[162:177], v[28:31], v[8:11], v[162:177]
	s_waitcnt lgkmcnt(0)
	v_mfma_f32_32x32x16_bf16 v[114:129], v[24:27], v[12:15], v[114:129]
	v_mfma_f32_32x32x16_bf16 v[178:193], v[28:31], v[12:15], v[178:193]
	s_waitcnt lgkmcnt(0)
	s_barrier
; #define G_LOAD(S, kt_) do { G_LD1(S##a0, S##b0, 0, kt_); G_LD1(S##a1, S##b1, 1, kt_); G_LD1(S##a2, S##b2, 2, kt_); G_LD1(S##a3, S##b3, 3, kt_); } while (0)
; #define G_STORE(S, buf_) do { G_ST1(S##a0, S##b0, 0, buf_); G_ST1(S##a1, S##b1, 1, buf_); G_ST1(S##a2, S##b2, 2, buf_); G_ST1(S##a3, S##b3, 3, buf_); } while (0)
; template <class AL, class BL>
; DI void gemm_core(AL al, BL bl, int m0, int n0, int K, char* smem, f32x16 (&acc)[2][2]) {
;     ...
;   G_LOAD(x, 0);
;   G_STORE(x, 0);
;   G_LOAD(x, 1);
;   G_LOAD(y, (nk > 2) ? 2 : 1);
;   __syncthreads();
;   for (int kt = 0; kt < nk; kt += 2) {
;     G_TILE(0, x, true, (kt + 3 < nk), kt + 3);
;     __syncthreads();
;     G_TILE(1, y, (kt + 2 < nk), (kt + 4 < nk), kt + 4);
;     __syncthreads();
	ds_read_b128 v[0:3], v57 offset:0
	ds_read_b128 v[4:7], v57 offset:2560
	ds_read_b128 v[8:11], v57 offset:5120
	ds_read_b128 v[12:15], v57 offset:7680
	ds_read_b128 v[16:19], v56 offset:0
	ds_read_b128 v[20:23], v56 offset:2560
	ds_read_b128 v[24:27], v56 offset:32
	ds_read_b128 v[28:31], v56 offset:2592
	s_waitcnt lgkmcnt(2)
	v_mfma_f32_32x32x16_bf16 v[66:81], v[16:19], v[0:3], v[66:81]
	v_mfma_f32_32x32x16_bf16 v[130:145], v[20:23], v[0:3], v[130:145]
	ds_read_b128 v[0:3], v57 offset:32
	s_waitcnt vmcnt(6)
	ds_write_b128 v58, v[214:217] offset:30720
	ds_write_b128 v58, v[218:221] offset:35840
	v_mfma_f32_32x32x16_bf16 v[82:97], v[16:19], v[4:7], v[82:97]
	v_mfma_f32_32x32x16_bf16 v[146:161], v[20:23], v[4:7], v[146:161]
	ds_read_b128 v[4:7], v57 offset:2592
	ds_write_b128 v58, v[222:225] offset:40960
	ds_write_b128 v58, v[228:231] offset:46080
	v_mfma_f32_32x32x16_bf16 v[98:113], v[16:19], v[8:11], v[98:113]
	v_mfma_f32_32x32x16_bf16 v[162:177], v[20:23], v[8:11], v[162:177]
	ds_read_b128 v[8:11], v57 offset:5152
	ds_write_b128 v58, v[232:235] offset:51200
	ds_write_b128 v58, v[236:239] offset:56320
	v_mfma_f32_32x32x16_bf16 v[114:129], v[16:19], v[12:15], v[114:129]
	v_mfma_f32_32x32x16_bf16 v[178:193], v[20:23], v[12:15], v[178:193]
	ds_read_b128 v[12:15], v57 offset:7712
	s_waitcnt lgkmcnt(9)
	v_mfma_f32_32x32x16_bf16 v[66:81], v[24:27], v[0:3], v[66:81]
	global_load_dwordx4 v[214:217], v[240:241], off offset:2368
	global_load_dwordx4 v[218:221], v[242:243], off offset:2368
	v_mfma_f32_32x32x16_bf16 v[130:145], v[28:31], v[0:3], v[130:145]
	s_waitcnt lgkmcnt(6)
	v_mfma_f32_32x32x16_bf16 v[82:97], v[24:27], v[4:7], v[82:97]
	global_load_dwordx4 v[222:225], v[244:245], off offset:320
	global_load_dwordx4 v[228:231], v[246:247], off offset:320
	v_mfma_f32_32x32x16_bf16 v[146:161], v[28:31], v[4:7], v[146:161]
	s_waitcnt lgkmcnt(3)
	v_mfma_f32_32x32x16_bf16 v[98:113], v[24:27], v[8:11], v[98:113]
	global_load_dwordx4 v[232:235], v[248:249], off offset:320
	global_load_dwordx4 v[236:239], v[250:251], off offset:320
	v_mfma_f32_32x32x16_bf16 v[162:177], v[28:31], v[8:11], v[162:177]
	s_waitcnt lgkmcnt(0)
	v_mfma_f32_32x32x16_bf16 v[114:129], v[24:27], v[12:15], v[114:129]
	v_mfma_f32_32x32x16_bf16 v[178:193], v[28:31], v[12:15], v[178:193]
	s_waitcnt lgkmcnt(0)
	s_barrier
	ds_read_b128 v[0:3], v57 offset:30720
	ds_read_b128 v[4:7], v57 offset:33280
	ds_read_b128 v[8:11], v57 offset:35840
	ds_read_b128 v[12:15], v57 offset:38400
	ds_read_b128 v[16:19], v56 offset:30720
	ds_read_b128 v[20:23], v56 offset:33280
	ds_read_b128 v[24:27], v56 offset:30752
	ds_read_b128 v[28:31], v56 offset:33312
	s_waitcnt lgkmcnt(2)
	v_mfma_f32_32x32x16_bf16 v[66:81], v[16:19], v[0:3], v[66:81]
	v_mfma_f32_32x32x16_bf16 v[130:145], v[20:23], v[0:3], v[130:145]
	ds_read_b128 v[0:3], v57 offset:30752
	s_waitcnt vmcnt(6)
	ds_write_b128 v58, v[32:35] offset:0
	ds_write_b128 v58, v[36:39] offset:5120
	v_mfma_f32_32x32x16_bf16 v[82:97], v[16:19], v[4:7], v[82:97]
	v_mfma_f32_32x32x16_bf16 v[146:161], v[20:23], v[4:7], v[146:161]
	ds_read_b128 v[4:7], v57 offset:33312
	ds_write_b128 v58, v[40:43] offset:10240
	ds_write_b128 v58, v[44:47] offset:15360
	v_mfma_f32_32x32x16_bf16 v[98:113], v[16:19], v[8:11], v[98:113]
	v_mfma_f32_32x32x16_bf16 v[162:177], v[20:23], v[8:11], v[162:177]
	ds_read_b128 v[8:11], v57 offset:35872
	ds_write_b128 v58, v[48:51] offset:20480
	ds_write_b128 v58, v[52:55] offset:25600
	v_mfma_f32_32x32x16_bf16 v[114:129], v[16:19], v[12:15], v[114:129]
	v_mfma_f32_32x32x16_bf16 v[178:193], v[20:23], v[12:15], v[178:193]
	ds_read_b128 v[12:15], v57 offset:38432
	s_waitcnt lgkmcnt(9)
	v_mfma_f32_32x32x16_bf16 v[66:81], v[24:27], v[0:3], v[66:81]
	global_load_dwordx4 v[32:35], v[240:241], off offset:2432
	global_load_dwordx4 v[36:39], v[242:243], off offset:2432
	v_mfma_f32_32x32x16_bf16 v[130:145], v[28:31], v[0:3], v[130:145]
	s_waitcnt lgkmcnt(6)
	v_mfma_f32_32x32x16_bf16 v[82:97], v[24:27], v[4:7], v[82:97]
	global_load_dwordx4 v[40:43], v[244:245], off offset:384
	global_load_dwordx4 v[44:47], v[246:247], off offset:384
	v_mfma_f32_32x32x16_bf16 v[146:161], v[28:31], v[4:7], v[146:161]
	s_waitcnt lgkmcnt(3)
	v_mfma_f32_32x32x16_bf16 v[98:113], v[24:27], v[8:11], v[98:113]
	global_load_dwordx4 v[48:51], v[248:249], off offset:384
	global_load_dwordx4 v[52:55], v[250:251], off offset:384
	v_mfma_f32_32x32x16_bf16 v[162:177], v[28:31], v[8:11], v[162:177]
	s_waitcnt lgkmcnt(0)
	v_mfma_f32_32x32x16_bf16 v[114:129], v[24:27], v[12:15], v[114:129]
	v_mfma_f32_32x32x16_bf16 v[178:193], v[28:31], v[12:15], v[178:193]
	s_waitcnt lgkmcnt(0)
	s_barrier
; #define G_LOAD(S, kt_) do { G_LD1(S##a0, S##b0, 0, kt_); G_LD1(S##a1, S##b1, 1, kt_); G_LD1(S##a2, S##b2, 2, kt_); G_LD1(S##a3, S##b3, 3, kt_); } while (0)
; #define G_STORE(S, buf_) do { G_ST1(S##a0, S##b0, 0, buf_); G_ST1(S##a1, S##b1, 1, buf_); G_ST1(S##a2, S##b2, 2, buf_); G_ST1(S##a3, S##b3, 3, buf_); } while (0)
; template <class AL, class BL>
; DI void gemm_core(AL al, BL bl, int m0, int n0, int K, char* smem, f32x16 (&acc)[2][2]) {
;     ...
;   G_LOAD(x, 0);
;   G_STORE(x, 0);
;   G_LOAD(x, 1);
;   G_LOAD(y, (nk > 2) ? 2 : 1);
;   __syncthreads();
;   for (int kt = 0; kt < nk; kt += 2) {
;     G_TILE(0, x, true, (kt + 3 < nk), kt + 3);
;     __syncthreads();
;     G_TILE(1, y, (kt + 2 < nk), (kt + 4 < nk), kt + 4);
;     __syncthreads();
	ds_read_b128 v[0:3], v57 offset:0
	ds_read_b128 v[4:7], v57 offset:2560
	ds_read_b128 v[8:11], v57 offset:5120
	ds_read_b128 v[12:15], v57 offset:7680
	ds_read_b128 v[16:19], v56 offset:0
	ds_read_b128 v[20:23], v56 offset:2560
	ds_read_b128 v[24:27], v56 offset:32
	ds_read_b128 v[28:31], v56 offset:2592
	s_waitcnt lgkmcnt(2)
	v_mfma_f32_32x32x16_bf16 v[66:81], v[16:19], v[0:3], v[66:81]
	v_mfma_f32_32x32x16_bf16 v[130:145], v[20:23], v[0:3], v[130:145]
	ds_read_b128 v[0:3], v57 offset:32
	s_waitcnt vmcnt(6)
	ds_write_b128 v58, v[214:217] offset:30720
	ds_write_b128 v58, v[218:221] offset:35840
	v_mfma_f32_32x32x16_bf16 v[82:97], v[16:19], v[4:7], v[82:97]
	v_mfma_f32_32x32x16_bf16 v[146:161], v[20:23], v[4:7], v[146:161]
	ds_read_b128 v[4:7], v57 offset:2592
	ds_write_b128 v58, v[222:225] offset:40960
	ds_write_b128 v58, v[228:231] offset:46080
	v_mfma_f32_32x32x16_bf16 v[98:113], v[16:19], v[8:11], v[98:113]
	v_mfma_f32_32x32x16_bf16 v[162:177], v[20:23], v[8:11], v[162:177]
	ds_read_b128 v[8:11], v57 offset:5152
	ds_write_b128 v58, v[232:235] offset:51200
	ds_write_b128 v58, v[236:239] offset:56320
	v_mfma_f32_32x32x16_bf16 v[114:129], v[16:19], v[12:15], v[114:129]
	v_mfma_f32_32x32x16_bf16 v[178:193], v[20:23], v[12:15], v[178:193]
	ds_read_b128 v[12:15], v57 offset:7712
	s_waitcnt lgkmcnt(9)
	v_mfma_f32_32x32x16_bf16 v[66:81], v[24:27], v[0:3], v[66:81]
	global_load_dwordx4 v[214:217], v[240:241], off offset:2496
	global_load_dwordx4 v[218:221], v[242:243], off offset:2496
	v_mfma_f32_32x32x16_bf16 v[130:145], v[28:31], v[0:3], v[130:145]
	s_waitcnt lgkmcnt(6)
	v_mfma_f32_32x32x16_bf16 v[82:97], v[24:27], v[4:7], v[82:97]
	global_load_dwordx4 v[222:225], v[244:245], off offset:448
	global_load_dwordx4 v[228:231], v[246:247], off offset:448
	v_mfma_f32_32x32x16_bf16 v[146:161], v[28:31], v[4:7], v[146:161]
	s_waitcnt lgkmcnt(3)
	v_mfma_f32_32x32x16_bf16 v[98:113], v[24:27], v[8:11], v[98:113]
	global_load_dwordx4 v[232:235], v[248:249], off offset:448
	global_load_dwordx4 v[236:239], v[250:251], off offset:448
	v_mfma_f32_32x32x16_bf16 v[162:177], v[28:31], v[8:11], v[162:177]
	s_waitcnt lgkmcnt(0)
	v_mfma_f32_32x32x16_bf16 v[114:129], v[24:27], v[12:15], v[114:129]
	v_mfma_f32_32x32x16_bf16 v[178:193], v[28:31], v[12:15], v[178:193]
	s_waitcnt lgkmcnt(0)
	s_barrier
	ds_read_b128 v[0:3], v57 offset:30720
	ds_read_b128 v[4:7], v57 offset:33280
	ds_read_b128 v[8:11], v57 offset:35840
	ds_read_b128 v[12:15], v57 offset:38400
	ds_read_b128 v[16:19], v56 offset:30720
	ds_read_b128 v[20:23], v56 offset:33280
	ds_read_b128 v[24:27], v56 offset:30752
	ds_read_b128 v[28:31], v56 offset:33312
	s_waitcnt lgkmcnt(2)
	v_mfma_f32_32x32x16_bf16 v[66:81], v[16:19], v[0:3], v[66:81]
	v_mfma_f32_32x32x16_bf16 v[130:145], v[20:23], v[0:3], v[130:145]
	ds_read_b128 v[0:3], v57 offset:30752
	s_waitcnt vmcnt(6)
	ds_write_b128 v58, v[32:35] offset:0
	ds_write_b128 v58, v[36:39] offset:5120
	v_mfma_f32_32x32x16_bf16 v[82:97], v[16:19], v[4:7], v[82:97]
	v_mfma_f32_32x32x16_bf16 v[146:161], v[20:23], v[4:7], v[146:161]
	ds_read_b128 v[4:7], v57 offset:33312
	ds_write_b128 v58, v[40:43] offset:10240
	ds_write_b128 v58, v[44:47] offset:15360
	v_mfma_f32_32x32x16_bf16 v[98:113], v[16:19], v[8:11], v[98:113]
	v_mfma_f32_32x32x16_bf16 v[162:177], v[20:23], v[8:11], v[162:177]
	ds_read_b128 v[8:11], v57 offset:35872
	ds_write_b128 v58, v[48:51] offset:20480
	ds_write_b128 v58, v[52:55] offset:25600
	v_mfma_f32_32x32x16_bf16 v[114:129], v[16:19], v[12:15], v[114:129]
	v_mfma_f32_32x32x16_bf16 v[178:193], v[20:23], v[12:15], v[178:193]
	ds_read_b128 v[12:15], v57 offset:38432
	s_waitcnt lgkmcnt(9)
	v_mfma_f32_32x32x16_bf16 v[66:81], v[24:27], v[0:3], v[66:81]
	global_load_dwordx4 v[32:35], v[240:241], off offset:2560
	global_load_dwordx4 v[36:39], v[242:243], off offset:2560
	v_mfma_f32_32x32x16_bf16 v[130:145], v[28:31], v[0:3], v[130:145]
	s_waitcnt lgkmcnt(6)
	v_mfma_f32_32x32x16_bf16 v[82:97], v[24:27], v[4:7], v[82:97]
	global_load_dwordx4 v[40:43], v[244:245], off offset:512
	global_load_dwordx4 v[44:47], v[246:247], off offset:512
	v_mfma_f32_32x32x16_bf16 v[146:161], v[28:31], v[4:7], v[146:161]
	s_waitcnt lgkmcnt(3)
	v_mfma_f32_32x32x16_bf16 v[98:113], v[24:27], v[8:11], v[98:113]
	global_load_dwordx4 v[48:51], v[248:249], off offset:512
	global_load_dwordx4 v[52:55], v[250:251], off offset:512
	v_mfma_f32_32x32x16_bf16 v[162:177], v[28:31], v[8:11], v[162:177]
	s_waitcnt lgkmcnt(0)
	v_mfma_f32_32x32x16_bf16 v[114:129], v[24:27], v[12:15], v[114:129]
	v_mfma_f32_32x32x16_bf16 v[178:193], v[28:31], v[12:15], v[178:193]
	s_waitcnt lgkmcnt(0)
	s_barrier
; #define G_LOAD(S, kt_) do { G_LD1(S##a0, S##b0, 0, kt_); G_LD1(S##a1, S##b1, 1, kt_); G_LD1(S##a2, S##b2, 2, kt_); G_LD1(S##a3, S##b3, 3, kt_); } while (0)
; #define G_STORE(S, buf_) do { G_ST1(S##a0, S##b0, 0, buf_); G_ST1(S##a1, S##b1, 1, buf_); G_ST1(S##a2, S##b2, 2, buf_); G_ST1(S##a3, S##b3, 3, buf_); } while (0)
; template <class AL, class BL>
; DI void gemm_core(AL al, BL bl, int m0, int n0, int K, char* smem, f32x16 (&acc)[2][2]) {
;     ...
;   G_LOAD(x, 0);
;   G_STORE(x, 0);
;   G_LOAD(x, 1);
;   G_LOAD(y, (nk > 2) ? 2 : 1);
;   __syncthreads();
;   for (int kt = 0; kt < nk; kt += 2) {
;     G_TILE(0, x, true, (kt + 3 < nk), kt + 3);
;     __syncthreads();
;     G_TILE(1, y, (kt + 2 < nk), (kt + 4 < nk), kt + 4);
;     __syncthreads();
	ds_read_b128 v[0:3], v57 offset:0
	ds_read_b128 v[4:7], v57 offset:2560
	ds_read_b128 v[8:11], v57 offset:5120
	ds_read_b128 v[12:15], v57 offset:7680
	ds_read_b128 v[16:19], v56 offset:0
	ds_read_b128 v[20:23], v56 offset:2560
	ds_read_b128 v[24:27], v56 offset:32
	ds_read_b128 v[28:31], v56 offset:2592
	s_waitcnt lgkmcnt(2)
	v_mfma_f32_32x32x16_bf16 v[66:81], v[16:19], v[0:3], v[66:81]
	v_mfma_f32_32x32x16_bf16 v[130:145], v[20:23], v[0:3], v[130:145]
	ds_read_b128 v[0:3], v57 offset:32
	s_waitcnt vmcnt(6)
	ds_write_b128 v58, v[214:217] offset:30720
	ds_write_b128 v58, v[218:221] offset:35840
	v_mfma_f32_32x32x16_bf16 v[82:97], v[16:19], v[4:7], v[82:97]
	v_mfma_f32_32x32x16_bf16 v[146:161], v[20:23], v[4:7], v[146:161]
	ds_read_b128 v[4:7], v57 offset:2592
	ds_write_b128 v58, v[222:225] offset:40960
	ds_write_b128 v58, v[228:231] offset:46080
	v_mfma_f32_32x32x16_bf16 v[98:113], v[16:19], v[8:11], v[98:113]
	v_mfma_f32_32x32x16_bf16 v[162:177], v[20:23], v[8:11], v[162:177]
	ds_read_b128 v[8:11], v57 offset:5152
	ds_write_b128 v58, v[232:235] offset:51200
	ds_write_b128 v58, v[236:239] offset:56320
	v_mfma_f32_32x32x16_bf16 v[114:129], v[16:19], v[12:15], v[114:129]
	v_mfma_f32_32x32x16_bf16 v[178:193], v[20:23], v[12:15], v[178:193]
	ds_read_b128 v[12:15], v57 offset:7712
	s_waitcnt lgkmcnt(9)
	v_mfma_f32_32x32x16_bf16 v[66:81], v[24:27], v[0:3], v[66:81]
	global_load_dwordx4 v[214:217], v[240:241], off offset:2624
	global_load_dwordx4 v[218:221], v[242:243], off offset:2624
	v_mfma_f32_32x32x16_bf16 v[130:145], v[28:31], v[0:3], v[130:145]
	s_waitcnt lgkmcnt(6)
	v_mfma_f32_32x32x16_bf16 v[82:97], v[24:27], v[4:7], v[82:97]
	global_load_dwordx4 v[222:225], v[244:245], off offset:576
	global_load_dwordx4 v[228:231], v[246:247], off offset:576
	v_mfma_f32_32x32x16_bf16 v[146:161], v[28:31], v[4:7], v[146:161]
	s_waitcnt lgkmcnt(3)
	v_mfma_f32_32x32x16_bf16 v[98:113], v[24:27], v[8:11], v[98:113]
	global_load_dwordx4 v[232:235], v[248:249], off offset:576
	global_load_dwordx4 v[236:239], v[250:251], off offset:576
	v_mfma_f32_32x32x16_bf16 v[162:177], v[28:31], v[8:11], v[162:177]
	s_waitcnt lgkmcnt(0)
	v_mfma_f32_32x32x16_bf16 v[114:129], v[24:27], v[12:15], v[114:129]
	v_mfma_f32_32x32x16_bf16 v[178:193], v[28:31], v[12:15], v[178:193]
	s_waitcnt lgkmcnt(0)
	s_barrier
	ds_read_b128 v[0:3], v57 offset:30720
	ds_read_b128 v[4:7], v57 offset:33280
	ds_read_b128 v[8:11], v57 offset:35840
	ds_read_b128 v[12:15], v57 offset:38400
	ds_read_b128 v[16:19], v56 offset:30720
	ds_read_b128 v[20:23], v56 offset:33280
	ds_read_b128 v[24:27], v56 offset:30752
	ds_read_b128 v[28:31], v56 offset:33312
	s_waitcnt lgkmcnt(2)
	v_mfma_f32_32x32x16_bf16 v[66:81], v[16:19], v[0:3], v[66:81]
	v_mfma_f32_32x32x16_bf16 v[130:145], v[20:23], v[0:3], v[130:145]
	ds_read_b128 v[0:3], v57 offset:30752
	s_waitcnt vmcnt(6)
	ds_write_b128 v58, v[32:35] offset:0
	ds_write_b128 v58, v[36:39] offset:5120
	v_mfma_f32_32x32x16_bf16 v[82:97], v[16:19], v[4:7], v[82:97]
	v_mfma_f32_32x32x16_bf16 v[146:161], v[20:23], v[4:7], v[146:161]
	ds_read_b128 v[4:7], v57 offset:33312
	ds_write_b128 v58, v[40:43] offset:10240
	ds_write_b128 v58, v[44:47] offset:15360
	v_mfma_f32_32x32x16_bf16 v[98:113], v[16:19], v[8:11], v[98:113]
	v_mfma_f32_32x32x16_bf16 v[162:177], v[20:23], v[8:11], v[162:177]
	ds_read_b128 v[8:11], v57 offset:35872
	ds_write_b128 v58, v[48:51] offset:20480
	ds_write_b128 v58, v[52:55] offset:25600
	v_mfma_f32_32x32x16_bf16 v[114:129], v[16:19], v[12:15], v[114:129]
	v_mfma_f32_32x32x16_bf16 v[178:193], v[20:23], v[12:15], v[178:193]
	ds_read_b128 v[12:15], v57 offset:38432
	s_waitcnt lgkmcnt(9)
	v_mfma_f32_32x32x16_bf16 v[66:81], v[24:27], v[0:3], v[66:81]
	global_load_dwordx4 v[32:35], v[240:241], off offset:2688
	global_load_dwordx4 v[36:39], v[242:243], off offset:2688
	v_mfma_f32_32x32x16_bf16 v[130:145], v[28:31], v[0:3], v[130:145]
	s_waitcnt lgkmcnt(6)
	v_mfma_f32_32x32x16_bf16 v[82:97], v[24:27], v[4:7], v[82:97]
	global_load_dwordx4 v[40:43], v[244:245], off offset:640
	global_load_dwordx4 v[44:47], v[246:247], off offset:640
	v_mfma_f32_32x32x16_bf16 v[146:161], v[28:31], v[4:7], v[146:161]
	s_waitcnt lgkmcnt(3)
	v_mfma_f32_32x32x16_bf16 v[98:113], v[24:27], v[8:11], v[98:113]
	global_load_dwordx4 v[48:51], v[248:249], off offset:640
	global_load_dwordx4 v[52:55], v[250:251], off offset:640
	v_mfma_f32_32x32x16_bf16 v[162:177], v[28:31], v[8:11], v[162:177]
	s_waitcnt lgkmcnt(0)
	v_mfma_f32_32x32x16_bf16 v[114:129], v[24:27], v[12:15], v[114:129]
	v_mfma_f32_32x32x16_bf16 v[178:193], v[28:31], v[12:15], v[178:193]
	s_waitcnt lgkmcnt(0)
	s_barrier
; #define G_LOAD(S, kt_) do { G_LD1(S##a0, S##b0, 0, kt_); G_LD1(S##a1, S##b1, 1, kt_); G_LD1(S##a2, S##b2, 2, kt_); G_LD1(S##a3, S##b3, 3, kt_); } while (0)
; #define G_STORE(S, buf_) do { G_ST1(S##a0, S##b0, 0, buf_); G_ST1(S##a1, S##b1, 1, buf_); G_ST1(S##a2, S##b2, 2, buf_); G_ST1(S##a3, S##b3, 3, buf_); } while (0)
; template <class AL, class BL>
; DI void gemm_core(AL al, BL bl, int m0, int n0, int K, char* smem, f32x16 (&acc)[2][2]) {
;     ...
;   G_LOAD(x, 0);
;   G_STORE(x, 0);
;   G_LOAD(x, 1);
;   G_LOAD(y, (nk > 2) ? 2 : 1);
;   __syncthreads();
;   for (int kt = 0; kt < nk; kt += 2) {
;     G_TILE(0, x, true, (kt + 3 < nk), kt + 3);
;     __syncthreads();
;     G_TILE(1, y, (kt + 2 < nk), (kt + 4 < nk), kt + 4);
;     __syncthreads();
	ds_read_b128 v[0:3], v57 offset:0
	ds_read_b128 v[4:7], v57 offset:2560
	ds_read_b128 v[8:11], v57 offset:5120
	ds_read_b128 v[12:15], v57 offset:7680
	ds_read_b128 v[16:19], v56 offset:0
	ds_read_b128 v[20:23], v56 offset:2560
	ds_read_b128 v[24:27], v56 offset:32
	ds_read_b128 v[28:31], v56 offset:2592
	s_waitcnt lgkmcnt(2)
	v_mfma_f32_32x32x16_bf16 v[66:81], v[16:19], v[0:3], v[66:81]
	v_mfma_f32_32x32x16_bf16 v[130:145], v[20:23], v[0:3], v[130:145]
	ds_read_b128 v[0:3], v57 offset:32
	s_waitcnt vmcnt(6)
	ds_write_b128 v58, v[214:217] offset:30720
	ds_write_b128 v58, v[218:221] offset:35840
	v_mfma_f32_32x32x16_bf16 v[82:97], v[16:19], v[4:7], v[82:97]
	v_mfma_f32_32x32x16_bf16 v[146:161], v[20:23], v[4:7], v[146:161]
	ds_read_b128 v[4:7], v57 offset:2592
	ds_write_b128 v58, v[222:225] offset:40960
	ds_write_b128 v58, v[228:231] offset:46080
	v_mfma_f32_32x32x16_bf16 v[98:113], v[16:19], v[8:11], v[98:113]
	v_mfma_f32_32x32x16_bf16 v[162:177], v[20:23], v[8:11], v[162:177]
	ds_read_b128 v[8:11], v57 offset:5152
	ds_write_b128 v58, v[232:235] offset:51200
	ds_write_b128 v58, v[236:239] offset:56320
	v_mfma_f32_32x32x16_bf16 v[114:129], v[16:19], v[12:15], v[114:129]
	v_mfma_f32_32x32x16_bf16 v[178:193], v[20:23], v[12:15], v[178:193]
	ds_read_b128 v[12:15], v57 offset:7712
	s_waitcnt lgkmcnt(9)
	v_mfma_f32_32x32x16_bf16 v[66:81], v[24:27], v[0:3], v[66:81]
	global_load_dwordx4 v[214:217], v[240:241], off offset:2752
	global_load_dwordx4 v[218:221], v[242:243], off offset:2752
	v_mfma_f32_32x32x16_bf16 v[130:145], v[28:31], v[0:3], v[130:145]
	s_waitcnt lgkmcnt(6)
	v_mfma_f32_32x32x16_bf16 v[82:97], v[24:27], v[4:7], v[82:97]
	global_load_dwordx4 v[222:225], v[244:245], off offset:704
	global_load_dwordx4 v[228:231], v[246:247], off offset:704
	v_mfma_f32_32x32x16_bf16 v[146:161], v[28:31], v[4:7], v[146:161]
	s_waitcnt lgkmcnt(3)
	v_mfma_f32_32x32x16_bf16 v[98:113], v[24:27], v[8:11], v[98:113]
	global_load_dwordx4 v[232:235], v[248:249], off offset:704
	global_load_dwordx4 v[236:239], v[250:251], off offset:704
	v_mfma_f32_32x32x16_bf16 v[162:177], v[28:31], v[8:11], v[162:177]
	s_waitcnt lgkmcnt(0)
	v_mfma_f32_32x32x16_bf16 v[114:129], v[24:27], v[12:15], v[114:129]
	v_mfma_f32_32x32x16_bf16 v[178:193], v[28:31], v[12:15], v[178:193]
	s_waitcnt lgkmcnt(0)
	s_barrier
	ds_read_b128 v[0:3], v57 offset:30720
	ds_read_b128 v[4:7], v57 offset:33280
	ds_read_b128 v[8:11], v57 offset:35840
	ds_read_b128 v[12:15], v57 offset:38400
	ds_read_b128 v[16:19], v56 offset:30720
	ds_read_b128 v[20:23], v56 offset:33280
	ds_read_b128 v[24:27], v56 offset:30752
	ds_read_b128 v[28:31], v56 offset:33312
	s_waitcnt lgkmcnt(2)
	v_mfma_f32_32x32x16_bf16 v[66:81], v[16:19], v[0:3], v[66:81]
	v_mfma_f32_32x32x16_bf16 v[130:145], v[20:23], v[0:3], v[130:145]
	ds_read_b128 v[0:3], v57 offset:30752
	s_waitcnt vmcnt(6)
	ds_write_b128 v58, v[32:35] offset:0
	ds_write_b128 v58, v[36:39] offset:5120
	v_mfma_f32_32x32x16_bf16 v[82:97], v[16:19], v[4:7], v[82:97]
	v_mfma_f32_32x32x16_bf16 v[146:161], v[20:23], v[4:7], v[146:161]
	ds_read_b128 v[4:7], v57 offset:33312
	ds_write_b128 v58, v[40:43] offset:10240
	ds_write_b128 v58, v[44:47] offset:15360
	v_mfma_f32_32x32x16_bf16 v[98:113], v[16:19], v[8:11], v[98:113]
	v_mfma_f32_32x32x16_bf16 v[162:177], v[20:23], v[8:11], v[162:177]
	ds_read_b128 v[8:11], v57 offset:35872
	ds_write_b128 v58, v[48:51] offset:20480
	ds_write_b128 v58, v[52:55] offset:25600
	v_mfma_f32_32x32x16_bf16 v[114:129], v[16:19], v[12:15], v[114:129]
	v_mfma_f32_32x32x16_bf16 v[178:193], v[20:23], v[12:15], v[178:193]
	ds_read_b128 v[12:15], v57 offset:38432
	s_waitcnt lgkmcnt(9)
	v_mfma_f32_32x32x16_bf16 v[66:81], v[24:27], v[0:3], v[66:81]
	global_load_dwordx4 v[32:35], v[240:241], off offset:2816
	global_load_dwordx4 v[36:39], v[242:243], off offset:2816
	v_mfma_f32_32x32x16_bf16 v[130:145], v[28:31], v[0:3], v[130:145]
	s_waitcnt lgkmcnt(6)
	v_mfma_f32_32x32x16_bf16 v[82:97], v[24:27], v[4:7], v[82:97]
	global_load_dwordx4 v[40:43], v[244:245], off offset:768
	global_load_dwordx4 v[44:47], v[246:247], off offset:768
	v_mfma_f32_32x32x16_bf16 v[146:161], v[28:31], v[4:7], v[146:161]
	s_waitcnt lgkmcnt(3)
	v_mfma_f32_32x32x16_bf16 v[98:113], v[24:27], v[8:11], v[98:113]
	global_load_dwordx4 v[48:51], v[248:249], off offset:768
	global_load_dwordx4 v[52:55], v[250:251], off offset:768
	v_mfma_f32_32x32x16_bf16 v[162:177], v[28:31], v[8:11], v[162:177]
	s_waitcnt lgkmcnt(0)
	v_mfma_f32_32x32x16_bf16 v[114:129], v[24:27], v[12:15], v[114:129]
	v_mfma_f32_32x32x16_bf16 v[178:193], v[28:31], v[12:15], v[178:193]
	s_waitcnt lgkmcnt(0)
	s_barrier
; #define G_LOAD(S, kt_) do { G_LD1(S##a0, S##b0, 0, kt_); G_LD1(S##a1, S##b1, 1, kt_); G_LD1(S##a2, S##b2, 2, kt_); G_LD1(S##a3, S##b3, 3, kt_); } while (0)
; #define G_STORE(S, buf_) do { G_ST1(S##a0, S##b0, 0, buf_); G_ST1(S##a1, S##b1, 1, buf_); G_ST1(S##a2, S##b2, 2, buf_); G_ST1(S##a3, S##b3, 3, buf_); } while (0)
; template <class AL, class BL>
; DI void gemm_core(AL al, BL bl, int m0, int n0, int K, char* smem, f32x16 (&acc)[2][2]) {
;     ...
;   G_LOAD(x, 0);
;   G_STORE(x, 0);
;   G_LOAD(x, 1);
;   G_LOAD(y, (nk > 2) ? 2 : 1);
;   __syncthreads();
;   for (int kt = 0; kt < nk; kt += 2) {
;     G_TILE(0, x, true, (kt + 3 < nk), kt + 3);
;     __syncthreads();
;     G_TILE(1, y, (kt + 2 < nk), (kt + 4 < nk), kt + 4);
;     __syncthreads();
	ds_read_b128 v[0:3], v57 offset:0
	ds_read_b128 v[4:7], v57 offset:2560
	ds_read_b128 v[8:11], v57 offset:5120
	ds_read_b128 v[12:15], v57 offset:7680
	ds_read_b128 v[16:19], v56 offset:0
	ds_read_b128 v[20:23], v56 offset:2560
	ds_read_b128 v[24:27], v56 offset:32
	ds_read_b128 v[28:31], v56 offset:2592
	s_waitcnt lgkmcnt(2)
	v_mfma_f32_32x32x16_bf16 v[66:81], v[16:19], v[0:3], v[66:81]
	v_mfma_f32_32x32x16_bf16 v[130:145], v[20:23], v[0:3], v[130:145]
	ds_read_b128 v[0:3], v57 offset:32
	s_waitcnt vmcnt(6)
	ds_write_b128 v58, v[214:217] offset:30720
	ds_write_b128 v58, v[218:221] offset:35840
	v_mfma_f32_32x32x16_bf16 v[82:97], v[16:19], v[4:7], v[82:97]
	v_mfma_f32_32x32x16_bf16 v[146:161], v[20:23], v[4:7], v[146:161]
	ds_read_b128 v[4:7], v57 offset:2592
	ds_write_b128 v58, v[222:225] offset:40960
	ds_write_b128 v58, v[228:231] offset:46080
	v_mfma_f32_32x32x16_bf16 v[98:113], v[16:19], v[8:11], v[98:113]
	v_mfma_f32_32x32x16_bf16 v[162:177], v[20:23], v[8:11], v[162:177]
	ds_read_b128 v[8:11], v57 offset:5152
	ds_write_b128 v58, v[232:235] offset:51200
	ds_write_b128 v58, v[236:239] offset:56320
	v_mfma_f32_32x32x16_bf16 v[114:129], v[16:19], v[12:15], v[114:129]
	v_mfma_f32_32x32x16_bf16 v[178:193], v[20:23], v[12:15], v[178:193]
	ds_read_b128 v[12:15], v57 offset:7712
	s_waitcnt lgkmcnt(9)
	v_mfma_f32_32x32x16_bf16 v[66:81], v[24:27], v[0:3], v[66:81]
	global_load_dwordx4 v[214:217], v[240:241], off offset:2880
	global_load_dwordx4 v[218:221], v[242:243], off offset:2880
	v_mfma_f32_32x32x16_bf16 v[130:145], v[28:31], v[0:3], v[130:145]
	s_waitcnt lgkmcnt(6)
	v_mfma_f32_32x32x16_bf16 v[82:97], v[24:27], v[4:7], v[82:97]
	global_load_dwordx4 v[222:225], v[244:245], off offset:832
	global_load_dwordx4 v[228:231], v[246:247], off offset:832
	v_mfma_f32_32x32x16_bf16 v[146:161], v[28:31], v[4:7], v[146:161]
	s_waitcnt lgkmcnt(3)
	v_mfma_f32_32x32x16_bf16 v[98:113], v[24:27], v[8:11], v[98:113]
	global_load_dwordx4 v[232:235], v[248:249], off offset:832
	global_load_dwordx4 v[236:239], v[250:251], off offset:832
	v_mfma_f32_32x32x16_bf16 v[162:177], v[28:31], v[8:11], v[162:177]
	s_waitcnt lgkmcnt(0)
	v_mfma_f32_32x32x16_bf16 v[114:129], v[24:27], v[12:15], v[114:129]
	v_mfma_f32_32x32x16_bf16 v[178:193], v[28:31], v[12:15], v[178:193]
	s_waitcnt lgkmcnt(0)
	s_barrier
	ds_read_b128 v[0:3], v57 offset:30720
	ds_read_b128 v[4:7], v57 offset:33280
	ds_read_b128 v[8:11], v57 offset:35840
	ds_read_b128 v[12:15], v57 offset:38400
	ds_read_b128 v[16:19], v56 offset:30720
	ds_read_b128 v[20:23], v56 offset:33280
	ds_read_b128 v[24:27], v56 offset:30752
	ds_read_b128 v[28:31], v56 offset:33312
	s_waitcnt lgkmcnt(2)
	v_mfma_f32_32x32x16_bf16 v[66:81], v[16:19], v[0:3], v[66:81]
	v_mfma_f32_32x32x16_bf16 v[130:145], v[20:23], v[0:3], v[130:145]
	ds_read_b128 v[0:3], v57 offset:30752
	s_waitcnt vmcnt(6)
	ds_write_b128 v58, v[32:35] offset:0
	ds_write_b128 v58, v[36:39] offset:5120
	v_mfma_f32_32x32x16_bf16 v[82:97], v[16:19], v[4:7], v[82:97]
	v_mfma_f32_32x32x16_bf16 v[146:161], v[20:23], v[4:7], v[146:161]
	ds_read_b128 v[4:7], v57 offset:33312
	ds_write_b128 v58, v[40:43] offset:10240
	ds_write_b128 v58, v[44:47] offset:15360
	v_mfma_f32_32x32x16_bf16 v[98:113], v[16:19], v[8:11], v[98:113]
	v_mfma_f32_32x32x16_bf16 v[162:177], v[20:23], v[8:11], v[162:177]
	ds_read_b128 v[8:11], v57 offset:35872
	ds_write_b128 v58, v[48:51] offset:20480
	ds_write_b128 v58, v[52:55] offset:25600
	v_mfma_f32_32x32x16_bf16 v[114:129], v[16:19], v[12:15], v[114:129]
	v_mfma_f32_32x32x16_bf16 v[178:193], v[20:23], v[12:15], v[178:193]
	ds_read_b128 v[12:15], v57 offset:38432
	s_waitcnt lgkmcnt(9)
	v_mfma_f32_32x32x16_bf16 v[66:81], v[24:27], v[0:3], v[66:81]
	global_load_dwordx4 v[32:35], v[240:241], off offset:2944
	global_load_dwordx4 v[36:39], v[242:243], off offset:2944
	v_mfma_f32_32x32x16_bf16 v[130:145], v[28:31], v[0:3], v[130:145]
	s_waitcnt lgkmcnt(6)
	v_mfma_f32_32x32x16_bf16 v[82:97], v[24:27], v[4:7], v[82:97]
	global_load_dwordx4 v[40:43], v[244:245], off offset:896
	global_load_dwordx4 v[44:47], v[246:247], off offset:896
	v_mfma_f32_32x32x16_bf16 v[146:161], v[28:31], v[4:7], v[146:161]
	s_waitcnt lgkmcnt(3)
	v_mfma_f32_32x32x16_bf16 v[98:113], v[24:27], v[8:11], v[98:113]
	global_load_dwordx4 v[48:51], v[248:249], off offset:896
	global_load_dwordx4 v[52:55], v[250:251], off offset:896
	v_mfma_f32_32x32x16_bf16 v[162:177], v[28:31], v[8:11], v[162:177]
	s_waitcnt lgkmcnt(0)
	v_mfma_f32_32x32x16_bf16 v[114:129], v[24:27], v[12:15], v[114:129]
	v_mfma_f32_32x32x16_bf16 v[178:193], v[28:31], v[12:15], v[178:193]
	s_waitcnt lgkmcnt(0)
	s_barrier
; #define G_LOAD(S, kt_) do { G_LD1(S##a0, S##b0, 0, kt_); G_LD1(S##a1, S##b1, 1, kt_); G_LD1(S##a2, S##b2, 2, kt_); G_LD1(S##a3, S##b3, 3, kt_); } while (0)
; #define G_STORE(S, buf_) do { G_ST1(S##a0, S##b0, 0, buf_); G_ST1(S##a1, S##b1, 1, buf_); G_ST1(S##a2, S##b2, 2, buf_); G_ST1(S##a3, S##b3, 3, buf_); } while (0)
; template <class AL, class BL>
; DI void gemm_core(AL al, BL bl, int m0, int n0, int K, char* smem, f32x16 (&acc)[2][2]) {
;     ...
;   G_LOAD(x, 0);
;   G_STORE(x, 0);
;   G_LOAD(x, 1);
;   G_LOAD(y, (nk > 2) ? 2 : 1);
;   __syncthreads();
;   for (int kt = 0; kt < nk; kt += 2) {
;     G_TILE(0, x, true, (kt + 3 < nk), kt + 3);
;     __syncthreads();
;     G_TILE(1, y, (kt + 2 < nk), (kt + 4 < nk), kt + 4);
;     __syncthreads();
	ds_read_b128 v[0:3], v57 offset:0
	ds_read_b128 v[4:7], v57 offset:2560
	ds_read_b128 v[8:11], v57 offset:5120
	ds_read_b128 v[12:15], v57 offset:7680
	ds_read_b128 v[16:19], v56 offset:0
	ds_read_b128 v[20:23], v56 offset:2560
	ds_read_b128 v[24:27], v56 offset:32
	ds_read_b128 v[28:31], v56 offset:2592
	s_waitcnt lgkmcnt(2)
	v_mfma_f32_32x32x16_bf16 v[66:81], v[16:19], v[0:3], v[66:81]
	v_mfma_f32_32x32x16_bf16 v[130:145], v[20:23], v[0:3], v[130:145]
	ds_read_b128 v[0:3], v57 offset:32
	s_waitcnt vmcnt(6)
	ds_write_b128 v58, v[214:217] offset:30720
	ds_write_b128 v58, v[218:221] offset:35840
	v_mfma_f32_32x32x16_bf16 v[82:97], v[16:19], v[4:7], v[82:97]
	v_mfma_f32_32x32x16_bf16 v[146:161], v[20:23], v[4:7], v[146:161]
	ds_read_b128 v[4:7], v57 offset:2592
	ds_write_b128 v58, v[222:225] offset:40960
	ds_write_b128 v58, v[228:231] offset:46080
	v_mfma_f32_32x32x16_bf16 v[98:113], v[16:19], v[8:11], v[98:113]
	v_mfma_f32_32x32x16_bf16 v[162:177], v[20:23], v[8:11], v[162:177]
	ds_read_b128 v[8:11], v57 offset:5152
	ds_write_b128 v58, v[232:235] offset:51200
	ds_write_b128 v58, v[236:239] offset:56320
	v_mfma_f32_32x32x16_bf16 v[114:129], v[16:19], v[12:15], v[114:129]
	v_mfma_f32_32x32x16_bf16 v[178:193], v[20:23], v[12:15], v[178:193]
	ds_read_b128 v[12:15], v57 offset:7712
	s_waitcnt lgkmcnt(9)
	v_mfma_f32_32x32x16_bf16 v[66:81], v[24:27], v[0:3], v[66:81]
	global_load_dwordx4 v[214:217], v[240:241], off offset:3008
	global_load_dwordx4 v[218:221], v[242:243], off offset:3008
	v_mfma_f32_32x32x16_bf16 v[130:145], v[28:31], v[0:3], v[130:145]
	s_waitcnt lgkmcnt(6)
	v_mfma_f32_32x32x16_bf16 v[82:97], v[24:27], v[4:7], v[82:97]
	global_load_dwordx4 v[222:225], v[244:245], off offset:960
	global_load_dwordx4 v[228:231], v[246:247], off offset:960
	v_mfma_f32_32x32x16_bf16 v[146:161], v[28:31], v[4:7], v[146:161]
	s_waitcnt lgkmcnt(3)
	v_mfma_f32_32x32x16_bf16 v[98:113], v[24:27], v[8:11], v[98:113]
	global_load_dwordx4 v[232:235], v[248:249], off offset:960
	global_load_dwordx4 v[236:239], v[250:251], off offset:960
	v_mfma_f32_32x32x16_bf16 v[162:177], v[28:31], v[8:11], v[162:177]
	s_waitcnt lgkmcnt(0)
	v_mfma_f32_32x32x16_bf16 v[114:129], v[24:27], v[12:15], v[114:129]
	v_mfma_f32_32x32x16_bf16 v[178:193], v[28:31], v[12:15], v[178:193]
	s_waitcnt lgkmcnt(0)
	s_barrier
	ds_read_b128 v[0:3], v57 offset:30720
	ds_read_b128 v[4:7], v57 offset:33280
	ds_read_b128 v[8:11], v57 offset:35840
	ds_read_b128 v[12:15], v57 offset:38400
	ds_read_b128 v[16:19], v56 offset:30720
	ds_read_b128 v[20:23], v56 offset:33280
	ds_read_b128 v[24:27], v56 offset:30752
	ds_read_b128 v[28:31], v56 offset:33312
	s_waitcnt lgkmcnt(2)
	v_mfma_f32_32x32x16_bf16 v[66:81], v[16:19], v[0:3], v[66:81]
	v_mfma_f32_32x32x16_bf16 v[130:145], v[20:23], v[0:3], v[130:145]
	ds_read_b128 v[0:3], v57 offset:30752
	s_waitcnt vmcnt(6)
	ds_write_b128 v58, v[32:35] offset:0
	ds_write_b128 v58, v[36:39] offset:5120
	v_mfma_f32_32x32x16_bf16 v[82:97], v[16:19], v[4:7], v[82:97]
	v_mfma_f32_32x32x16_bf16 v[146:161], v[20:23], v[4:7], v[146:161]
	ds_read_b128 v[4:7], v57 offset:33312
	ds_write_b128 v58, v[40:43] offset:10240
	ds_write_b128 v58, v[44:47] offset:15360
	v_mfma_f32_32x32x16_bf16 v[98:113], v[16:19], v[8:11], v[98:113]
	v_mfma_f32_32x32x16_bf16 v[162:177], v[20:23], v[8:11], v[162:177]
	ds_read_b128 v[8:11], v57 offset:35872
	ds_write_b128 v58, v[48:51] offset:20480
	ds_write_b128 v58, v[52:55] offset:25600
	v_mfma_f32_32x32x16_bf16 v[114:129], v[16:19], v[12:15], v[114:129]
	v_mfma_f32_32x32x16_bf16 v[178:193], v[20:23], v[12:15], v[178:193]
	ds_read_b128 v[12:15], v57 offset:38432
	s_waitcnt lgkmcnt(9)
	v_mfma_f32_32x32x16_bf16 v[66:81], v[24:27], v[0:3], v[66:81]
	global_load_dwordx4 v[32:35], v[240:241], off offset:3072
	global_load_dwordx4 v[36:39], v[242:243], off offset:3072
	v_mfma_f32_32x32x16_bf16 v[130:145], v[28:31], v[0:3], v[130:145]
	s_waitcnt lgkmcnt(6)
	v_mfma_f32_32x32x16_bf16 v[82:97], v[24:27], v[4:7], v[82:97]
	global_load_dwordx4 v[40:43], v[244:245], off offset:1024
	global_load_dwordx4 v[44:47], v[246:247], off offset:1024
	v_mfma_f32_32x32x16_bf16 v[146:161], v[28:31], v[4:7], v[146:161]
	s_waitcnt lgkmcnt(3)
	v_mfma_f32_32x32x16_bf16 v[98:113], v[24:27], v[8:11], v[98:113]
	global_load_dwordx4 v[48:51], v[248:249], off offset:1024
	global_load_dwordx4 v[52:55], v[250:251], off offset:1024
	v_mfma_f32_32x32x16_bf16 v[162:177], v[28:31], v[8:11], v[162:177]
	s_waitcnt lgkmcnt(0)
	v_mfma_f32_32x32x16_bf16 v[114:129], v[24:27], v[12:15], v[114:129]
	v_mfma_f32_32x32x16_bf16 v[178:193], v[28:31], v[12:15], v[178:193]
	s_waitcnt lgkmcnt(0)
	s_barrier
; #define G_LOAD(S, kt_) do { G_LD1(S##a0, S##b0, 0, kt_); G_LD1(S##a1, S##b1, 1, kt_); G_LD1(S##a2, S##b2, 2, kt_); G_LD1(S##a3, S##b3, 3, kt_); } while (0)
; #define G_STORE(S, buf_) do { G_ST1(S##a0, S##b0, 0, buf_); G_ST1(S##a1, S##b1, 1, buf_); G_ST1(S##a2, S##b2, 2, buf_); G_ST1(S##a3, S##b3, 3, buf_); } while (0)
; template <class AL, class BL>
; DI void gemm_core(AL al, BL bl, int m0, int n0, int K, char* smem, f32x16 (&acc)[2][2]) {
;     ...
;   G_LOAD(x, 0);
;   G_STORE(x, 0);
;   G_LOAD(x, 1);
;   G_LOAD(y, (nk > 2) ? 2 : 1);
;   __syncthreads();
;   for (int kt = 0; kt < nk; kt += 2) {
;     G_TILE(0, x, true, (kt + 3 < nk), kt + 3);
;     __syncthreads();
;     G_TILE(1, y, (kt + 2 < nk), (kt + 4 < nk), kt + 4);
;     __syncthreads();
	ds_read_b128 v[0:3], v57 offset:0
	ds_read_b128 v[4:7], v57 offset:2560
	ds_read_b128 v[8:11], v57 offset:5120
	ds_read_b128 v[12:15], v57 offset:7680
	ds_read_b128 v[16:19], v56 offset:0
	ds_read_b128 v[20:23], v56 offset:2560
	ds_read_b128 v[24:27], v56 offset:32
	ds_read_b128 v[28:31], v56 offset:2592
	s_waitcnt lgkmcnt(2)
	v_mfma_f32_32x32x16_bf16 v[66:81], v[16:19], v[0:3], v[66:81]
	v_mfma_f32_32x32x16_bf16 v[130:145], v[20:23], v[0:3], v[130:145]
	ds_read_b128 v[0:3], v57 offset:32
	s_waitcnt vmcnt(6)
	ds_write_b128 v58, v[214:217] offset:30720
	ds_write_b128 v58, v[218:221] offset:35840
	v_mfma_f32_32x32x16_bf16 v[82:97], v[16:19], v[4:7], v[82:97]
	v_mfma_f32_32x32x16_bf16 v[146:161], v[20:23], v[4:7], v[146:161]
	ds_read_b128 v[4:7], v57 offset:2592
	ds_write_b128 v58, v[222:225] offset:40960
	ds_write_b128 v58, v[228:231] offset:46080
	v_mfma_f32_32x32x16_bf16 v[98:113], v[16:19], v[8:11], v[98:113]
	v_mfma_f32_32x32x16_bf16 v[162:177], v[20:23], v[8:11], v[162:177]
	ds_read_b128 v[8:11], v57 offset:5152
	ds_write_b128 v58, v[232:235] offset:51200
	ds_write_b128 v58, v[236:239] offset:56320
	v_mfma_f32_32x32x16_bf16 v[114:129], v[16:19], v[12:15], v[114:129]
	v_mfma_f32_32x32x16_bf16 v[178:193], v[20:23], v[12:15], v[178:193]
	ds_read_b128 v[12:15], v57 offset:7712
	s_waitcnt lgkmcnt(9)
	v_mfma_f32_32x32x16_bf16 v[66:81], v[24:27], v[0:3], v[66:81]
	global_load_dwordx4 v[214:217], v[240:241], off offset:3136
	global_load_dwordx4 v[218:221], v[242:243], off offset:3136
	v_mfma_f32_32x32x16_bf16 v[130:145], v[28:31], v[0:3], v[130:145]
	s_waitcnt lgkmcnt(6)
	v_mfma_f32_32x32x16_bf16 v[82:97], v[24:27], v[4:7], v[82:97]
	global_load_dwordx4 v[222:225], v[244:245], off offset:1088
	global_load_dwordx4 v[228:231], v[246:247], off offset:1088
	v_mfma_f32_32x32x16_bf16 v[146:161], v[28:31], v[4:7], v[146:161]
	s_waitcnt lgkmcnt(3)
	v_mfma_f32_32x32x16_bf16 v[98:113], v[24:27], v[8:11], v[98:113]
	global_load_dwordx4 v[232:235], v[248:249], off offset:1088
	global_load_dwordx4 v[236:239], v[250:251], off offset:1088
	v_mfma_f32_32x32x16_bf16 v[162:177], v[28:31], v[8:11], v[162:177]
	s_waitcnt lgkmcnt(0)
	v_mfma_f32_32x32x16_bf16 v[114:129], v[24:27], v[12:15], v[114:129]
	v_mfma_f32_32x32x16_bf16 v[178:193], v[28:31], v[12:15], v[178:193]
	s_waitcnt lgkmcnt(0)
	s_barrier
	ds_read_b128 v[0:3], v57 offset:30720
	ds_read_b128 v[4:7], v57 offset:33280
	ds_read_b128 v[8:11], v57 offset:35840
	ds_read_b128 v[12:15], v57 offset:38400
	ds_read_b128 v[16:19], v56 offset:30720
	ds_read_b128 v[20:23], v56 offset:33280
	ds_read_b128 v[24:27], v56 offset:30752
	ds_read_b128 v[28:31], v56 offset:33312
	s_waitcnt lgkmcnt(2)
	v_mfma_f32_32x32x16_bf16 v[66:81], v[16:19], v[0:3], v[66:81]
	v_mfma_f32_32x32x16_bf16 v[130:145], v[20:23], v[0:3], v[130:145]
	ds_read_b128 v[0:3], v57 offset:30752
	s_waitcnt vmcnt(6)
	ds_write_b128 v58, v[32:35] offset:0
	ds_write_b128 v58, v[36:39] offset:5120
	v_mfma_f32_32x32x16_bf16 v[82:97], v[16:19], v[4:7], v[82:97]
	v_mfma_f32_32x32x16_bf16 v[146:161], v[20:23], v[4:7], v[146:161]
	ds_read_b128 v[4:7], v57 offset:33312
	ds_write_b128 v58, v[40:43] offset:10240
	ds_write_b128 v58, v[44:47] offset:15360
	v_mfma_f32_32x32x16_bf16 v[98:113], v[16:19], v[8:11], v[98:113]
	v_mfma_f32_32x32x16_bf16 v[162:177], v[20:23], v[8:11], v[162:177]
	ds_read_b128 v[8:11], v57 offset:35872
	ds_write_b128 v58, v[48:51] offset:20480
	ds_write_b128 v58, v[52:55] offset:25600
	v_mfma_f32_32x32x16_bf16 v[114:129], v[16:19], v[12:15], v[114:129]
	v_mfma_f32_32x32x16_bf16 v[178:193], v[20:23], v[12:15], v[178:193]
	ds_read_b128 v[12:15], v57 offset:38432
	s_waitcnt lgkmcnt(9)
	v_mfma_f32_32x32x16_bf16 v[66:81], v[24:27], v[0:3], v[66:81]
	global_load_dwordx4 v[32:35], v[240:241], off offset:3200
	global_load_dwordx4 v[36:39], v[242:243], off offset:3200
	v_mfma_f32_32x32x16_bf16 v[130:145], v[28:31], v[0:3], v[130:145]
	s_waitcnt lgkmcnt(6)
	v_mfma_f32_32x32x16_bf16 v[82:97], v[24:27], v[4:7], v[82:97]
	global_load_dwordx4 v[40:43], v[244:245], off offset:1152
	global_load_dwordx4 v[44:47], v[246:247], off offset:1152
	v_mfma_f32_32x32x16_bf16 v[146:161], v[28:31], v[4:7], v[146:161]
	s_waitcnt lgkmcnt(3)
	v_mfma_f32_32x32x16_bf16 v[98:113], v[24:27], v[8:11], v[98:113]
	global_load_dwordx4 v[48:51], v[248:249], off offset:1152
	global_load_dwordx4 v[52:55], v[250:251], off offset:1152
	v_mfma_f32_32x32x16_bf16 v[162:177], v[28:31], v[8:11], v[162:177]
	s_waitcnt lgkmcnt(0)
	v_mfma_f32_32x32x16_bf16 v[114:129], v[24:27], v[12:15], v[114:129]
	v_mfma_f32_32x32x16_bf16 v[178:193], v[28:31], v[12:15], v[178:193]
	s_waitcnt lgkmcnt(0)
	s_barrier
; #define G_LOAD(S, kt_) do { G_LD1(S##a0, S##b0, 0, kt_); G_LD1(S##a1, S##b1, 1, kt_); G_LD1(S##a2, S##b2, 2, kt_); G_LD1(S##a3, S##b3, 3, kt_); } while (0)
; #define G_STORE(S, buf_) do { G_ST1(S##a0, S##b0, 0, buf_); G_ST1(S##a1, S##b1, 1, buf_); G_ST1(S##a2, S##b2, 2, buf_); G_ST1(S##a3, S##b3, 3, buf_); } while (0)
; template <class AL, class BL>
; DI void gemm_core(AL al, BL bl, int m0, int n0, int K, char* smem, f32x16 (&acc)[2][2]) {
;     ...
;   G_LOAD(x, 0);
;   G_STORE(x, 0);
;   G_LOAD(x, 1);
;   G_LOAD(y, (nk > 2) ? 2 : 1);
;   __syncthreads();
;   for (int kt = 0; kt < nk; kt += 2) {
;     G_TILE(0, x, true, (kt + 3 < nk), kt + 3);
;     __syncthreads();
;     G_TILE(1, y, (kt + 2 < nk), (kt + 4 < nk), kt + 4);
;     __syncthreads();
	ds_read_b128 v[0:3], v57 offset:0
	ds_read_b128 v[4:7], v57 offset:2560
	ds_read_b128 v[8:11], v57 offset:5120
	ds_read_b128 v[12:15], v57 offset:7680
	ds_read_b128 v[16:19], v56 offset:0
	ds_read_b128 v[20:23], v56 offset:2560
	ds_read_b128 v[24:27], v56 offset:32
	ds_read_b128 v[28:31], v56 offset:2592
	s_waitcnt lgkmcnt(2)
	v_mfma_f32_32x32x16_bf16 v[66:81], v[16:19], v[0:3], v[66:81]
	v_mfma_f32_32x32x16_bf16 v[130:145], v[20:23], v[0:3], v[130:145]
	ds_read_b128 v[0:3], v57 offset:32
	s_waitcnt vmcnt(6)
	ds_write_b128 v58, v[214:217] offset:30720
	ds_write_b128 v58, v[218:221] offset:35840
	v_mfma_f32_32x32x16_bf16 v[82:97], v[16:19], v[4:7], v[82:97]
	v_mfma_f32_32x32x16_bf16 v[146:161], v[20:23], v[4:7], v[146:161]
	ds_read_b128 v[4:7], v57 offset:2592
	ds_write_b128 v58, v[222:225] offset:40960
	ds_write_b128 v58, v[228:231] offset:46080
	v_mfma_f32_32x32x16_bf16 v[98:113], v[16:19], v[8:11], v[98:113]
	v_mfma_f32_32x32x16_bf16 v[162:177], v[20:23], v[8:11], v[162:177]
	ds_read_b128 v[8:11], v57 offset:5152
	ds_write_b128 v58, v[232:235] offset:51200
	ds_write_b128 v58, v[236:239] offset:56320
	v_mfma_f32_32x32x16_bf16 v[114:129], v[16:19], v[12:15], v[114:129]
	v_mfma_f32_32x32x16_bf16 v[178:193], v[20:23], v[12:15], v[178:193]
	ds_read_b128 v[12:15], v57 offset:7712
	s_waitcnt lgkmcnt(9)
	v_mfma_f32_32x32x16_bf16 v[66:81], v[24:27], v[0:3], v[66:81]
	global_load_dwordx4 v[214:217], v[240:241], off offset:3264
	global_load_dwordx4 v[218:221], v[242:243], off offset:3264
	v_mfma_f32_32x32x16_bf16 v[130:145], v[28:31], v[0:3], v[130:145]
	s_waitcnt lgkmcnt(6)
	v_mfma_f32_32x32x16_bf16 v[82:97], v[24:27], v[4:7], v[82:97]
	global_load_dwordx4 v[222:225], v[244:245], off offset:1216
	global_load_dwordx4 v[228:231], v[246:247], off offset:1216
	v_mfma_f32_32x32x16_bf16 v[146:161], v[28:31], v[4:7], v[146:161]
	s_waitcnt lgkmcnt(3)
	v_mfma_f32_32x32x16_bf16 v[98:113], v[24:27], v[8:11], v[98:113]
	global_load_dwordx4 v[232:235], v[248:249], off offset:1216
	global_load_dwordx4 v[236:239], v[250:251], off offset:1216
	v_mfma_f32_32x32x16_bf16 v[162:177], v[28:31], v[8:11], v[162:177]
	s_waitcnt lgkmcnt(0)
	v_mfma_f32_32x32x16_bf16 v[114:129], v[24:27], v[12:15], v[114:129]
	v_mfma_f32_32x32x16_bf16 v[178:193], v[28:31], v[12:15], v[178:193]
	s_waitcnt lgkmcnt(0)
	s_barrier
	ds_read_b128 v[0:3], v57 offset:30720
	ds_read_b128 v[4:7], v57 offset:33280
	ds_read_b128 v[8:11], v57 offset:35840
	ds_read_b128 v[12:15], v57 offset:38400
	ds_read_b128 v[16:19], v56 offset:30720
	ds_read_b128 v[20:23], v56 offset:33280
	ds_read_b128 v[24:27], v56 offset:30752
	ds_read_b128 v[28:31], v56 offset:33312
	s_waitcnt lgkmcnt(2)
	v_mfma_f32_32x32x16_bf16 v[66:81], v[16:19], v[0:3], v[66:81]
	v_mfma_f32_32x32x16_bf16 v[130:145], v[20:23], v[0:3], v[130:145]
	ds_read_b128 v[0:3], v57 offset:30752
	s_waitcnt vmcnt(6)
	ds_write_b128 v58, v[32:35] offset:0
	ds_write_b128 v58, v[36:39] offset:5120
	v_mfma_f32_32x32x16_bf16 v[82:97], v[16:19], v[4:7], v[82:97]
	v_mfma_f32_32x32x16_bf16 v[146:161], v[20:23], v[4:7], v[146:161]
	ds_read_b128 v[4:7], v57 offset:33312
	ds_write_b128 v58, v[40:43] offset:10240
	ds_write_b128 v58, v[44:47] offset:15360
	v_mfma_f32_32x32x16_bf16 v[98:113], v[16:19], v[8:11], v[98:113]
	v_mfma_f32_32x32x16_bf16 v[162:177], v[20:23], v[8:11], v[162:177]
	ds_read_b128 v[8:11], v57 offset:35872
	ds_write_b128 v58, v[48:51] offset:20480
	ds_write_b128 v58, v[52:55] offset:25600
	v_mfma_f32_32x32x16_bf16 v[114:129], v[16:19], v[12:15], v[114:129]
	v_mfma_f32_32x32x16_bf16 v[178:193], v[20:23], v[12:15], v[178:193]
	ds_read_b128 v[12:15], v57 offset:38432
	s_waitcnt lgkmcnt(9)
	v_mfma_f32_32x32x16_bf16 v[66:81], v[24:27], v[0:3], v[66:81]
	global_load_dwordx4 v[32:35], v[240:241], off offset:3328
	global_load_dwordx4 v[36:39], v[242:243], off offset:3328
	v_mfma_f32_32x32x16_bf16 v[130:145], v[28:31], v[0:3], v[130:145]
	s_waitcnt lgkmcnt(6)
	v_mfma_f32_32x32x16_bf16 v[82:97], v[24:27], v[4:7], v[82:97]
	global_load_dwordx4 v[40:43], v[244:245], off offset:1280
	global_load_dwordx4 v[44:47], v[246:247], off offset:1280
	v_mfma_f32_32x32x16_bf16 v[146:161], v[28:31], v[4:7], v[146:161]
	s_waitcnt lgkmcnt(3)
	v_mfma_f32_32x32x16_bf16 v[98:113], v[24:27], v[8:11], v[98:113]
	global_load_dwordx4 v[48:51], v[248:249], off offset:1280
	global_load_dwordx4 v[52:55], v[250:251], off offset:1280
	v_mfma_f32_32x32x16_bf16 v[162:177], v[28:31], v[8:11], v[162:177]
	s_waitcnt lgkmcnt(0)
	v_mfma_f32_32x32x16_bf16 v[114:129], v[24:27], v[12:15], v[114:129]
	v_mfma_f32_32x32x16_bf16 v[178:193], v[28:31], v[12:15], v[178:193]
	s_waitcnt lgkmcnt(0)
	s_barrier
; #define G_LOAD(S, kt_) do { G_LD1(S##a0, S##b0, 0, kt_); G_LD1(S##a1, S##b1, 1, kt_); G_LD1(S##a2, S##b2, 2, kt_); G_LD1(S##a3, S##b3, 3, kt_); } while (0)
; #define G_STORE(S, buf_) do { G_ST1(S##a0, S##b0, 0, buf_); G_ST1(S##a1, S##b1, 1, buf_); G_ST1(S##a2, S##b2, 2, buf_); G_ST1(S##a3, S##b3, 3, buf_); } while (0)
; template <class AL, class BL>
; DI void gemm_core(AL al, BL bl, int m0, int n0, int K, char* smem, f32x16 (&acc)[2][2]) {
;     ...
;   G_LOAD(x, 0);
;   G_STORE(x, 0);
;   G_LOAD(x, 1);
;   G_LOAD(y, (nk > 2) ? 2 : 1);
;   __syncthreads();
;   for (int kt = 0; kt < nk; kt += 2) {
;     G_TILE(0, x, true, (kt + 3 < nk), kt + 3);
;     __syncthreads();
;     G_TILE(1, y, (kt + 2 < nk), (kt + 4 < nk), kt + 4);
;     __syncthreads();
	ds_read_b128 v[0:3], v57 offset:0
	ds_read_b128 v[4:7], v57 offset:2560
	ds_read_b128 v[8:11], v57 offset:5120
	ds_read_b128 v[12:15], v57 offset:7680
	ds_read_b128 v[16:19], v56 offset:0
	ds_read_b128 v[20:23], v56 offset:2560
	ds_read_b128 v[24:27], v56 offset:32
	ds_read_b128 v[28:31], v56 offset:2592
	s_waitcnt lgkmcnt(2)
	v_mfma_f32_32x32x16_bf16 v[66:81], v[16:19], v[0:3], v[66:81]
	v_mfma_f32_32x32x16_bf16 v[130:145], v[20:23], v[0:3], v[130:145]
	ds_read_b128 v[0:3], v57 offset:32
	s_waitcnt vmcnt(6)
	ds_write_b128 v58, v[214:217] offset:30720
	ds_write_b128 v58, v[218:221] offset:35840
	v_mfma_f32_32x32x16_bf16 v[82:97], v[16:19], v[4:7], v[82:97]
	v_mfma_f32_32x32x16_bf16 v[146:161], v[20:23], v[4:7], v[146:161]
	ds_read_b128 v[4:7], v57 offset:2592
	ds_write_b128 v58, v[222:225] offset:40960
	ds_write_b128 v58, v[228:231] offset:46080
	v_mfma_f32_32x32x16_bf16 v[98:113], v[16:19], v[8:11], v[98:113]
	v_mfma_f32_32x32x16_bf16 v[162:177], v[20:23], v[8:11], v[162:177]
	ds_read_b128 v[8:11], v57 offset:5152
	ds_write_b128 v58, v[232:235] offset:51200
	ds_write_b128 v58, v[236:239] offset:56320
	v_mfma_f32_32x32x16_bf16 v[114:129], v[16:19], v[12:15], v[114:129]
	v_mfma_f32_32x32x16_bf16 v[178:193], v[20:23], v[12:15], v[178:193]
	ds_read_b128 v[12:15], v57 offset:7712
	s_waitcnt lgkmcnt(9)
	v_mfma_f32_32x32x16_bf16 v[66:81], v[24:27], v[0:3], v[66:81]
	global_load_dwordx4 v[214:217], v[240:241], off offset:3392
	global_load_dwordx4 v[218:221], v[242:243], off offset:3392
	v_mfma_f32_32x32x16_bf16 v[130:145], v[28:31], v[0:3], v[130:145]
	s_waitcnt lgkmcnt(6)
	v_mfma_f32_32x32x16_bf16 v[82:97], v[24:27], v[4:7], v[82:97]
	global_load_dwordx4 v[222:225], v[244:245], off offset:1344
	global_load_dwordx4 v[228:231], v[246:247], off offset:1344
	v_mfma_f32_32x32x16_bf16 v[146:161], v[28:31], v[4:7], v[146:161]
	s_waitcnt lgkmcnt(3)
	v_mfma_f32_32x32x16_bf16 v[98:113], v[24:27], v[8:11], v[98:113]
	global_load_dwordx4 v[232:235], v[248:249], off offset:1344
	global_load_dwordx4 v[236:239], v[250:251], off offset:1344
	v_mfma_f32_32x32x16_bf16 v[162:177], v[28:31], v[8:11], v[162:177]
	s_waitcnt lgkmcnt(0)
	v_mfma_f32_32x32x16_bf16 v[114:129], v[24:27], v[12:15], v[114:129]
	v_mfma_f32_32x32x16_bf16 v[178:193], v[28:31], v[12:15], v[178:193]
	s_waitcnt lgkmcnt(0)
	s_barrier
	ds_read_b128 v[0:3], v57 offset:30720
	ds_read_b128 v[4:7], v57 offset:33280
	ds_read_b128 v[8:11], v57 offset:35840
	ds_read_b128 v[12:15], v57 offset:38400
	ds_read_b128 v[16:19], v56 offset:30720
	ds_read_b128 v[20:23], v56 offset:33280
	ds_read_b128 v[24:27], v56 offset:30752
	ds_read_b128 v[28:31], v56 offset:33312
	s_waitcnt lgkmcnt(2)
	v_mfma_f32_32x32x16_bf16 v[66:81], v[16:19], v[0:3], v[66:81]
	v_mfma_f32_32x32x16_bf16 v[130:145], v[20:23], v[0:3], v[130:145]
	ds_read_b128 v[0:3], v57 offset:30752
	s_waitcnt vmcnt(6)
	ds_write_b128 v58, v[32:35] offset:0
	ds_write_b128 v58, v[36:39] offset:5120
	v_mfma_f32_32x32x16_bf16 v[82:97], v[16:19], v[4:7], v[82:97]
	v_mfma_f32_32x32x16_bf16 v[146:161], v[20:23], v[4:7], v[146:161]
	ds_read_b128 v[4:7], v57 offset:33312
	ds_write_b128 v58, v[40:43] offset:10240
	ds_write_b128 v58, v[44:47] offset:15360
	v_mfma_f32_32x32x16_bf16 v[98:113], v[16:19], v[8:11], v[98:113]
	v_mfma_f32_32x32x16_bf16 v[162:177], v[20:23], v[8:11], v[162:177]
	ds_read_b128 v[8:11], v57 offset:35872
	ds_write_b128 v58, v[48:51] offset:20480
	ds_write_b128 v58, v[52:55] offset:25600
	v_mfma_f32_32x32x16_bf16 v[114:129], v[16:19], v[12:15], v[114:129]
	v_mfma_f32_32x32x16_bf16 v[178:193], v[20:23], v[12:15], v[178:193]
	ds_read_b128 v[12:15], v57 offset:38432
	s_waitcnt lgkmcnt(9)
	v_mfma_f32_32x32x16_bf16 v[66:81], v[24:27], v[0:3], v[66:81]
	global_load_dwordx4 v[32:35], v[240:241], off offset:3456
	global_load_dwordx4 v[36:39], v[242:243], off offset:3456
	v_mfma_f32_32x32x16_bf16 v[130:145], v[28:31], v[0:3], v[130:145]
	s_waitcnt lgkmcnt(6)
	v_mfma_f32_32x32x16_bf16 v[82:97], v[24:27], v[4:7], v[82:97]
	global_load_dwordx4 v[40:43], v[244:245], off offset:1408
	global_load_dwordx4 v[44:47], v[246:247], off offset:1408
	v_mfma_f32_32x32x16_bf16 v[146:161], v[28:31], v[4:7], v[146:161]
	s_waitcnt lgkmcnt(3)
	v_mfma_f32_32x32x16_bf16 v[98:113], v[24:27], v[8:11], v[98:113]
	global_load_dwordx4 v[48:51], v[248:249], off offset:1408
	global_load_dwordx4 v[52:55], v[250:251], off offset:1408
	v_mfma_f32_32x32x16_bf16 v[162:177], v[28:31], v[8:11], v[162:177]
	s_waitcnt lgkmcnt(0)
	v_mfma_f32_32x32x16_bf16 v[114:129], v[24:27], v[12:15], v[114:129]
	v_mfma_f32_32x32x16_bf16 v[178:193], v[28:31], v[12:15], v[178:193]
	s_waitcnt lgkmcnt(0)
	s_barrier
; #define G_LOAD(S, kt_) do { G_LD1(S##a0, S##b0, 0, kt_); G_LD1(S##a1, S##b1, 1, kt_); G_LD1(S##a2, S##b2, 2, kt_); G_LD1(S##a3, S##b3, 3, kt_); } while (0)
; #define G_STORE(S, buf_) do { G_ST1(S##a0, S##b0, 0, buf_); G_ST1(S##a1, S##b1, 1, buf_); G_ST1(S##a2, S##b2, 2, buf_); G_ST1(S##a3, S##b3, 3, buf_); } while (0)
; template <class AL, class BL>
; DI void gemm_core(AL al, BL bl, int m0, int n0, int K, char* smem, f32x16 (&acc)[2][2]) {
;     ...
;   G_LOAD(x, 0);
;   G_STORE(x, 0);
;   G_LOAD(x, 1);
;   G_LOAD(y, (nk > 2) ? 2 : 1);
;   __syncthreads();
;   for (int kt = 0; kt < nk; kt += 2) {
;     G_TILE(0, x, true, (kt + 3 < nk), kt + 3);
;     __syncthreads();
;     G_TILE(1, y, (kt + 2 < nk), (kt + 4 < nk), kt + 4);
;     __syncthreads();
	ds_read_b128 v[0:3], v57 offset:0
	ds_read_b128 v[4:7], v57 offset:2560
	ds_read_b128 v[8:11], v57 offset:5120
	ds_read_b128 v[12:15], v57 offset:7680
	ds_read_b128 v[16:19], v56 offset:0
	ds_read_b128 v[20:23], v56 offset:2560
	ds_read_b128 v[24:27], v56 offset:32
	ds_read_b128 v[28:31], v56 offset:2592
	s_waitcnt lgkmcnt(2)
	v_mfma_f32_32x32x16_bf16 v[66:81], v[16:19], v[0:3], v[66:81]
	v_mfma_f32_32x32x16_bf16 v[130:145], v[20:23], v[0:3], v[130:145]
	ds_read_b128 v[0:3], v57 offset:32
	s_waitcnt vmcnt(6)
	ds_write_b128 v58, v[214:217] offset:30720
	ds_write_b128 v58, v[218:221] offset:35840
	v_mfma_f32_32x32x16_bf16 v[82:97], v[16:19], v[4:7], v[82:97]
	v_mfma_f32_32x32x16_bf16 v[146:161], v[20:23], v[4:7], v[146:161]
	ds_read_b128 v[4:7], v57 offset:2592
	ds_write_b128 v58, v[222:225] offset:40960
	ds_write_b128 v58, v[228:231] offset:46080
	v_mfma_f32_32x32x16_bf16 v[98:113], v[16:19], v[8:11], v[98:113]
	v_mfma_f32_32x32x16_bf16 v[162:177], v[20:23], v[8:11], v[162:177]
	ds_read_b128 v[8:11], v57 offset:5152
	ds_write_b128 v58, v[232:235] offset:51200
	ds_write_b128 v58, v[236:239] offset:56320
	v_mfma_f32_32x32x16_bf16 v[114:129], v[16:19], v[12:15], v[114:129]
	v_mfma_f32_32x32x16_bf16 v[178:193], v[20:23], v[12:15], v[178:193]
	ds_read_b128 v[12:15], v57 offset:7712
	s_waitcnt lgkmcnt(9)
	v_mfma_f32_32x32x16_bf16 v[66:81], v[24:27], v[0:3], v[66:81]
	global_load_dwordx4 v[214:217], v[240:241], off offset:3520
	global_load_dwordx4 v[218:221], v[242:243], off offset:3520
	v_mfma_f32_32x32x16_bf16 v[130:145], v[28:31], v[0:3], v[130:145]
	s_waitcnt lgkmcnt(6)
	v_mfma_f32_32x32x16_bf16 v[82:97], v[24:27], v[4:7], v[82:97]
	global_load_dwordx4 v[222:225], v[244:245], off offset:1472
	global_load_dwordx4 v[228:231], v[246:247], off offset:1472
	v_mfma_f32_32x32x16_bf16 v[146:161], v[28:31], v[4:7], v[146:161]
	s_waitcnt lgkmcnt(3)
	v_mfma_f32_32x32x16_bf16 v[98:113], v[24:27], v[8:11], v[98:113]
	global_load_dwordx4 v[232:235], v[248:249], off offset:1472
	global_load_dwordx4 v[236:239], v[250:251], off offset:1472
	v_mfma_f32_32x32x16_bf16 v[162:177], v[28:31], v[8:11], v[162:177]
	s_waitcnt lgkmcnt(0)
	v_mfma_f32_32x32x16_bf16 v[114:129], v[24:27], v[12:15], v[114:129]
	v_mfma_f32_32x32x16_bf16 v[178:193], v[28:31], v[12:15], v[178:193]
	s_waitcnt lgkmcnt(0)
	s_barrier
	ds_read_b128 v[0:3], v57 offset:30720
	ds_read_b128 v[4:7], v57 offset:33280
	ds_read_b128 v[8:11], v57 offset:35840
	ds_read_b128 v[12:15], v57 offset:38400
	ds_read_b128 v[16:19], v56 offset:30720
	ds_read_b128 v[20:23], v56 offset:33280
	ds_read_b128 v[24:27], v56 offset:30752
	ds_read_b128 v[28:31], v56 offset:33312
	s_waitcnt lgkmcnt(2)
	v_mfma_f32_32x32x16_bf16 v[66:81], v[16:19], v[0:3], v[66:81]
	v_mfma_f32_32x32x16_bf16 v[130:145], v[20:23], v[0:3], v[130:145]
	ds_read_b128 v[0:3], v57 offset:30752
	s_waitcnt vmcnt(6)
	ds_write_b128 v58, v[32:35] offset:0
	ds_write_b128 v58, v[36:39] offset:5120
	v_mfma_f32_32x32x16_bf16 v[82:97], v[16:19], v[4:7], v[82:97]
	v_mfma_f32_32x32x16_bf16 v[146:161], v[20:23], v[4:7], v[146:161]
	ds_read_b128 v[4:7], v57 offset:33312
	ds_write_b128 v58, v[40:43] offset:10240
	ds_write_b128 v58, v[44:47] offset:15360
	v_mfma_f32_32x32x16_bf16 v[98:113], v[16:19], v[8:11], v[98:113]
	v_mfma_f32_32x32x16_bf16 v[162:177], v[20:23], v[8:11], v[162:177]
	ds_read_b128 v[8:11], v57 offset:35872
	ds_write_b128 v58, v[48:51] offset:20480
	ds_write_b128 v58, v[52:55] offset:25600
	v_mfma_f32_32x32x16_bf16 v[114:129], v[16:19], v[12:15], v[114:129]
	v_mfma_f32_32x32x16_bf16 v[178:193], v[20:23], v[12:15], v[178:193]
	ds_read_b128 v[12:15], v57 offset:38432
	s_waitcnt lgkmcnt(9)
	v_mfma_f32_32x32x16_bf16 v[66:81], v[24:27], v[0:3], v[66:81]
	global_load_dwordx4 v[32:35], v[240:241], off offset:3584
	global_load_dwordx4 v[36:39], v[242:243], off offset:3584
	v_mfma_f32_32x32x16_bf16 v[130:145], v[28:31], v[0:3], v[130:145]
	s_waitcnt lgkmcnt(6)
	v_mfma_f32_32x32x16_bf16 v[82:97], v[24:27], v[4:7], v[82:97]
	global_load_dwordx4 v[40:43], v[244:245], off offset:1536
	global_load_dwordx4 v[44:47], v[246:247], off offset:1536
	v_mfma_f32_32x32x16_bf16 v[146:161], v[28:31], v[4:7], v[146:161]
	s_waitcnt lgkmcnt(3)
	v_mfma_f32_32x32x16_bf16 v[98:113], v[24:27], v[8:11], v[98:113]
	global_load_dwordx4 v[48:51], v[248:249], off offset:1536
	global_load_dwordx4 v[52:55], v[250:251], off offset:1536
	v_mfma_f32_32x32x16_bf16 v[162:177], v[28:31], v[8:11], v[162:177]
	s_waitcnt lgkmcnt(0)
	v_mfma_f32_32x32x16_bf16 v[114:129], v[24:27], v[12:15], v[114:129]
	v_mfma_f32_32x32x16_bf16 v[178:193], v[28:31], v[12:15], v[178:193]
	s_waitcnt lgkmcnt(0)
	s_barrier
; #define G_LOAD(S, kt_) do { G_LD1(S##a0, S##b0, 0, kt_); G_LD1(S##a1, S##b1, 1, kt_); G_LD1(S##a2, S##b2, 2, kt_); G_LD1(S##a3, S##b3, 3, kt_); } while (0)
; #define G_STORE(S, buf_) do { G_ST1(S##a0, S##b0, 0, buf_); G_ST1(S##a1, S##b1, 1, buf_); G_ST1(S##a2, S##b2, 2, buf_); G_ST1(S##a3, S##b3, 3, buf_); } while (0)
; template <class AL, class BL>
; DI void gemm_core(AL al, BL bl, int m0, int n0, int K, char* smem, f32x16 (&acc)[2][2]) {
;     ...
;   G_LOAD(x, 0);
;   G_STORE(x, 0);
;   G_LOAD(x, 1);
;   G_LOAD(y, (nk > 2) ? 2 : 1);
;   __syncthreads();
;   for (int kt = 0; kt < nk; kt += 2) {
;     G_TILE(0, x, true, (kt + 3 < nk), kt + 3);
;     __syncthreads();
;     G_TILE(1, y, (kt + 2 < nk), (kt + 4 < nk), kt + 4);
;     __syncthreads();
	ds_read_b128 v[0:3], v57 offset:0
	ds_read_b128 v[4:7], v57 offset:2560
	ds_read_b128 v[8:11], v57 offset:5120
	ds_read_b128 v[12:15], v57 offset:7680
	ds_read_b128 v[16:19], v56 offset:0
	ds_read_b128 v[20:23], v56 offset:2560
	ds_read_b128 v[24:27], v56 offset:32
	ds_read_b128 v[28:31], v56 offset:2592
	s_waitcnt lgkmcnt(2)
	v_mfma_f32_32x32x16_bf16 v[66:81], v[16:19], v[0:3], v[66:81]
	v_mfma_f32_32x32x16_bf16 v[130:145], v[20:23], v[0:3], v[130:145]
	ds_read_b128 v[0:3], v57 offset:32
	s_waitcnt vmcnt(6)
	ds_write_b128 v58, v[214:217] offset:30720
	ds_write_b128 v58, v[218:221] offset:35840
	v_mfma_f32_32x32x16_bf16 v[82:97], v[16:19], v[4:7], v[82:97]
	v_mfma_f32_32x32x16_bf16 v[146:161], v[20:23], v[4:7], v[146:161]
	ds_read_b128 v[4:7], v57 offset:2592
	ds_write_b128 v58, v[222:225] offset:40960
	ds_write_b128 v58, v[228:231] offset:46080
	v_mfma_f32_32x32x16_bf16 v[98:113], v[16:19], v[8:11], v[98:113]
	v_mfma_f32_32x32x16_bf16 v[162:177], v[20:23], v[8:11], v[162:177]
	ds_read_b128 v[8:11], v57 offset:5152
	ds_write_b128 v58, v[232:235] offset:51200
	ds_write_b128 v58, v[236:239] offset:56320
	v_mfma_f32_32x32x16_bf16 v[114:129], v[16:19], v[12:15], v[114:129]
	v_mfma_f32_32x32x16_bf16 v[178:193], v[20:23], v[12:15], v[178:193]
	ds_read_b128 v[12:15], v57 offset:7712
	s_waitcnt lgkmcnt(9)
	v_mfma_f32_32x32x16_bf16 v[66:81], v[24:27], v[0:3], v[66:81]
	global_load_dwordx4 v[214:217], v[240:241], off offset:3648
	global_load_dwordx4 v[218:221], v[242:243], off offset:3648
	v_mfma_f32_32x32x16_bf16 v[130:145], v[28:31], v[0:3], v[130:145]
	s_waitcnt lgkmcnt(6)
	v_mfma_f32_32x32x16_bf16 v[82:97], v[24:27], v[4:7], v[82:97]
	global_load_dwordx4 v[222:225], v[244:245], off offset:1600
	global_load_dwordx4 v[228:231], v[246:247], off offset:1600
	v_mfma_f32_32x32x16_bf16 v[146:161], v[28:31], v[4:7], v[146:161]
	s_waitcnt lgkmcnt(3)
	v_mfma_f32_32x32x16_bf16 v[98:113], v[24:27], v[8:11], v[98:113]
	global_load_dwordx4 v[232:235], v[248:249], off offset:1600
	global_load_dwordx4 v[236:239], v[250:251], off offset:1600
	v_mfma_f32_32x32x16_bf16 v[162:177], v[28:31], v[8:11], v[162:177]
	s_waitcnt lgkmcnt(0)
	v_mfma_f32_32x32x16_bf16 v[114:129], v[24:27], v[12:15], v[114:129]
	v_mfma_f32_32x32x16_bf16 v[178:193], v[28:31], v[12:15], v[178:193]
	s_waitcnt lgkmcnt(0)
	s_barrier
	ds_read_b128 v[0:3], v57 offset:30720
	ds_read_b128 v[4:7], v57 offset:33280
	ds_read_b128 v[8:11], v57 offset:35840
	ds_read_b128 v[12:15], v57 offset:38400
	ds_read_b128 v[16:19], v56 offset:30720
	ds_read_b128 v[20:23], v56 offset:33280
	ds_read_b128 v[24:27], v56 offset:30752
	ds_read_b128 v[28:31], v56 offset:33312
	s_waitcnt lgkmcnt(2)
	v_mfma_f32_32x32x16_bf16 v[66:81], v[16:19], v[0:3], v[66:81]
	v_mfma_f32_32x32x16_bf16 v[130:145], v[20:23], v[0:3], v[130:145]
	ds_read_b128 v[0:3], v57 offset:30752
	s_waitcnt vmcnt(6)
	ds_write_b128 v58, v[32:35] offset:0
	ds_write_b128 v58, v[36:39] offset:5120
	v_mfma_f32_32x32x16_bf16 v[82:97], v[16:19], v[4:7], v[82:97]
	v_mfma_f32_32x32x16_bf16 v[146:161], v[20:23], v[4:7], v[146:161]
	ds_read_b128 v[4:7], v57 offset:33312
	ds_write_b128 v58, v[40:43] offset:10240
	ds_write_b128 v58, v[44:47] offset:15360
	v_mfma_f32_32x32x16_bf16 v[98:113], v[16:19], v[8:11], v[98:113]
	v_mfma_f32_32x32x16_bf16 v[162:177], v[20:23], v[8:11], v[162:177]
	ds_read_b128 v[8:11], v57 offset:35872
	ds_write_b128 v58, v[48:51] offset:20480
	ds_write_b128 v58, v[52:55] offset:25600
	v_mfma_f32_32x32x16_bf16 v[114:129], v[16:19], v[12:15], v[114:129]
	v_mfma_f32_32x32x16_bf16 v[178:193], v[20:23], v[12:15], v[178:193]
	ds_read_b128 v[12:15], v57 offset:38432
	s_waitcnt lgkmcnt(9)
	v_mfma_f32_32x32x16_bf16 v[66:81], v[24:27], v[0:3], v[66:81]
	global_load_dwordx4 v[32:35], v[240:241], off offset:3712
	global_load_dwordx4 v[36:39], v[242:243], off offset:3712
	v_mfma_f32_32x32x16_bf16 v[130:145], v[28:31], v[0:3], v[130:145]
	s_waitcnt lgkmcnt(6)
	v_mfma_f32_32x32x16_bf16 v[82:97], v[24:27], v[4:7], v[82:97]
	global_load_dwordx4 v[40:43], v[244:245], off offset:1664
	global_load_dwordx4 v[44:47], v[246:247], off offset:1664
	v_mfma_f32_32x32x16_bf16 v[146:161], v[28:31], v[4:7], v[146:161]
	s_waitcnt lgkmcnt(3)
	v_mfma_f32_32x32x16_bf16 v[98:113], v[24:27], v[8:11], v[98:113]
	global_load_dwordx4 v[48:51], v[248:249], off offset:1664
	global_load_dwordx4 v[52:55], v[250:251], off offset:1664
	v_mfma_f32_32x32x16_bf16 v[162:177], v[28:31], v[8:11], v[162:177]
	s_waitcnt lgkmcnt(0)
	v_mfma_f32_32x32x16_bf16 v[114:129], v[24:27], v[12:15], v[114:129]
	v_mfma_f32_32x32x16_bf16 v[178:193], v[28:31], v[12:15], v[178:193]
	s_waitcnt lgkmcnt(0)
	s_barrier
; #define G_LOAD(S, kt_) do { G_LD1(S##a0, S##b0, 0, kt_); G_LD1(S##a1, S##b1, 1, kt_); G_LD1(S##a2, S##b2, 2, kt_); G_LD1(S##a3, S##b3, 3, kt_); } while (0)
; #define G_STORE(S, buf_) do { G_ST1(S##a0, S##b0, 0, buf_); G_ST1(S##a1, S##b1, 1, buf_); G_ST1(S##a2, S##b2, 2, buf_); G_ST1(S##a3, S##b3, 3, buf_); } while (0)
; template <class AL, class BL>
; DI void gemm_core(AL al, BL bl, int m0, int n0, int K, char* smem, f32x16 (&acc)[2][2]) {
;     ...
;   G_LOAD(x, 0);
;   G_STORE(x, 0);
;   G_LOAD(x, 1);
;   G_LOAD(y, (nk > 2) ? 2 : 1);
;   __syncthreads();
;   for (int kt = 0; kt < nk; kt += 2) {
;     G_TILE(0, x, true, (kt + 3 < nk), kt + 3);
;     __syncthreads();
;     G_TILE(1, y, (kt + 2 < nk), (kt + 4 < nk), kt + 4);
;     __syncthreads();
	ds_read_b128 v[0:3], v57 offset:0
	ds_read_b128 v[4:7], v57 offset:2560
	ds_read_b128 v[8:11], v57 offset:5120
	ds_read_b128 v[12:15], v57 offset:7680
	ds_read_b128 v[16:19], v56 offset:0
	ds_read_b128 v[20:23], v56 offset:2560
	ds_read_b128 v[24:27], v56 offset:32
	ds_read_b128 v[28:31], v56 offset:2592
	s_waitcnt lgkmcnt(2)
	v_mfma_f32_32x32x16_bf16 v[66:81], v[16:19], v[0:3], v[66:81]
	v_mfma_f32_32x32x16_bf16 v[130:145], v[20:23], v[0:3], v[130:145]
	ds_read_b128 v[0:3], v57 offset:32
	s_waitcnt vmcnt(6)
	ds_write_b128 v58, v[214:217] offset:30720
	ds_write_b128 v58, v[218:221] offset:35840
	v_mfma_f32_32x32x16_bf16 v[82:97], v[16:19], v[4:7], v[82:97]
	v_mfma_f32_32x32x16_bf16 v[146:161], v[20:23], v[4:7], v[146:161]
	ds_read_b128 v[4:7], v57 offset:2592
	ds_write_b128 v58, v[222:225] offset:40960
	ds_write_b128 v58, v[228:231] offset:46080
	v_mfma_f32_32x32x16_bf16 v[98:113], v[16:19], v[8:11], v[98:113]
	v_mfma_f32_32x32x16_bf16 v[162:177], v[20:23], v[8:11], v[162:177]
	ds_read_b128 v[8:11], v57 offset:5152
	ds_write_b128 v58, v[232:235] offset:51200
	ds_write_b128 v58, v[236:239] offset:56320
	v_mfma_f32_32x32x16_bf16 v[114:129], v[16:19], v[12:15], v[114:129]
	v_mfma_f32_32x32x16_bf16 v[178:193], v[20:23], v[12:15], v[178:193]
	ds_read_b128 v[12:15], v57 offset:7712
	s_waitcnt lgkmcnt(9)
	v_mfma_f32_32x32x16_bf16 v[66:81], v[24:27], v[0:3], v[66:81]
	global_load_dwordx4 v[214:217], v[240:241], off offset:3776
	global_load_dwordx4 v[218:221], v[242:243], off offset:3776
	v_mfma_f32_32x32x16_bf16 v[130:145], v[28:31], v[0:3], v[130:145]
	s_waitcnt lgkmcnt(6)
	v_mfma_f32_32x32x16_bf16 v[82:97], v[24:27], v[4:7], v[82:97]
	global_load_dwordx4 v[222:225], v[244:245], off offset:1728
	global_load_dwordx4 v[228:231], v[246:247], off offset:1728
	v_mfma_f32_32x32x16_bf16 v[146:161], v[28:31], v[4:7], v[146:161]
	s_waitcnt lgkmcnt(3)
	v_mfma_f32_32x32x16_bf16 v[98:113], v[24:27], v[8:11], v[98:113]
	global_load_dwordx4 v[232:235], v[248:249], off offset:1728
	global_load_dwordx4 v[236:239], v[250:251], off offset:1728
	v_mfma_f32_32x32x16_bf16 v[162:177], v[28:31], v[8:11], v[162:177]
	s_waitcnt lgkmcnt(0)
	v_mfma_f32_32x32x16_bf16 v[114:129], v[24:27], v[12:15], v[114:129]
	v_mfma_f32_32x32x16_bf16 v[178:193], v[28:31], v[12:15], v[178:193]
	s_waitcnt lgkmcnt(0)
	s_barrier
	ds_read_b128 v[0:3], v57 offset:30720
	ds_read_b128 v[4:7], v57 offset:33280
	ds_read_b128 v[8:11], v57 offset:35840
	ds_read_b128 v[12:15], v57 offset:38400
	ds_read_b128 v[16:19], v56 offset:30720
	ds_read_b128 v[20:23], v56 offset:33280
	ds_read_b128 v[24:27], v56 offset:30752
	ds_read_b128 v[28:31], v56 offset:33312
	s_waitcnt lgkmcnt(2)
	v_mfma_f32_32x32x16_bf16 v[66:81], v[16:19], v[0:3], v[66:81]
	v_mfma_f32_32x32x16_bf16 v[130:145], v[20:23], v[0:3], v[130:145]
	ds_read_b128 v[0:3], v57 offset:30752
	s_waitcnt vmcnt(6)
	ds_write_b128 v58, v[32:35] offset:0
	ds_write_b128 v58, v[36:39] offset:5120
	v_mfma_f32_32x32x16_bf16 v[82:97], v[16:19], v[4:7], v[82:97]
	v_mfma_f32_32x32x16_bf16 v[146:161], v[20:23], v[4:7], v[146:161]
	ds_read_b128 v[4:7], v57 offset:33312
	ds_write_b128 v58, v[40:43] offset:10240
	ds_write_b128 v58, v[44:47] offset:15360
	v_mfma_f32_32x32x16_bf16 v[98:113], v[16:19], v[8:11], v[98:113]
	v_mfma_f32_32x32x16_bf16 v[162:177], v[20:23], v[8:11], v[162:177]
	ds_read_b128 v[8:11], v57 offset:35872
	ds_write_b128 v58, v[48:51] offset:20480
	ds_write_b128 v58, v[52:55] offset:25600
	v_mfma_f32_32x32x16_bf16 v[114:129], v[16:19], v[12:15], v[114:129]
	v_mfma_f32_32x32x16_bf16 v[178:193], v[20:23], v[12:15], v[178:193]
	ds_read_b128 v[12:15], v57 offset:38432
	s_waitcnt lgkmcnt(9)
	v_mfma_f32_32x32x16_bf16 v[66:81], v[24:27], v[0:3], v[66:81]
	global_load_dwordx4 v[32:35], v[240:241], off offset:3840
	global_load_dwordx4 v[36:39], v[242:243], off offset:3840
	v_mfma_f32_32x32x16_bf16 v[130:145], v[28:31], v[0:3], v[130:145]
	s_waitcnt lgkmcnt(6)
	v_mfma_f32_32x32x16_bf16 v[82:97], v[24:27], v[4:7], v[82:97]
	global_load_dwordx4 v[40:43], v[244:245], off offset:1792
	global_load_dwordx4 v[44:47], v[246:247], off offset:1792
	v_mfma_f32_32x32x16_bf16 v[146:161], v[28:31], v[4:7], v[146:161]
	s_waitcnt lgkmcnt(3)
	v_mfma_f32_32x32x16_bf16 v[98:113], v[24:27], v[8:11], v[98:113]
	global_load_dwordx4 v[48:51], v[248:249], off offset:1792
	global_load_dwordx4 v[52:55], v[250:251], off offset:1792
	v_mfma_f32_32x32x16_bf16 v[162:177], v[28:31], v[8:11], v[162:177]
	s_waitcnt lgkmcnt(0)
	v_mfma_f32_32x32x16_bf16 v[114:129], v[24:27], v[12:15], v[114:129]
	v_mfma_f32_32x32x16_bf16 v[178:193], v[28:31], v[12:15], v[178:193]
	s_waitcnt lgkmcnt(0)
	s_barrier
; #define G_LOAD(S, kt_) do { G_LD1(S##a0, S##b0, 0, kt_); G_LD1(S##a1, S##b1, 1, kt_); G_LD1(S##a2, S##b2, 2, kt_); G_LD1(S##a3, S##b3, 3, kt_); } while (0)
; #define G_STORE(S, buf_) do { G_ST1(S##a0, S##b0, 0, buf_); G_ST1(S##a1, S##b1, 1, buf_); G_ST1(S##a2, S##b2, 2, buf_); G_ST1(S##a3, S##b3, 3, buf_); } while (0)
; template <class AL, class BL>
; DI void gemm_core(AL al, BL bl, int m0, int n0, int K, char* smem, f32x16 (&acc)[2][2]) {
;     ...
;   G_LOAD(x, 0);
;   G_STORE(x, 0);
;   G_LOAD(x, 1);
;   G_LOAD(y, (nk > 2) ? 2 : 1);
;   __syncthreads();
;   for (int kt = 0; kt < nk; kt += 2) {
;     G_TILE(0, x, true, (kt + 3 < nk), kt + 3);
;     __syncthreads();
;     G_TILE(1, y, (kt + 2 < nk), (kt + 4 < nk), kt + 4);
;     __syncthreads();
	ds_read_b128 v[0:3], v57 offset:0
	ds_read_b128 v[4:7], v57 offset:2560
	ds_read_b128 v[8:11], v57 offset:5120
	ds_read_b128 v[12:15], v57 offset:7680
	ds_read_b128 v[16:19], v56 offset:0
	ds_read_b128 v[20:23], v56 offset:2560
	ds_read_b128 v[24:27], v56 offset:32
	ds_read_b128 v[28:31], v56 offset:2592
	s_waitcnt lgkmcnt(2)
	v_mfma_f32_32x32x16_bf16 v[66:81], v[16:19], v[0:3], v[66:81]
	v_mfma_f32_32x32x16_bf16 v[130:145], v[20:23], v[0:3], v[130:145]
	ds_read_b128 v[0:3], v57 offset:32
	s_waitcnt vmcnt(6)
	ds_write_b128 v58, v[214:217] offset:30720
	ds_write_b128 v58, v[218:221] offset:35840
	v_mfma_f32_32x32x16_bf16 v[82:97], v[16:19], v[4:7], v[82:97]
	v_mfma_f32_32x32x16_bf16 v[146:161], v[20:23], v[4:7], v[146:161]
	ds_read_b128 v[4:7], v57 offset:2592
	ds_write_b128 v58, v[222:225] offset:40960
	ds_write_b128 v58, v[228:231] offset:46080
	v_mfma_f32_32x32x16_bf16 v[98:113], v[16:19], v[8:11], v[98:113]
	v_mfma_f32_32x32x16_bf16 v[162:177], v[20:23], v[8:11], v[162:177]
	ds_read_b128 v[8:11], v57 offset:5152
	ds_write_b128 v58, v[232:235] offset:51200
	ds_write_b128 v58, v[236:239] offset:56320
	v_mfma_f32_32x32x16_bf16 v[114:129], v[16:19], v[12:15], v[114:129]
	v_mfma_f32_32x32x16_bf16 v[178:193], v[20:23], v[12:15], v[178:193]
	ds_read_b128 v[12:15], v57 offset:7712
	s_waitcnt lgkmcnt(9)
	v_mfma_f32_32x32x16_bf16 v[66:81], v[24:27], v[0:3], v[66:81]
	global_load_dwordx4 v[214:217], v[240:241], off offset:3904
	global_load_dwordx4 v[218:221], v[242:243], off offset:3904
	v_mfma_f32_32x32x16_bf16 v[130:145], v[28:31], v[0:3], v[130:145]
	s_waitcnt lgkmcnt(6)
	v_mfma_f32_32x32x16_bf16 v[82:97], v[24:27], v[4:7], v[82:97]
	global_load_dwordx4 v[222:225], v[244:245], off offset:1856
	global_load_dwordx4 v[228:231], v[246:247], off offset:1856
	v_mfma_f32_32x32x16_bf16 v[146:161], v[28:31], v[4:7], v[146:161]
	s_waitcnt lgkmcnt(3)
	v_mfma_f32_32x32x16_bf16 v[98:113], v[24:27], v[8:11], v[98:113]
	global_load_dwordx4 v[232:235], v[248:249], off offset:1856
	global_load_dwordx4 v[236:239], v[250:251], off offset:1856
	v_mfma_f32_32x32x16_bf16 v[162:177], v[28:31], v[8:11], v[162:177]
	s_waitcnt lgkmcnt(0)
	v_mfma_f32_32x32x16_bf16 v[114:129], v[24:27], v[12:15], v[114:129]
	v_mfma_f32_32x32x16_bf16 v[178:193], v[28:31], v[12:15], v[178:193]
	s_waitcnt lgkmcnt(0)
	s_barrier
	ds_read_b128 v[0:3], v57 offset:30720
	ds_read_b128 v[4:7], v57 offset:33280
	ds_read_b128 v[8:11], v57 offset:35840
	ds_read_b128 v[12:15], v57 offset:38400
	ds_read_b128 v[16:19], v56 offset:30720
	ds_read_b128 v[20:23], v56 offset:33280
	ds_read_b128 v[24:27], v56 offset:30752
	ds_read_b128 v[28:31], v56 offset:33312
	s_waitcnt lgkmcnt(2)
	v_mfma_f32_32x32x16_bf16 v[66:81], v[16:19], v[0:3], v[66:81]
	v_mfma_f32_32x32x16_bf16 v[130:145], v[20:23], v[0:3], v[130:145]
	ds_read_b128 v[0:3], v57 offset:30752
	s_waitcnt vmcnt(6)
	ds_write_b128 v58, v[32:35] offset:0
	ds_write_b128 v58, v[36:39] offset:5120
	v_mfma_f32_32x32x16_bf16 v[82:97], v[16:19], v[4:7], v[82:97]
	v_mfma_f32_32x32x16_bf16 v[146:161], v[20:23], v[4:7], v[146:161]
	ds_read_b128 v[4:7], v57 offset:33312
	ds_write_b128 v58, v[40:43] offset:10240
	ds_write_b128 v58, v[44:47] offset:15360
	v_mfma_f32_32x32x16_bf16 v[98:113], v[16:19], v[8:11], v[98:113]
	v_mfma_f32_32x32x16_bf16 v[162:177], v[20:23], v[8:11], v[162:177]
	ds_read_b128 v[8:11], v57 offset:35872
	ds_write_b128 v58, v[48:51] offset:20480
	ds_write_b128 v58, v[52:55] offset:25600
	v_mfma_f32_32x32x16_bf16 v[114:129], v[16:19], v[12:15], v[114:129]
	v_mfma_f32_32x32x16_bf16 v[178:193], v[20:23], v[12:15], v[178:193]
	ds_read_b128 v[12:15], v57 offset:38432
	s_waitcnt lgkmcnt(9)
	v_mfma_f32_32x32x16_bf16 v[66:81], v[24:27], v[0:3], v[66:81]
	global_load_dwordx4 v[32:35], v[240:241], off offset:3968
	global_load_dwordx4 v[36:39], v[242:243], off offset:3968
	v_mfma_f32_32x32x16_bf16 v[130:145], v[28:31], v[0:3], v[130:145]
	s_waitcnt lgkmcnt(6)
	v_mfma_f32_32x32x16_bf16 v[82:97], v[24:27], v[4:7], v[82:97]
	global_load_dwordx4 v[40:43], v[244:245], off offset:1920
	global_load_dwordx4 v[44:47], v[246:247], off offset:1920
	v_mfma_f32_32x32x16_bf16 v[146:161], v[28:31], v[4:7], v[146:161]
	s_waitcnt lgkmcnt(3)
	v_mfma_f32_32x32x16_bf16 v[98:113], v[24:27], v[8:11], v[98:113]
	global_load_dwordx4 v[48:51], v[248:249], off offset:1920
	global_load_dwordx4 v[52:55], v[250:251], off offset:1920
	v_mfma_f32_32x32x16_bf16 v[162:177], v[28:31], v[8:11], v[162:177]
	s_waitcnt lgkmcnt(0)
	v_mfma_f32_32x32x16_bf16 v[114:129], v[24:27], v[12:15], v[114:129]
	v_mfma_f32_32x32x16_bf16 v[178:193], v[28:31], v[12:15], v[178:193]
	s_waitcnt lgkmcnt(0)
	s_barrier
; #define G_LOAD(S, kt_) do { G_LD1(S##a0, S##b0, 0, kt_); G_LD1(S##a1, S##b1, 1, kt_); G_LD1(S##a2, S##b2, 2, kt_); G_LD1(S##a3, S##b3, 3, kt_); } while (0)
; #define G_STORE(S, buf_) do { G_ST1(S##a0, S##b0, 0, buf_); G_ST1(S##a1, S##b1, 1, buf_); G_ST1(S##a2, S##b2, 2, buf_); G_ST1(S##a3, S##b3, 3, buf_); } while (0)
; template <class AL, class BL>
; DI void gemm_core(AL al, BL bl, int m0, int n0, int K, char* smem, f32x16 (&acc)[2][2]) {
;     ...
;   G_LOAD(x, 0);
;   G_STORE(x, 0);
;   G_LOAD(x, 1);
;   G_LOAD(y, (nk > 2) ? 2 : 1);
;   __syncthreads();
;   for (int kt = 0; kt < nk; kt += 2) {
;     G_TILE(0, x, true, (kt + 3 < nk), kt + 3);
;     __syncthreads();
;     G_TILE(1, y, (kt + 2 < nk), (kt + 4 < nk), kt + 4);
;     __syncthreads();
	ds_read_b128 v[0:3], v57 offset:0
	ds_read_b128 v[4:7], v57 offset:2560
	ds_read_b128 v[8:11], v57 offset:5120
	ds_read_b128 v[12:15], v57 offset:7680
	ds_read_b128 v[16:19], v56 offset:0
	ds_read_b128 v[20:23], v56 offset:2560
	ds_read_b128 v[24:27], v56 offset:32
	ds_read_b128 v[28:31], v56 offset:2592
	s_waitcnt lgkmcnt(2)
	v_mfma_f32_32x32x16_bf16 v[66:81], v[16:19], v[0:3], v[66:81]
	v_mfma_f32_32x32x16_bf16 v[130:145], v[20:23], v[0:3], v[130:145]
	ds_read_b128 v[0:3], v57 offset:32
	s_waitcnt vmcnt(6)
	ds_write_b128 v58, v[214:217] offset:30720
	ds_write_b128 v58, v[218:221] offset:35840
	v_mfma_f32_32x32x16_bf16 v[82:97], v[16:19], v[4:7], v[82:97]
	v_mfma_f32_32x32x16_bf16 v[146:161], v[20:23], v[4:7], v[146:161]
	ds_read_b128 v[4:7], v57 offset:2592
	ds_write_b128 v58, v[222:225] offset:40960
	ds_write_b128 v58, v[228:231] offset:46080
	v_mfma_f32_32x32x16_bf16 v[98:113], v[16:19], v[8:11], v[98:113]
	v_mfma_f32_32x32x16_bf16 v[162:177], v[20:23], v[8:11], v[162:177]
	ds_read_b128 v[8:11], v57 offset:5152
	ds_write_b128 v58, v[232:235] offset:51200
	ds_write_b128 v58, v[236:239] offset:56320
	v_mfma_f32_32x32x16_bf16 v[114:129], v[16:19], v[12:15], v[114:129]
	v_mfma_f32_32x32x16_bf16 v[178:193], v[20:23], v[12:15], v[178:193]
	ds_read_b128 v[12:15], v57 offset:7712
	s_waitcnt lgkmcnt(9)
	v_mfma_f32_32x32x16_bf16 v[66:81], v[24:27], v[0:3], v[66:81]
	global_load_dwordx4 v[214:217], v[240:241], off offset:4032
	global_load_dwordx4 v[218:221], v[242:243], off offset:4032
	v_mfma_f32_32x32x16_bf16 v[130:145], v[28:31], v[0:3], v[130:145]
	s_waitcnt lgkmcnt(6)
	v_mfma_f32_32x32x16_bf16 v[82:97], v[24:27], v[4:7], v[82:97]
	global_load_dwordx4 v[222:225], v[244:245], off offset:1984
	global_load_dwordx4 v[228:231], v[246:247], off offset:1984
	v_mfma_f32_32x32x16_bf16 v[146:161], v[28:31], v[4:7], v[146:161]
	s_waitcnt lgkmcnt(3)
	v_mfma_f32_32x32x16_bf16 v[98:113], v[24:27], v[8:11], v[98:113]
	global_load_dwordx4 v[232:235], v[248:249], off offset:1984
	global_load_dwordx4 v[236:239], v[250:251], off offset:1984
	v_mfma_f32_32x32x16_bf16 v[162:177], v[28:31], v[8:11], v[162:177]
	s_waitcnt lgkmcnt(0)
	v_mfma_f32_32x32x16_bf16 v[114:129], v[24:27], v[12:15], v[114:129]
	v_mfma_f32_32x32x16_bf16 v[178:193], v[28:31], v[12:15], v[178:193]
	s_waitcnt lgkmcnt(0)
	s_barrier
	ds_read_b128 v[0:3], v57 offset:30720
	ds_read_b128 v[4:7], v57 offset:33280
	ds_read_b128 v[8:11], v57 offset:35840
	ds_read_b128 v[12:15], v57 offset:38400
	ds_read_b128 v[16:19], v56 offset:30720
	ds_read_b128 v[20:23], v56 offset:33280
	ds_read_b128 v[24:27], v56 offset:30752
	ds_read_b128 v[28:31], v56 offset:33312
	s_waitcnt lgkmcnt(2)
	v_mfma_f32_32x32x16_bf16 v[66:81], v[16:19], v[0:3], v[66:81]
	v_mfma_f32_32x32x16_bf16 v[130:145], v[20:23], v[0:3], v[130:145]
	ds_read_b128 v[0:3], v57 offset:30752
	s_waitcnt vmcnt(6)
	ds_write_b128 v58, v[32:35] offset:0
	ds_write_b128 v58, v[36:39] offset:5120
	v_mfma_f32_32x32x16_bf16 v[82:97], v[16:19], v[4:7], v[82:97]
	v_mfma_f32_32x32x16_bf16 v[146:161], v[20:23], v[4:7], v[146:161]
	ds_read_b128 v[4:7], v57 offset:33312
	ds_write_b128 v58, v[40:43] offset:10240
	ds_write_b128 v58, v[44:47] offset:15360
	v_mfma_f32_32x32x16_bf16 v[98:113], v[16:19], v[8:11], v[98:113]
	v_mfma_f32_32x32x16_bf16 v[162:177], v[20:23], v[8:11], v[162:177]
	ds_read_b128 v[8:11], v57 offset:35872
	ds_write_b128 v58, v[48:51] offset:20480
	ds_write_b128 v58, v[52:55] offset:25600
	v_mfma_f32_32x32x16_bf16 v[114:129], v[16:19], v[12:15], v[114:129]
	v_mfma_f32_32x32x16_bf16 v[178:193], v[20:23], v[12:15], v[178:193]
	ds_read_b128 v[12:15], v57 offset:38432
	s_waitcnt lgkmcnt(9)
	v_mfma_f32_32x32x16_bf16 v[66:81], v[24:27], v[0:3], v[66:81]
	v_mfma_f32_32x32x16_bf16 v[130:145], v[28:31], v[0:3], v[130:145]
	s_waitcnt lgkmcnt(6)
	v_mfma_f32_32x32x16_bf16 v[82:97], v[24:27], v[4:7], v[82:97]
	v_mfma_f32_32x32x16_bf16 v[146:161], v[28:31], v[4:7], v[146:161]
	s_waitcnt lgkmcnt(3)
	v_mfma_f32_32x32x16_bf16 v[98:113], v[24:27], v[8:11], v[98:113]
	v_mfma_f32_32x32x16_bf16 v[162:177], v[28:31], v[8:11], v[162:177]
	s_waitcnt lgkmcnt(0)
	v_mfma_f32_32x32x16_bf16 v[114:129], v[24:27], v[12:15], v[114:129]
	v_mfma_f32_32x32x16_bf16 v[178:193], v[28:31], v[12:15], v[178:193]
	s_waitcnt lgkmcnt(0)
	s_barrier
; #define G_LOAD(S, kt_) do { G_LD1(S##a0, S##b0, 0, kt_); G_LD1(S##a1, S##b1, 1, kt_); G_LD1(S##a2, S##b2, 2, kt_); G_LD1(S##a3, S##b3, 3, kt_); } while (0)
; #define G_STORE(S, buf_) do { G_ST1(S##a0, S##b0, 0, buf_); G_ST1(S##a1, S##b1, 1, buf_); G_ST1(S##a2, S##b2, 2, buf_); G_ST1(S##a3, S##b3, 3, buf_); } while (0)
; template <class AL, class BL>
; DI void gemm_core(AL al, BL bl, int m0, int n0, int K, char* smem, f32x16 (&acc)[2][2]) {
;     ...
;   G_LOAD(x, 0);
;   G_STORE(x, 0);
;   G_LOAD(x, 1);
;   G_LOAD(y, (nk > 2) ? 2 : 1);
;   __syncthreads();
;   for (int kt = 0; kt < nk; kt += 2) {
;     G_TILE(0, x, true, (kt + 3 < nk), kt + 3);
;     __syncthreads();
;     G_TILE(1, y, (kt + 2 < nk), (kt + 4 < nk), kt + 4);
;     __syncthreads();
; DI void ffn_up_phase(const Params& p, const u16* xb, int ldx, const u16* wupT, u16* hid, char* smem) {
;     ...
;   gemm_phase(NT / 128, 32, 1024,
;              [=](int m, int k) { return xb + (long)m * ldx + k; },
;              [=](int n, int k) { return wupT + (long)n * 1024 + k; },
;              [=](const f32x16 (&acc)[2][2], int m0, int n0) {
;                epi_bf16_tile(acc, m0, n0, hid + (long)m0 * 4096 + n0, 4096, smem, [=](int m, int n, float v) {
;                  const float a = fmaxf(v * rs[m], 0.f);
;                  return a * a;
;                });
	ds_read_b128 v[0:3], v57 offset:0
	ds_read_b128 v[4:7], v57 offset:2560
	ds_read_b128 v[8:11], v57 offset:5120
	ds_read_b128 v[12:15], v57 offset:7680
	ds_read_b128 v[16:19], v56 offset:0
	ds_read_b128 v[20:23], v56 offset:2560
	ds_read_b128 v[24:27], v56 offset:32
	ds_read_b128 v[28:31], v56 offset:2592
	s_waitcnt lgkmcnt(2)
	v_mfma_f32_32x32x16_bf16 v[66:81], v[16:19], v[0:3], v[66:81]
	v_mfma_f32_32x32x16_bf16 v[130:145], v[20:23], v[0:3], v[130:145]
	ds_read_b128 v[0:3], v57 offset:32
	s_waitcnt vmcnt(0)
	ds_write_b128 v58, v[214:217] offset:30720
	ds_write_b128 v58, v[218:221] offset:35840
	v_mfma_f32_32x32x16_bf16 v[82:97], v[16:19], v[4:7], v[82:97]
	v_mfma_f32_32x32x16_bf16 v[146:161], v[20:23], v[4:7], v[146:161]
	ds_read_b128 v[4:7], v57 offset:2592
	ds_write_b128 v58, v[222:225] offset:40960
	ds_write_b128 v58, v[228:231] offset:46080
	v_mfma_f32_32x32x16_bf16 v[98:113], v[16:19], v[8:11], v[98:113]
	v_mfma_f32_32x32x16_bf16 v[162:177], v[20:23], v[8:11], v[162:177]
	ds_read_b128 v[8:11], v57 offset:5152
	ds_write_b128 v58, v[232:235] offset:51200
	ds_write_b128 v58, v[236:239] offset:56320
	v_mfma_f32_32x32x16_bf16 v[114:129], v[16:19], v[12:15], v[114:129]
	v_mfma_f32_32x32x16_bf16 v[178:193], v[20:23], v[12:15], v[178:193]
	ds_read_b128 v[12:15], v57 offset:7712
	s_waitcnt lgkmcnt(9)
	v_mfma_f32_32x32x16_bf16 v[66:81], v[24:27], v[0:3], v[66:81]
	v_mfma_f32_32x32x16_bf16 v[130:145], v[28:31], v[0:3], v[130:145]
	s_waitcnt lgkmcnt(6)
	v_mfma_f32_32x32x16_bf16 v[82:97], v[24:27], v[4:7], v[82:97]
	v_mfma_f32_32x32x16_bf16 v[146:161], v[28:31], v[4:7], v[146:161]
	s_waitcnt lgkmcnt(3)
	v_mfma_f32_32x32x16_bf16 v[98:113], v[24:27], v[8:11], v[98:113]
	v_mfma_f32_32x32x16_bf16 v[162:177], v[28:31], v[8:11], v[162:177]
	s_waitcnt lgkmcnt(0)
	v_mfma_f32_32x32x16_bf16 v[114:129], v[24:27], v[12:15], v[114:129]
	v_mfma_f32_32x32x16_bf16 v[178:193], v[28:31], v[12:15], v[178:193]
	s_waitcnt lgkmcnt(0)
	s_barrier
	ds_read_b128 v[0:3], v57 offset:30720
	ds_read_b128 v[4:7], v57 offset:33280
	ds_read_b128 v[8:11], v57 offset:35840
	ds_read_b128 v[12:15], v57 offset:38400
	ds_read_b128 v[16:19], v56 offset:30720
	ds_read_b128 v[20:23], v56 offset:33280
	ds_read_b128 v[24:27], v56 offset:30752
	ds_read_b128 v[28:31], v56 offset:33312
	s_waitcnt lgkmcnt(2)
	v_mfma_f32_32x32x16_bf16 v[66:81], v[16:19], v[0:3], v[66:81]
	global_load_dword v32, v61, s[12:13] offset:0
	global_load_dword v33, v61, s[12:13] offset:4
	global_load_dword v34, v61, s[12:13] offset:8
	global_load_dword v35, v61, s[12:13] offset:12
	v_mfma_f32_32x32x16_bf16 v[130:145], v[20:23], v[0:3], v[130:145]
	ds_read_b128 v[0:3], v57 offset:30752
	v_mfma_f32_32x32x16_bf16 v[82:97], v[16:19], v[4:7], v[82:97]
	global_load_dword v36, v61, s[12:13] offset:32
	global_load_dword v37, v61, s[12:13] offset:36
	global_load_dword v38, v61, s[12:13] offset:40
	global_load_dword v39, v61, s[12:13] offset:44
	v_mfma_f32_32x32x16_bf16 v[146:161], v[20:23], v[4:7], v[146:161]
	ds_read_b128 v[4:7], v57 offset:33312
	v_mfma_f32_32x32x16_bf16 v[98:113], v[16:19], v[8:11], v[98:113]
	global_load_dword v40, v61, s[12:13] offset:64
	global_load_dword v41, v61, s[12:13] offset:68
	global_load_dword v42, v61, s[12:13] offset:72
	global_load_dword v43, v61, s[12:13] offset:76
	v_mfma_f32_32x32x16_bf16 v[162:177], v[20:23], v[8:11], v[162:177]
	ds_read_b128 v[8:11], v57 offset:35872
	v_mfma_f32_32x32x16_bf16 v[114:129], v[16:19], v[12:15], v[114:129]
	global_load_dword v44, v61, s[12:13] offset:96
	global_load_dword v45, v61, s[12:13] offset:100
	global_load_dword v46, v61, s[12:13] offset:104
	global_load_dword v47, v61, s[12:13] offset:108
	v_mfma_f32_32x32x16_bf16 v[178:193], v[20:23], v[12:15], v[178:193]
	ds_read_b128 v[12:15], v57 offset:38432
	s_waitcnt lgkmcnt(3)
	v_mfma_f32_32x32x16_bf16 v[66:81], v[24:27], v[0:3], v[66:81]
	global_load_dword v48, v61, s[12:13] offset:128
	global_load_dword v49, v61, s[12:13] offset:132
	global_load_dword v50, v61, s[12:13] offset:136
	global_load_dword v51, v61, s[12:13] offset:140
	v_mfma_f32_32x32x16_bf16 v[130:145], v[28:31], v[0:3], v[130:145]
	s_waitcnt lgkmcnt(2)
	v_mfma_f32_32x32x16_bf16 v[82:97], v[24:27], v[4:7], v[82:97]
	global_load_dword v52, v61, s[12:13] offset:160
	global_load_dword v53, v61, s[12:13] offset:164
	global_load_dword v54, v61, s[12:13] offset:168
	global_load_dword v55, v61, s[12:13] offset:172
	v_mfma_f32_32x32x16_bf16 v[146:161], v[28:31], v[4:7], v[146:161]
	s_waitcnt lgkmcnt(1)
	v_mfma_f32_32x32x16_bf16 v[98:113], v[24:27], v[8:11], v[98:113]
	global_load_dword v214, v61, s[12:13] offset:192
	global_load_dword v215, v61, s[12:13] offset:196
	global_load_dword v216, v61, s[12:13] offset:200
	global_load_dword v217, v61, s[12:13] offset:204
	v_mfma_f32_32x32x16_bf16 v[162:177], v[28:31], v[8:11], v[162:177]
	s_waitcnt lgkmcnt(0)
	v_mfma_f32_32x32x16_bf16 v[114:129], v[24:27], v[12:15], v[114:129]
	global_load_dword v218, v61, s[12:13] offset:224
	global_load_dword v219, v61, s[12:13] offset:228
	global_load_dword v220, v61, s[12:13] offset:232
	global_load_dword v221, v61, s[12:13] offset:236
	v_mfma_f32_32x32x16_bf16 v[178:193], v[28:31], v[12:15], v[178:193]
	s_waitcnt lgkmcnt(0)
	s_barrier
	s_nop 7
	s_nop 3
	s_waitcnt vmcnt(0)
	v_mov_b32_e32 v0, v32
	v_mov_b32_e32 v1, v33
	v_mov_b32_e32 v2, v34
	v_mov_b32_e32 v3, v35
	v_mov_b32_e32 v4, v36
	v_mov_b32_e32 v5, v37
	v_mov_b32_e32 v6, v38
	v_mov_b32_e32 v7, v39
	v_mov_b32_e32 v8, v40
	v_mov_b32_e32 v9, v41
	v_mov_b32_e32 v10, v42
	v_mov_b32_e32 v11, v43
	v_mov_b32_e32 v12, v44
	v_mov_b32_e32 v13, v45
	v_mov_b32_e32 v14, v46
	v_mov_b32_e32 v15, v47
	v_mov_b32_e32 v16, v48
	v_mov_b32_e32 v17, v49
	v_mov_b32_e32 v18, v50
	v_mov_b32_e32 v19, v51
	v_mov_b32_e32 v20, v52
	v_mov_b32_e32 v21, v53
	v_mov_b32_e32 v22, v54
	v_mov_b32_e32 v23, v55
	v_mov_b32_e32 v24, v214
	v_mov_b32_e32 v25, v215
	v_mov_b32_e32 v26, v216
	v_mov_b32_e32 v27, v217
	v_mov_b32_e32 v28, v218
	v_mov_b32_e32 v29, v219
	v_mov_b32_e32 v30, v220
	v_mov_b32_e32 v31, v221
	s_add_u32 s98, s98, s50
	s_cmpk_lt_u32 s98, 2048
	s_cbranch_scc0 .Lfu1_nonext
	s_cmpk_lt_u32 s98, 2016
	s_cbranch_scc1 .Lfu1_m1
	s_sub_u32 s31, s98, 2016
	s_mov_b32 s33, 14
	s_branch .Lfu1_g1
